# write-through (sc1) on all bf16 published streams: SwiGLU activations, bf16 copies of the residual stream, zc, q-prime/kv-prime, pool output, V image; f32 stores stay plain
# baseline (speedup 1.0000x reference)
; __device__ __forceinline__ unsigned cvtpk(float lo, float hi) { f32x2_t v = {lo, hi}; bf16x2_t b = __builtin_convertvector(v, bf16x2_t); return __builtin_bit_cast(unsigned, b); }
;     __device__ __forceinline__ void operator()(const Acc& acc, const Unit& u, int wr, int wc, int fr, int fq) const {
;         const int row0 = u.pm * BM + wr * 64 + fr, col0 = u.pn * BM + wc * 32 + 8 * fq;
; #pragma unroll
;         for (int ai = 0; ai < 2; ++ai)
; #pragma unroll
;             for (int m = 0; m < 4; ++m) { const int row = row0 + ai * HALF + m * 16; float* rp = X + (size_t)row * DM + col0; const float* ip = Xin + (size_t)row * DM + col0; bf16_t* bp = XB + (size_t)row * DM + col0; float part = 0.f;
; #pragma unroll
;                 for (int bj = 0; bj < 2; ++bj) { f32x4* p = (f32x4*)(rp + bj * HALF); const f32x4* q = (const f32x4*)(ip + bj * HALF); f32x4 a = q[0], b = q[1]; a += acc[ai][bj][m][0] * scale; b += acc[ai][bj][m][1] * scale; p[0] = a; p[1] = b;
;                     *(u32x4*)(bp + bj * HALF) = (u32x4){cvtpk(a[0], a[1]), cvtpk(a[2], a[3]), cvtpk(b[0], b[1]), cvtpk(b[2], b[3])};
;                     part += (a[0] * a[0] + a[1] * a[1]) + (a[2] * a[2] + a[3] * a[3]) + (b[0] * b[0] + b[1] * b[1]) + (b[2] * b[2] + b[3] * b[3]); }
;                 part += __shfl_xor(part, 16); part += __shfl_xor(part, 32);
;                 if (fq == 0) __hip_atomic_fetch_add(SS + row, (u64)(part * SSF), __ATOMIC_RELAXED, __HIP_MEMORY_SCOPE_AGENT); }
.LBB0_173:
	v_lshl_add_u32 v140, s66, 8, v144
	v_lshl_or_b32 v138, s67, 8, v146
	v_ashrrev_i32_e32 v141, 31, v140
	v_ashrrev_i32_e32 v139, 31, v138
	v_lshlrev_b64 v[156:157], 12, v[140:141]
	v_lshlrev_b64 v[142:143], 2, v[138:139]
	v_lshl_add_u64 v[148:149], s[2:3], 0, v[156:157]
	v_lshl_add_u64 v[158:159], v[148:149], 0, v[142:143]
	global_load_dwordx4 v[148:151], v[158:159], off
	global_load_dwordx4 v[152:155], v[158:159], off offset:16
	v_lshlrev_b64 v[162:163], 11, v[140:141]
	v_lshl_add_u64 v[156:157], s[48:49], 0, v[156:157]
	v_lshl_add_u64 v[162:163], s[20:21], 0, v[162:163]
	v_lshl_add_u64 v[164:165], v[156:157], 0, v[142:143]
	v_lshl_add_u64 v[162:163], v[138:139], 1, v[162:163]
	s_waitcnt vmcnt(0)
	v_pk_fma_f32 v[126:127], v[126:127], 0.5, v[150:151] op_sel_hi:[1,0,1]
	v_pk_fma_f32 v[124:125], v[124:125], 0.5, v[148:149] op_sel_hi:[1,0,1]
	v_pk_fma_f32 v[150:151], v[122:123], 0.5, v[154:155] op_sel_hi:[1,0,1]
	v_pk_fma_f32 v[148:149], v[120:121], 0.5, v[152:153] op_sel_hi:[1,0,1]
	v_cvt_pk_bf16_f32 v120, v124, v125
	v_cvt_pk_bf16_f32 v121, v126, v127
	v_cvt_pk_bf16_f32 v122, v148, v149
	v_cvt_pk_bf16_f32 v123, v150, v151
	global_store_dwordx4 v[164:165], v[124:127], off
	global_store_dwordx4 v[164:165], v[148:151], off offset:16
	global_store_dwordx4 v[162:163], v[120:123], off sc1
	global_load_dwordx4 v[152:155], v[158:159], off offset:512
	s_nop 0
	global_load_dwordx4 v[156:159], v[158:159], off offset:528
	v_and_b32_e32 v121, 64, v229
	v_xor_b32_e32 v120, 16, v229
	v_add_u32_e32 v121, 64, v121
	v_xor_b32_e32 v122, 32, v229
	v_cmp_lt_i32_e32 vcc, v120, v121
	v_mul_f32_e32 v123, v127, v127
	v_fmac_f32_e32 v123, v126, v126
	v_cndmask_b32_e32 v120, v229, v120, vcc
	v_cmp_lt_i32_e32 vcc, v122, v121
	v_lshlrev_b32_e32 v121, 2, v120
	v_mul_f32_e32 v127, v151, v151
	v_cndmask_b32_e32 v122, v229, v122, vcc
	v_lshlrev_b32_e32 v120, 2, v122
	v_mul_f32_e32 v122, v125, v125
	v_mul_f32_e32 v125, v149, v149
	v_fmac_f32_e32 v122, v124, v124
	v_fmac_f32_e32 v125, v148, v148
	v_add_f32_e32 v122, v122, v123
	v_fmac_f32_e32 v127, v150, v150
	v_add_f32_e32 v122, v125, v122
	v_add_f32_e32 v126, v127, v122
	s_waitcnt vmcnt(1)
	v_pk_fma_f32 v[118:119], v[118:119], 0.5, v[154:155] op_sel_hi:[1,0,1]
	v_pk_fma_f32 v[116:117], v[116:117], 0.5, v[152:153] op_sel_hi:[1,0,1]
	s_waitcnt vmcnt(0)
	v_pk_fma_f32 v[122:123], v[112:113], 0.5, v[156:157] op_sel_hi:[1,0,1]
	v_mul_f32_e32 v112, v117, v117
	v_mul_f32_e32 v113, v119, v119
	v_pk_fma_f32 v[124:125], v[114:115], 0.5, v[158:159] op_sel_hi:[1,0,1]
	v_mul_f32_e32 v114, v123, v123
	v_fmac_f32_e32 v112, v116, v116
	v_fmac_f32_e32 v113, v118, v118
	v_mul_f32_e32 v115, v125, v125
	v_fmac_f32_e32 v114, v122, v122
	v_add_f32_e32 v112, v112, v113
	v_add_f32_e32 v112, v114, v112
	v_fmac_f32_e32 v115, v124, v124
	v_add_f32_e32 v112, v115, v112
	v_add_f32_e32 v112, v126, v112
	ds_bpermute_b32 v113, v121, v112
	global_store_dwordx4 v[164:165], v[116:119], off offset:512
	global_store_dwordx4 v[164:165], v[122:125], off offset:528
	s_waitcnt lgkmcnt(0)
	v_add_f32_e32 v114, v112, v113
	ds_bpermute_b32 v115, v120, v114
	v_cvt_pk_bf16_f32 v116, v116, v117
	v_cvt_pk_bf16_f32 v117, v118, v119
	v_cvt_pk_bf16_f32 v118, v122, v123
	v_cvt_pk_bf16_f32 v119, v124, v125
	v_lshl_add_u64 v[112:113], v[140:141], 3, s[18:19]
	global_store_dwordx4 v[162:163], v[116:119], off offset:256 sc1
	s_and_saveexec_b64 s[16:17], s[42:43]
	s_cbranch_execz .LBB0_175
	s_waitcnt lgkmcnt(0)
	v_add_f32_e32 v114, v114, v115
	v_mul_f32_e32 v114, 0x4b800000, v114
	v_trunc_f32_e32 v114, v114
	v_mul_f32_e32 v115, 0x2f800000, v114
	v_floor_f32_e32 v115, v115
	v_fmac_f32_e32 v114, 0xcf800000, v115
	v_cvt_u32_f32_e32 v114, v114
	v_cvt_u32_f32_e32 v115, v115
	global_atomic_add_x2 v[112:113], v[114:115], off
.LBB0_175:
	s_or_b64 exec, exec, s[16:17]
	v_or_b32_e32 v118, 16, v140
	v_ashrrev_i32_e32 v119, 31, v118
	v_lshlrev_b64 v[126:127], 12, v[118:119]
	s_waitcnt lgkmcnt(0)
	v_lshl_add_u64 v[114:115], s[2:3], 0, v[126:127]
	v_lshl_add_u64 v[148:149], v[114:115], 0, v[142:143]
	global_load_dwordx4 v[114:117], v[148:149], off
	global_load_dwordx4 v[122:125], v[148:149], off offset:16
	v_lshlrev_b64 v[118:119], 11, v[118:119]
	v_lshl_add_u64 v[126:127], s[48:49], 0, v[126:127]
	v_lshl_add_u64 v[118:119], s[20:21], 0, v[118:119]
	v_lshl_add_u64 v[126:127], v[126:127], 0, v[142:143]
	v_lshl_add_u64 v[118:119], v[138:139], 1, v[118:119]
	s_waitcnt vmcnt(1)
	v_pk_fma_f32 v[110:111], v[110:111], 0.5, v[116:117] op_sel_hi:[1,0,1]
	v_pk_fma_f32 v[108:109], v[108:109], 0.5, v[114:115] op_sel_hi:[1,0,1]
	s_waitcnt vmcnt(0)
	v_pk_fma_f32 v[106:107], v[106:107], 0.5, v[124:125] op_sel_hi:[1,0,1]
	v_pk_fma_f32 v[104:105], v[104:105], 0.5, v[122:123] op_sel_hi:[1,0,1]
	v_cvt_pk_bf16_f32 v114, v108, v109
	v_cvt_pk_bf16_f32 v115, v110, v111
	v_cvt_pk_bf16_f32 v116, v104, v105
	v_cvt_pk_bf16_f32 v117, v106, v107
	global_store_dwordx4 v[126:127], v[108:111], off
	global_store_dwordx4 v[126:127], v[104:107], off offset:16
	global_store_dwordx4 v[118:119], v[114:117], off sc1
	global_load_dwordx4 v[114:117], v[148:149], off offset:512
	s_nop 0
	global_load_dwordx4 v[122:125], v[148:149], off offset:528
	v_mul_f32_e32 v109, v109, v109
	v_mul_f32_e32 v111, v111, v111
	v_mul_f32_e32 v105, v105, v105
	v_fmac_f32_e32 v109, v108, v108
	v_fmac_f32_e32 v111, v110, v110
	v_mul_f32_e32 v107, v107, v107
	v_fmac_f32_e32 v105, v104, v104
	v_add_f32_e32 v104, v109, v111
	v_fmac_f32_e32 v107, v106, v106
	v_add_f32_e32 v104, v105, v104
	v_add_f32_e32 v108, v107, v104
	s_waitcnt vmcnt(1)
	v_pk_fma_f32 v[102:103], v[102:103], 0.5, v[116:117] op_sel_hi:[1,0,1]
	v_pk_fma_f32 v[100:101], v[100:101], 0.5, v[114:115] op_sel_hi:[1,0,1]
	s_waitcnt vmcnt(0)
	v_pk_fma_f32 v[104:105], v[96:97], 0.5, v[122:123] op_sel_hi:[1,0,1]
	v_mul_f32_e32 v96, v101, v101
	v_mul_f32_e32 v97, v103, v103
	v_pk_fma_f32 v[106:107], v[98:99], 0.5, v[124:125] op_sel_hi:[1,0,1]
	v_mul_f32_e32 v98, v105, v105
	v_fmac_f32_e32 v96, v100, v100
	v_fmac_f32_e32 v97, v102, v102
	v_mul_f32_e32 v99, v107, v107
	v_fmac_f32_e32 v98, v104, v104
	v_add_f32_e32 v96, v96, v97
	v_add_f32_e32 v96, v98, v96
	v_fmac_f32_e32 v99, v106, v106
	v_add_f32_e32 v96, v99, v96
	v_add_f32_e32 v96, v108, v96
	ds_bpermute_b32 v97, v121, v96
	global_store_dwordx4 v[126:127], v[100:103], off offset:512
	global_store_dwordx4 v[126:127], v[104:107], off offset:528
	v_cvt_pk_bf16_f32 v98, v100, v101
	v_cvt_pk_bf16_f32 v99, v102, v103
	v_cvt_pk_bf16_f32 v100, v104, v105
	s_waitcnt lgkmcnt(0)
	v_add_f32_e32 v96, v96, v97
	ds_bpermute_b32 v97, v120, v96
	v_cvt_pk_bf16_f32 v101, v106, v107
	global_store_dwordx4 v[118:119], v[98:101], off offset:256 sc1
	s_and_saveexec_b64 s[16:17], s[42:43]
	s_cbranch_execz .LBB0_177
	s_waitcnt lgkmcnt(0)
	v_add_f32_e32 v96, v96, v97
	v_mul_f32_e32 v96, 0x4b800000, v96
	v_trunc_f32_e32 v96, v96
	v_mul_f32_e32 v97, 0x2f800000, v96
	v_floor_f32_e32 v97, v97
	v_fmac_f32_e32 v96, 0xcf800000, v97
	v_cvt_u32_f32_e32 v96, v96
	v_cvt_u32_f32_e32 v97, v97
	global_atomic_add_x2 v[112:113], v[96:97], off offset:128
; __device__ __forceinline__ unsigned cvtpk(float lo, float hi) { f32x2_t v = {lo, hi}; bf16x2_t b = __builtin_convertvector(v, bf16x2_t); return __builtin_bit_cast(unsigned, b); }
;     __device__ __forceinline__ void operator()(const Acc& acc, const Unit& u, int wr, int wc, int fr, int fq) const {
;         const int row0 = u.pm * BM + wr * 64 + fr, col0 = u.pn * BM + wc * 32 + 8 * fq;
; #pragma unroll
;         for (int ai = 0; ai < 2; ++ai)
; #pragma unroll
;             for (int m = 0; m < 4; ++m) { const int row = row0 + ai * HALF + m * 16; float* rp = X + (size_t)row * DM + col0; const float* ip = Xin + (size_t)row * DM + col0; bf16_t* bp = XB + (size_t)row * DM + col0; float part = 0.f;
; #pragma unroll
;                 for (int bj = 0; bj < 2; ++bj) { f32x4* p = (f32x4*)(rp + bj * HALF); const f32x4* q = (const f32x4*)(ip + bj * HALF); f32x4 a = q[0], b = q[1]; a += acc[ai][bj][m][0] * scale; b += acc[ai][bj][m][1] * scale; p[0] = a; p[1] = b;
;                     *(u32x4*)(bp + bj * HALF) = (u32x4){cvtpk(a[0], a[1]), cvtpk(a[2], a[3]), cvtpk(b[0], b[1]), cvtpk(b[2], b[3])};
;                     part += (a[0] * a[0] + a[1] * a[1]) + (a[2] * a[2] + a[3] * a[3]) + (b[0] * b[0] + b[1] * b[1]) + (b[2] * b[2] + b[3] * b[3]); }
;                 part += __shfl_xor(part, 16); part += __shfl_xor(part, 32);
;                 if (fq == 0) __hip_atomic_fetch_add(SS + row, (u64)(part * SSF), __ATOMIC_RELAXED, __HIP_MEMORY_SCOPE_AGENT); }
.LBB0_177:
	s_or_b64 exec, exec, s[16:17]
	v_or_b32_e32 v104, 32, v140
	v_ashrrev_i32_e32 v105, 31, v104
	v_lshlrev_b64 v[106:107], 12, v[104:105]
	s_waitcnt lgkmcnt(0)
	v_lshl_add_u64 v[96:97], s[2:3], 0, v[106:107]
	v_lshl_add_u64 v[108:109], v[96:97], 0, v[142:143]
	global_load_dwordx4 v[96:99], v[108:109], off
	global_load_dwordx4 v[100:103], v[108:109], off offset:16
	v_lshlrev_b64 v[104:105], 11, v[104:105]
	v_lshl_add_u64 v[106:107], s[48:49], 0, v[106:107]
	v_lshl_add_u64 v[104:105], s[20:21], 0, v[104:105]
	v_lshl_add_u64 v[106:107], v[106:107], 0, v[142:143]
	v_lshl_add_u64 v[104:105], v[138:139], 1, v[104:105]
	s_waitcnt vmcnt(1)
	v_pk_fma_f32 v[94:95], v[94:95], 0.5, v[98:99] op_sel_hi:[1,0,1]
	v_pk_fma_f32 v[92:93], v[92:93], 0.5, v[96:97] op_sel_hi:[1,0,1]
	s_waitcnt vmcnt(0)
	v_pk_fma_f32 v[90:91], v[90:91], 0.5, v[102:103] op_sel_hi:[1,0,1]
	v_pk_fma_f32 v[88:89], v[88:89], 0.5, v[100:101] op_sel_hi:[1,0,1]
	v_cvt_pk_bf16_f32 v96, v92, v93
	v_cvt_pk_bf16_f32 v97, v94, v95
	v_cvt_pk_bf16_f32 v98, v88, v89
	v_cvt_pk_bf16_f32 v99, v90, v91
	global_store_dwordx4 v[106:107], v[92:95], off
	global_store_dwordx4 v[106:107], v[88:91], off offset:16
	global_store_dwordx4 v[104:105], v[96:99], off sc1
	global_load_dwordx4 v[96:99], v[108:109], off offset:512
	s_nop 0
	global_load_dwordx4 v[100:103], v[108:109], off offset:528
	v_mul_f32_e32 v93, v93, v93
	v_mul_f32_e32 v95, v95, v95
	v_mul_f32_e32 v89, v89, v89
	v_fmac_f32_e32 v93, v92, v92
	v_fmac_f32_e32 v95, v94, v94
	v_mul_f32_e32 v91, v91, v91
	v_fmac_f32_e32 v89, v88, v88
	v_add_f32_e32 v88, v93, v95
	v_fmac_f32_e32 v91, v90, v90
	v_add_f32_e32 v88, v89, v88
	v_add_f32_e32 v92, v91, v88
	s_waitcnt vmcnt(1)
	v_pk_fma_f32 v[86:87], v[86:87], 0.5, v[98:99] op_sel_hi:[1,0,1]
	v_pk_fma_f32 v[84:85], v[84:85], 0.5, v[96:97] op_sel_hi:[1,0,1]
	s_waitcnt vmcnt(0)
	v_pk_fma_f32 v[88:89], v[80:81], 0.5, v[100:101] op_sel_hi:[1,0,1]
	v_mul_f32_e32 v80, v85, v85
	v_mul_f32_e32 v81, v87, v87
	v_pk_fma_f32 v[90:91], v[82:83], 0.5, v[102:103] op_sel_hi:[1,0,1]
	v_mul_f32_e32 v82, v89, v89
	v_fmac_f32_e32 v80, v84, v84
	v_fmac_f32_e32 v81, v86, v86
	v_mul_f32_e32 v83, v91, v91
	v_fmac_f32_e32 v82, v88, v88
	v_add_f32_e32 v80, v80, v81
	v_add_f32_e32 v80, v82, v80
	v_fmac_f32_e32 v83, v90, v90
	v_add_f32_e32 v80, v83, v80
	v_add_f32_e32 v80, v92, v80
	ds_bpermute_b32 v81, v121, v80
	global_store_dwordx4 v[106:107], v[84:87], off offset:512
	global_store_dwordx4 v[106:107], v[88:91], off offset:528
	v_cvt_pk_bf16_f32 v82, v84, v85
	v_cvt_pk_bf16_f32 v83, v86, v87
	v_cvt_pk_bf16_f32 v84, v88, v89
	s_waitcnt lgkmcnt(0)
	v_add_f32_e32 v80, v80, v81
	ds_bpermute_b32 v81, v120, v80
	v_cvt_pk_bf16_f32 v85, v90, v91
	global_store_dwordx4 v[104:105], v[82:85], off offset:256 sc1
	s_and_saveexec_b64 s[16:17], s[42:43]
	s_cbranch_execz .LBB0_179
	s_waitcnt lgkmcnt(0)
	v_add_f32_e32 v80, v80, v81
	v_mul_f32_e32 v80, 0x4b800000, v80
	v_trunc_f32_e32 v80, v80
	v_mul_f32_e32 v81, 0x2f800000, v80
	v_floor_f32_e32 v81, v81
	v_fmac_f32_e32 v80, 0xcf800000, v81
	v_cvt_u32_f32_e32 v80, v80
	v_cvt_u32_f32_e32 v81, v81
	global_atomic_add_x2 v[112:113], v[80:81], off offset:256
.LBB0_179:
	s_or_b64 exec, exec, s[16:17]
	v_or_b32_e32 v88, 48, v140
	v_ashrrev_i32_e32 v89, 31, v88
	v_lshlrev_b64 v[90:91], 12, v[88:89]
	s_waitcnt lgkmcnt(0)
	v_lshl_add_u64 v[80:81], s[2:3], 0, v[90:91]
	v_lshl_add_u64 v[92:93], v[80:81], 0, v[142:143]
	global_load_dwordx4 v[80:83], v[92:93], off
	global_load_dwordx4 v[84:87], v[92:93], off offset:16
	v_lshlrev_b64 v[88:89], 11, v[88:89]
	v_lshl_add_u64 v[90:91], s[48:49], 0, v[90:91]
	v_lshl_add_u64 v[88:89], s[20:21], 0, v[88:89]
	v_lshl_add_u64 v[90:91], v[90:91], 0, v[142:143]
	v_lshl_add_u64 v[88:89], v[138:139], 1, v[88:89]
	s_waitcnt vmcnt(1)
	v_pk_fma_f32 v[78:79], v[78:79], 0.5, v[82:83] op_sel_hi:[1,0,1]
	v_pk_fma_f32 v[76:77], v[76:77], 0.5, v[80:81] op_sel_hi:[1,0,1]
	s_waitcnt vmcnt(0)
	v_pk_fma_f32 v[74:75], v[74:75], 0.5, v[86:87] op_sel_hi:[1,0,1]
	v_pk_fma_f32 v[72:73], v[72:73], 0.5, v[84:85] op_sel_hi:[1,0,1]
	v_cvt_pk_bf16_f32 v80, v76, v77
	v_cvt_pk_bf16_f32 v81, v78, v79
	v_cvt_pk_bf16_f32 v82, v72, v73
	v_cvt_pk_bf16_f32 v83, v74, v75
	global_store_dwordx4 v[90:91], v[76:79], off
	global_store_dwordx4 v[90:91], v[72:75], off offset:16
	global_store_dwordx4 v[88:89], v[80:83], off sc1
	global_load_dwordx4 v[80:83], v[92:93], off offset:512
	s_nop 0
	global_load_dwordx4 v[84:87], v[92:93], off offset:528
	v_mul_f32_e32 v77, v77, v77
	v_mul_f32_e32 v79, v79, v79
	v_mul_f32_e32 v73, v73, v73
	v_fmac_f32_e32 v77, v76, v76
	v_fmac_f32_e32 v79, v78, v78
	v_mul_f32_e32 v75, v75, v75
	v_fmac_f32_e32 v73, v72, v72
	v_add_f32_e32 v72, v77, v79
	v_fmac_f32_e32 v75, v74, v74
	v_add_f32_e32 v72, v73, v72
	v_add_f32_e32 v76, v75, v72
	s_waitcnt vmcnt(1)
	v_pk_fma_f32 v[70:71], v[70:71], 0.5, v[82:83] op_sel_hi:[1,0,1]
	v_pk_fma_f32 v[68:69], v[68:69], 0.5, v[80:81] op_sel_hi:[1,0,1]
	s_waitcnt vmcnt(0)
	v_pk_fma_f32 v[72:73], v[64:65], 0.5, v[84:85] op_sel_hi:[1,0,1]
	v_mul_f32_e32 v64, v69, v69
	v_mul_f32_e32 v65, v71, v71
	v_pk_fma_f32 v[74:75], v[66:67], 0.5, v[86:87] op_sel_hi:[1,0,1]
	v_mul_f32_e32 v66, v73, v73
	v_fmac_f32_e32 v64, v68, v68
	v_fmac_f32_e32 v65, v70, v70
	v_mul_f32_e32 v67, v75, v75
	v_fmac_f32_e32 v66, v72, v72
	v_add_f32_e32 v64, v64, v65
	v_add_f32_e32 v64, v66, v64
	v_fmac_f32_e32 v67, v74, v74
	v_add_f32_e32 v64, v67, v64
	v_add_f32_e32 v64, v76, v64
	ds_bpermute_b32 v65, v121, v64
	global_store_dwordx4 v[90:91], v[68:71], off offset:512
	global_store_dwordx4 v[90:91], v[72:75], off offset:528
	v_cvt_pk_bf16_f32 v66, v68, v69
	v_cvt_pk_bf16_f32 v67, v70, v71
	v_cvt_pk_bf16_f32 v68, v72, v73
	s_waitcnt lgkmcnt(0)
	v_add_f32_e32 v64, v64, v65
	ds_bpermute_b32 v65, v120, v64
	v_cvt_pk_bf16_f32 v69, v74, v75
	global_store_dwordx4 v[88:89], v[66:69], off offset:256 sc1
	s_and_saveexec_b64 s[16:17], s[42:43]
	s_cbranch_execz .LBB0_181
	s_waitcnt lgkmcnt(0)
	v_add_f32_e32 v64, v64, v65
	v_mul_f32_e32 v64, 0x4b800000, v64
	v_trunc_f32_e32 v64, v64
	v_mul_f32_e32 v65, 0x2f800000, v64
	v_floor_f32_e32 v65, v65
	v_fmac_f32_e32 v64, 0xcf800000, v65
	v_cvt_u32_f32_e32 v64, v64
	v_cvt_u32_f32_e32 v65, v65
	global_atomic_add_x2 v[112:113], v[64:65], off offset:384
; __device__ __forceinline__ unsigned cvtpk(float lo, float hi) { f32x2_t v = {lo, hi}; bf16x2_t b = __builtin_convertvector(v, bf16x2_t); return __builtin_bit_cast(unsigned, b); }
;     __device__ __forceinline__ void operator()(const Acc& acc, const Unit& u, int wr, int wc, int fr, int fq) const {
;         const int row0 = u.pm * BM + wr * 64 + fr, col0 = u.pn * BM + wc * 32 + 8 * fq;
; #pragma unroll
;         for (int ai = 0; ai < 2; ++ai)
; #pragma unroll
;             for (int m = 0; m < 4; ++m) { const int row = row0 + ai * HALF + m * 16; float* rp = X + (size_t)row * DM + col0; const float* ip = Xin + (size_t)row * DM + col0; bf16_t* bp = XB + (size_t)row * DM + col0; float part = 0.f;
; #pragma unroll
;                 for (int bj = 0; bj < 2; ++bj) { f32x4* p = (f32x4*)(rp + bj * HALF); const f32x4* q = (const f32x4*)(ip + bj * HALF); f32x4 a = q[0], b = q[1]; a += acc[ai][bj][m][0] * scale; b += acc[ai][bj][m][1] * scale; p[0] = a; p[1] = b;
;                     *(u32x4*)(bp + bj * HALF) = (u32x4){cvtpk(a[0], a[1]), cvtpk(a[2], a[3]), cvtpk(b[0], b[1]), cvtpk(b[2], b[3])};
;                     part += (a[0] * a[0] + a[1] * a[1]) + (a[2] * a[2] + a[3] * a[3]) + (b[0] * b[0] + b[1] * b[1]) + (b[2] * b[2] + b[3] * b[3]); }
;                 part += __shfl_xor(part, 16); part += __shfl_xor(part, 32);
;                 if (fq == 0) __hip_atomic_fetch_add(SS + row, (u64)(part * SSF), __ATOMIC_RELAXED, __HIP_MEMORY_SCOPE_AGENT); }
.LBB0_181:
	s_or_b64 exec, exec, s[16:17]
	v_add_u32_e32 v72, 0x80, v140
	v_ashrrev_i32_e32 v73, 31, v72
	v_lshlrev_b64 v[74:75], 12, v[72:73]
	s_waitcnt lgkmcnt(0)
	v_lshl_add_u64 v[64:65], s[2:3], 0, v[74:75]
	v_lshl_add_u64 v[76:77], v[64:65], 0, v[142:143]
	global_load_dwordx4 v[64:67], v[76:77], off
	global_load_dwordx4 v[68:71], v[76:77], off offset:16
	v_lshlrev_b64 v[72:73], 11, v[72:73]
	v_lshl_add_u64 v[74:75], s[48:49], 0, v[74:75]
	v_lshl_add_u64 v[72:73], s[20:21], 0, v[72:73]
	v_lshl_add_u64 v[74:75], v[74:75], 0, v[142:143]
	v_lshl_add_u64 v[72:73], v[138:139], 1, v[72:73]
	s_waitcnt vmcnt(1)
	v_pk_fma_f32 v[62:63], v[62:63], 0.5, v[66:67] op_sel_hi:[1,0,1]
	v_pk_fma_f32 v[60:61], v[60:61], 0.5, v[64:65] op_sel_hi:[1,0,1]
	s_waitcnt vmcnt(0)
	v_pk_fma_f32 v[58:59], v[58:59], 0.5, v[70:71] op_sel_hi:[1,0,1]
	v_pk_fma_f32 v[56:57], v[56:57], 0.5, v[68:69] op_sel_hi:[1,0,1]
	v_cvt_pk_bf16_f32 v64, v60, v61
	v_cvt_pk_bf16_f32 v65, v62, v63
	v_cvt_pk_bf16_f32 v66, v56, v57
	v_cvt_pk_bf16_f32 v67, v58, v59
	global_store_dwordx4 v[74:75], v[60:63], off
	global_store_dwordx4 v[74:75], v[56:59], off offset:16
	global_store_dwordx4 v[72:73], v[64:67], off sc1
	global_load_dwordx4 v[64:67], v[76:77], off offset:512
	s_nop 0
	global_load_dwordx4 v[68:71], v[76:77], off offset:528
	v_mul_f32_e32 v61, v61, v61
	v_mul_f32_e32 v63, v63, v63
	v_mul_f32_e32 v57, v57, v57
	v_fmac_f32_e32 v61, v60, v60
	v_fmac_f32_e32 v63, v62, v62
	v_mul_f32_e32 v59, v59, v59
	v_fmac_f32_e32 v57, v56, v56
	v_add_f32_e32 v56, v61, v63
	v_fmac_f32_e32 v59, v58, v58
	v_add_f32_e32 v56, v57, v56
	v_add_f32_e32 v60, v59, v56
	s_waitcnt vmcnt(1)
	v_pk_fma_f32 v[54:55], v[54:55], 0.5, v[66:67] op_sel_hi:[1,0,1]
	v_pk_fma_f32 v[52:53], v[52:53], 0.5, v[64:65] op_sel_hi:[1,0,1]
	s_waitcnt vmcnt(0)
	v_pk_fma_f32 v[56:57], v[48:49], 0.5, v[68:69] op_sel_hi:[1,0,1]
	v_mul_f32_e32 v48, v53, v53
	v_mul_f32_e32 v49, v55, v55
	v_pk_fma_f32 v[58:59], v[50:51], 0.5, v[70:71] op_sel_hi:[1,0,1]
	v_mul_f32_e32 v50, v57, v57
	v_fmac_f32_e32 v48, v52, v52
	v_fmac_f32_e32 v49, v54, v54
	v_mul_f32_e32 v51, v59, v59
	v_fmac_f32_e32 v50, v56, v56
	v_add_f32_e32 v48, v48, v49
	v_add_f32_e32 v48, v50, v48
	v_fmac_f32_e32 v51, v58, v58
	v_add_f32_e32 v48, v51, v48
	v_add_f32_e32 v48, v60, v48
	ds_bpermute_b32 v49, v121, v48
	global_store_dwordx4 v[74:75], v[52:55], off offset:512
	global_store_dwordx4 v[74:75], v[56:59], off offset:528
	v_cvt_pk_bf16_f32 v50, v52, v53
	v_cvt_pk_bf16_f32 v51, v54, v55
	v_cvt_pk_bf16_f32 v52, v56, v57
	s_waitcnt lgkmcnt(0)
	v_add_f32_e32 v48, v48, v49
	ds_bpermute_b32 v49, v120, v48
	v_cvt_pk_bf16_f32 v53, v58, v59
	global_store_dwordx4 v[72:73], v[50:53], off offset:256 sc1
	s_and_saveexec_b64 s[16:17], s[42:43]
	s_cbranch_execz .LBB0_183
	s_waitcnt lgkmcnt(0)
	v_add_f32_e32 v48, v48, v49
	v_mul_f32_e32 v48, 0x4b800000, v48
	v_trunc_f32_e32 v48, v48
	v_mul_f32_e32 v49, 0x2f800000, v48
	v_floor_f32_e32 v49, v49
	v_fmac_f32_e32 v48, 0xcf800000, v49
	v_cvt_u32_f32_e32 v48, v48
	v_cvt_u32_f32_e32 v49, v49
	global_atomic_add_x2 v[112:113], v[48:49], off offset:1024
.LBB0_183:
	s_or_b64 exec, exec, s[16:17]
	v_add_u32_e32 v56, 0x90, v140
	v_ashrrev_i32_e32 v57, 31, v56
	v_lshlrev_b64 v[58:59], 12, v[56:57]
	s_waitcnt lgkmcnt(0)
	v_lshl_add_u64 v[48:49], s[2:3], 0, v[58:59]
	v_lshl_add_u64 v[60:61], v[48:49], 0, v[142:143]
	global_load_dwordx4 v[48:51], v[60:61], off
	global_load_dwordx4 v[52:55], v[60:61], off offset:16
	v_lshlrev_b64 v[56:57], 11, v[56:57]
	v_lshl_add_u64 v[58:59], s[48:49], 0, v[58:59]
	v_lshl_add_u64 v[56:57], s[20:21], 0, v[56:57]
	v_lshl_add_u64 v[58:59], v[58:59], 0, v[142:143]
	v_lshl_add_u64 v[56:57], v[138:139], 1, v[56:57]
	s_waitcnt vmcnt(1)
	v_pk_fma_f32 v[46:47], v[46:47], 0.5, v[50:51] op_sel_hi:[1,0,1]
	v_pk_fma_f32 v[44:45], v[44:45], 0.5, v[48:49] op_sel_hi:[1,0,1]
	s_waitcnt vmcnt(0)
	v_pk_fma_f32 v[42:43], v[42:43], 0.5, v[54:55] op_sel_hi:[1,0,1]
	v_pk_fma_f32 v[40:41], v[40:41], 0.5, v[52:53] op_sel_hi:[1,0,1]
	v_cvt_pk_bf16_f32 v48, v44, v45
	v_cvt_pk_bf16_f32 v49, v46, v47
	v_cvt_pk_bf16_f32 v50, v40, v41
	v_cvt_pk_bf16_f32 v51, v42, v43
	global_store_dwordx4 v[58:59], v[44:47], off
	global_store_dwordx4 v[58:59], v[40:43], off offset:16
	global_store_dwordx4 v[56:57], v[48:51], off sc1
	global_load_dwordx4 v[48:51], v[60:61], off offset:512
	s_nop 0
	global_load_dwordx4 v[52:55], v[60:61], off offset:528
	v_mul_f32_e32 v45, v45, v45
	v_mul_f32_e32 v47, v47, v47
	v_mul_f32_e32 v41, v41, v41
	v_fmac_f32_e32 v45, v44, v44
	v_fmac_f32_e32 v47, v46, v46
	v_mul_f32_e32 v43, v43, v43
	v_fmac_f32_e32 v41, v40, v40
	v_add_f32_e32 v40, v45, v47
	v_fmac_f32_e32 v43, v42, v42
	v_add_f32_e32 v40, v41, v40
	v_add_f32_e32 v44, v43, v40
	s_waitcnt vmcnt(1)
	v_pk_fma_f32 v[38:39], v[38:39], 0.5, v[50:51] op_sel_hi:[1,0,1]
	v_pk_fma_f32 v[36:37], v[36:37], 0.5, v[48:49] op_sel_hi:[1,0,1]
	s_waitcnt vmcnt(0)
	v_pk_fma_f32 v[40:41], v[32:33], 0.5, v[52:53] op_sel_hi:[1,0,1]
	v_mul_f32_e32 v32, v37, v37
	v_mul_f32_e32 v33, v39, v39
	v_pk_fma_f32 v[42:43], v[34:35], 0.5, v[54:55] op_sel_hi:[1,0,1]
	v_mul_f32_e32 v34, v41, v41
	v_fmac_f32_e32 v32, v36, v36
	v_fmac_f32_e32 v33, v38, v38
	v_mul_f32_e32 v35, v43, v43
	v_fmac_f32_e32 v34, v40, v40
	v_add_f32_e32 v32, v32, v33
	v_add_f32_e32 v32, v34, v32
	v_fmac_f32_e32 v35, v42, v42
	v_add_f32_e32 v32, v35, v32
	v_add_f32_e32 v32, v44, v32
	ds_bpermute_b32 v33, v121, v32
	global_store_dwordx4 v[58:59], v[36:39], off offset:512
	global_store_dwordx4 v[58:59], v[40:43], off offset:528
	v_cvt_pk_bf16_f32 v34, v36, v37
	v_cvt_pk_bf16_f32 v35, v38, v39
	v_cvt_pk_bf16_f32 v36, v40, v41
	s_waitcnt lgkmcnt(0)
	v_add_f32_e32 v32, v32, v33
	ds_bpermute_b32 v33, v120, v32
	v_cvt_pk_bf16_f32 v37, v42, v43
	global_store_dwordx4 v[56:57], v[34:37], off offset:256 sc1
	s_and_saveexec_b64 s[16:17], s[42:43]
	s_cbranch_execz .LBB0_185
	s_waitcnt lgkmcnt(0)
	v_add_f32_e32 v32, v32, v33
	v_mul_f32_e32 v32, 0x4b800000, v32
	v_trunc_f32_e32 v32, v32
	v_mul_f32_e32 v33, 0x2f800000, v32
	v_floor_f32_e32 v33, v33
	v_fmac_f32_e32 v32, 0xcf800000, v33
	v_cvt_u32_f32_e32 v32, v32
	v_cvt_u32_f32_e32 v33, v33
	global_atomic_add_x2 v[112:113], v[32:33], off offset:1152
; __device__ __forceinline__ unsigned cvtpk(float lo, float hi) { f32x2_t v = {lo, hi}; bf16x2_t b = __builtin_convertvector(v, bf16x2_t); return __builtin_bit_cast(unsigned, b); }
;     __device__ __forceinline__ void operator()(const Acc& acc, const Unit& u, int wr, int wc, int fr, int fq) const {
;         const int row0 = u.pm * BM + wr * 64 + fr, col0 = u.pn * BM + wc * 32 + 8 * fq;
; #pragma unroll
;         for (int ai = 0; ai < 2; ++ai)
; #pragma unroll
;             for (int m = 0; m < 4; ++m) { const int row = row0 + ai * HALF + m * 16; float* rp = X + (size_t)row * DM + col0; const float* ip = Xin + (size_t)row * DM + col0; bf16_t* bp = XB + (size_t)row * DM + col0; float part = 0.f;
; #pragma unroll
;                 for (int bj = 0; bj < 2; ++bj) { f32x4* p = (f32x4*)(rp + bj * HALF); const f32x4* q = (const f32x4*)(ip + bj * HALF); f32x4 a = q[0], b = q[1]; a += acc[ai][bj][m][0] * scale; b += acc[ai][bj][m][1] * scale; p[0] = a; p[1] = b;
;                     *(u32x4*)(bp + bj * HALF) = (u32x4){cvtpk(a[0], a[1]), cvtpk(a[2], a[3]), cvtpk(b[0], b[1]), cvtpk(b[2], b[3])};
;                     part += (a[0] * a[0] + a[1] * a[1]) + (a[2] * a[2] + a[3] * a[3]) + (b[0] * b[0] + b[1] * b[1]) + (b[2] * b[2] + b[3] * b[3]); }
;                 part += __shfl_xor(part, 16); part += __shfl_xor(part, 32);
;                 if (fq == 0) __hip_atomic_fetch_add(SS + row, (u64)(part * SSF), __ATOMIC_RELAXED, __HIP_MEMORY_SCOPE_AGENT); }
.LBB0_185:
	s_or_b64 exec, exec, s[16:17]
	v_add_u32_e32 v40, 0xa0, v140
	v_ashrrev_i32_e32 v41, 31, v40
	v_lshlrev_b64 v[42:43], 12, v[40:41]
	s_waitcnt lgkmcnt(0)
	v_lshl_add_u64 v[32:33], s[2:3], 0, v[42:43]
	v_lshl_add_u64 v[44:45], v[32:33], 0, v[142:143]
	global_load_dwordx4 v[32:35], v[44:45], off
	global_load_dwordx4 v[36:39], v[44:45], off offset:16
	v_lshlrev_b64 v[40:41], 11, v[40:41]
	v_lshl_add_u64 v[42:43], s[48:49], 0, v[42:43]
	v_lshl_add_u64 v[40:41], s[20:21], 0, v[40:41]
	v_lshl_add_u64 v[42:43], v[42:43], 0, v[142:143]
	v_lshl_add_u64 v[40:41], v[138:139], 1, v[40:41]
	s_waitcnt vmcnt(1)
	v_pk_fma_f32 v[30:31], v[30:31], 0.5, v[34:35] op_sel_hi:[1,0,1]
	v_pk_fma_f32 v[28:29], v[28:29], 0.5, v[32:33] op_sel_hi:[1,0,1]
	s_waitcnt vmcnt(0)
	v_pk_fma_f32 v[26:27], v[26:27], 0.5, v[38:39] op_sel_hi:[1,0,1]
	v_pk_fma_f32 v[24:25], v[24:25], 0.5, v[36:37] op_sel_hi:[1,0,1]
	v_cvt_pk_bf16_f32 v32, v28, v29
	v_cvt_pk_bf16_f32 v33, v30, v31
	v_cvt_pk_bf16_f32 v34, v24, v25
	v_cvt_pk_bf16_f32 v35, v26, v27
	global_store_dwordx4 v[42:43], v[28:31], off
	global_store_dwordx4 v[42:43], v[24:27], off offset:16
	global_store_dwordx4 v[40:41], v[32:35], off sc1
	global_load_dwordx4 v[32:35], v[44:45], off offset:512
	s_nop 0
	global_load_dwordx4 v[36:39], v[44:45], off offset:528
	v_mul_f32_e32 v29, v29, v29
	v_mul_f32_e32 v31, v31, v31
	v_mul_f32_e32 v25, v25, v25
	v_fmac_f32_e32 v29, v28, v28
	v_fmac_f32_e32 v31, v30, v30
	v_mul_f32_e32 v27, v27, v27
	v_fmac_f32_e32 v25, v24, v24
	v_add_f32_e32 v24, v29, v31
	v_fmac_f32_e32 v27, v26, v26
	v_add_f32_e32 v24, v25, v24
	v_add_f32_e32 v28, v27, v24
	s_waitcnt vmcnt(1)
	v_pk_fma_f32 v[22:23], v[22:23], 0.5, v[34:35] op_sel_hi:[1,0,1]
	v_pk_fma_f32 v[20:21], v[20:21], 0.5, v[32:33] op_sel_hi:[1,0,1]
	s_waitcnt vmcnt(0)
	v_pk_fma_f32 v[24:25], v[16:17], 0.5, v[36:37] op_sel_hi:[1,0,1]
	v_mul_f32_e32 v16, v21, v21
	v_mul_f32_e32 v17, v23, v23
	v_pk_fma_f32 v[26:27], v[18:19], 0.5, v[38:39] op_sel_hi:[1,0,1]
	v_mul_f32_e32 v18, v25, v25
	v_fmac_f32_e32 v16, v20, v20
	v_fmac_f32_e32 v17, v22, v22
	v_mul_f32_e32 v19, v27, v27
	v_fmac_f32_e32 v18, v24, v24
	v_add_f32_e32 v16, v16, v17
	v_add_f32_e32 v16, v18, v16
	v_fmac_f32_e32 v19, v26, v26
	v_add_f32_e32 v16, v19, v16
	v_add_f32_e32 v16, v28, v16
	ds_bpermute_b32 v17, v121, v16
	global_store_dwordx4 v[42:43], v[20:23], off offset:512
	global_store_dwordx4 v[42:43], v[24:27], off offset:528
	v_cvt_pk_bf16_f32 v18, v20, v21
	v_cvt_pk_bf16_f32 v19, v22, v23
	v_cvt_pk_bf16_f32 v20, v24, v25
	s_waitcnt lgkmcnt(0)
	v_add_f32_e32 v16, v16, v17
	ds_bpermute_b32 v17, v120, v16
	v_cvt_pk_bf16_f32 v21, v26, v27
	global_store_dwordx4 v[40:41], v[18:21], off offset:256 sc1
	s_and_saveexec_b64 s[16:17], s[42:43]
	s_cbranch_execz .LBB0_187
	s_waitcnt lgkmcnt(0)
	v_add_f32_e32 v16, v16, v17
	v_mul_f32_e32 v16, 0x4b800000, v16
	v_trunc_f32_e32 v16, v16
	v_mul_f32_e32 v17, 0x2f800000, v16
	v_floor_f32_e32 v17, v17
	v_fmac_f32_e32 v16, 0xcf800000, v17
	v_cvt_u32_f32_e32 v16, v16
	v_cvt_u32_f32_e32 v17, v17
	global_atomic_add_x2 v[112:113], v[16:17], off offset:1280
.LBB0_187:
	s_or_b64 exec, exec, s[16:17]
	v_add_u32_e32 v16, 0xb0, v140
	s_waitcnt lgkmcnt(0)
	v_ashrrev_i32_e32 v17, 31, v16
	v_lshlrev_b64 v[18:19], 12, v[16:17]
	v_lshl_add_u64 v[20:21], s[48:49], 0, v[18:19]
	v_lshl_add_u64 v[18:19], s[2:3], 0, v[18:19]
	v_lshlrev_b64 v[16:17], 11, v[16:17]
	v_lshl_add_u64 v[26:27], v[18:19], 0, v[142:143]
	v_lshl_add_u64 v[16:17], s[20:21], 0, v[16:17]
	v_lshl_add_u64 v[24:25], v[20:21], 0, v[142:143]
	v_lshl_add_u64 v[28:29], v[138:139], 1, v[16:17]
	global_load_dwordx4 v[16:19], v[26:27], off offset:16
	global_load_dwordx4 v[20:23], v[26:27], off
	s_waitcnt vmcnt(1)
	v_pk_fma_f32 v[10:11], v[10:11], 0.5, v[18:19] op_sel_hi:[1,0,1]
	s_waitcnt vmcnt(0)
	v_pk_fma_f32 v[14:15], v[14:15], 0.5, v[22:23] op_sel_hi:[1,0,1]
	v_pk_fma_f32 v[12:13], v[12:13], 0.5, v[20:21] op_sel_hi:[1,0,1]
	v_pk_fma_f32 v[8:9], v[8:9], 0.5, v[16:17] op_sel_hi:[1,0,1]
	global_store_dwordx4 v[24:25], v[12:15], off
	global_store_dwordx4 v[24:25], v[8:11], off offset:16
	v_cvt_pk_bf16_f32 v16, v12, v13
	v_mul_f32_e32 v13, v13, v13
	v_fmac_f32_e32 v13, v12, v12
	v_mul_f32_e32 v12, v15, v15
	v_cvt_pk_bf16_f32 v18, v8, v9
	v_fmac_f32_e32 v12, v14, v14
	v_mul_f32_e32 v9, v9, v9
	v_add_f32_e32 v12, v13, v12
	v_fmac_f32_e32 v9, v8, v8
	v_cvt_pk_bf16_f32 v17, v14, v15
	v_cvt_pk_bf16_f32 v19, v10, v11
	v_add_f32_e32 v8, v9, v12
	v_mul_f32_e32 v9, v11, v11
	global_store_dwordx4 v[28:29], v[16:19], off sc1
	v_fmac_f32_e32 v9, v10, v10
	s_nop 0
	v_add_f32_e32 v16, v9, v8
	global_load_dwordx4 v[8:11], v[26:27], off offset:528
	global_load_dwordx4 v[12:15], v[26:27], off offset:512
	s_waitcnt vmcnt(1)
	v_pk_fma_f32 v[2:3], v[2:3], 0.5, v[10:11] op_sel_hi:[1,0,1]
	s_waitcnt vmcnt(0)
	v_pk_fma_f32 v[6:7], v[6:7], 0.5, v[14:15] op_sel_hi:[1,0,1]
	v_pk_fma_f32 v[4:5], v[4:5], 0.5, v[12:13] op_sel_hi:[1,0,1]
	v_pk_fma_f32 v[0:1], v[0:1], 0.5, v[8:9] op_sel_hi:[1,0,1]
	global_store_dwordx4 v[24:25], v[4:7], off offset:512
	global_store_dwordx4 v[24:25], v[0:3], off offset:528
	v_cvt_pk_bf16_f32 v8, v4, v5
	v_mul_f32_e32 v5, v5, v5
	v_fmac_f32_e32 v5, v4, v4
	v_mul_f32_e32 v4, v7, v7
	v_cvt_pk_bf16_f32 v10, v0, v1
	v_fmac_f32_e32 v4, v6, v6
	v_mul_f32_e32 v1, v1, v1
	v_add_f32_e32 v4, v5, v4
	v_fmac_f32_e32 v1, v0, v0
	v_add_f32_e32 v0, v1, v4
	v_mul_f32_e32 v1, v3, v3
	v_fmac_f32_e32 v1, v2, v2
	v_add_f32_e32 v0, v1, v0
	v_add_f32_e32 v0, v16, v0
	ds_bpermute_b32 v1, v121, v0
	v_cvt_pk_bf16_f32 v9, v6, v7
	v_cvt_pk_bf16_f32 v11, v2, v3
	global_store_dwordx4 v[28:29], v[8:11], off offset:256 sc1
	s_waitcnt lgkmcnt(0)
	v_add_f32_e32 v0, v0, v1
	ds_bpermute_b32 v1, v120, v0
	s_and_saveexec_b64 s[16:17], s[42:43]
	s_cbranch_execz .LBB0_189
	s_waitcnt lgkmcnt(0)
	v_add_f32_e32 v0, v0, v1
	v_mul_f32_e32 v0, 0x4b800000, v0
	v_trunc_f32_e32 v0, v0
	v_mul_f32_e32 v1, 0x2f800000, v0
	v_floor_f32_e32 v1, v1
	v_fmac_f32_e32 v0, 0xcf800000, v1
	v_cvt_u32_f32_e32 v0, v0
	v_cvt_u32_f32_e32 v1, v1
	global_atomic_add_x2 v[112:113], v[0:1], off offset:1408

; __device__ __forceinline__ unsigned cvtpk(float lo, float hi) { f32x2_t v = {lo, hi}; bf16x2_t b = __builtin_convertvector(v, bf16x2_t); return __builtin_bit_cast(unsigned, b); }
;     __device__ __forceinline__ void operator()(const Acc& acc, const Unit& u, int wr, int wc, int fr, int fq) const {
;     ...
;                 for (int bj = 0; bj < 2; ++bj) { const int col = col0 + bj * HALF; const f32x4 a = acc[ai][bj][m][0] * rs, b = acc[ai][bj][m][1] * rs;
;                     if (col < ZC) *(u32x4*)(ZCp + row * ZC + col) = (u32x4){cvtpk(a[0], a[1]), cvtpk(a[2], a[3]), cvtpk(b[0], b[1]), cvtpk(b[2], b[3])};
;                     else if (col < DIN) { f32x4* p = (f32x4*)(ZRp + row * ZR + (col - ZC)); p[0] = a; p[1] = b; } } }
.LBB0_262:
	s_or_saveexec_b64 s[0:1], s[0:1]
	v_mad_i64_i32 v[164:165], s[16:17], v142, s85, 0
	v_lshl_add_u64 v[164:165], s[14:15], 0, v[164:165]
	v_ashrrev_i32_e32 v141, 31, v140
	s_xor_b64 exec, exec, s[0:1]
	s_cbranch_execz .LBB0_264
	v_cvt_pk_bf16_f32 v124, v124, v125
	v_cvt_pk_bf16_f32 v125, v126, v127
	v_cvt_pk_bf16_f32 v126, v120, v121
	v_cvt_pk_bf16_f32 v127, v122, v123
	v_lshl_add_u64 v[120:121], v[140:141], 1, v[164:165]
	global_store_dwordx4 v[120:121], v[124:127], off sc1

; __device__ __forceinline__ unsigned cvtpk(float lo, float hi) { f32x2_t v = {lo, hi}; bf16x2_t b = __builtin_convertvector(v, bf16x2_t); return __builtin_bit_cast(unsigned, b); }
;     __device__ __forceinline__ void operator()(const Acc& acc, const Unit& u, int wr, int wc, int fr, int fq) const {
;     ...
;                 for (int bj = 0; bj < 2; ++bj) { const int col = col0 + bj * HALF; const f32x4 a = acc[ai][bj][m][0] * rs, b = acc[ai][bj][m][1] * rs;
;                     if (col < ZC) *(u32x4*)(ZCp + row * ZC + col) = (u32x4){cvtpk(a[0], a[1]), cvtpk(a[2], a[3]), cvtpk(b[0], b[1]), cvtpk(b[2], b[3])};
;                     else if (col < DIN) { f32x4* p = (f32x4*)(ZRp + row * ZR + (col - ZC)); p[0] = a; p[1] = b; } } }
.LBB0_268:
	s_andn2_saveexec_b64 s[0:1], s[0:1]
	s_cbranch_execz .LBB0_270
	v_cvt_pk_bf16_f32 v116, v116, v117
	v_cvt_pk_bf16_f32 v117, v118, v119
	v_cvt_pk_bf16_f32 v118, v112, v113
	v_cvt_pk_bf16_f32 v119, v114, v115
	v_lshl_add_u64 v[112:113], v[140:141], 1, v[164:165]
	global_store_dwordx4 v[112:113], v[116:119], off offset:256 sc1

; __device__ __forceinline__ unsigned cvtpk(float lo, float hi) { f32x2_t v = {lo, hi}; bf16x2_t b = __builtin_convertvector(v, bf16x2_t); return __builtin_bit_cast(unsigned, b); }
;     __device__ __forceinline__ void operator()(const Acc& acc, const Unit& u, int wr, int wc, int fr, int fq) const {
;     ...
;                 for (int bj = 0; bj < 2; ++bj) { const int col = col0 + bj * HALF; const f32x4 a = acc[ai][bj][m][0] * rs, b = acc[ai][bj][m][1] * rs;
;                     if (col < ZC) *(u32x4*)(ZCp + row * ZC + col) = (u32x4){cvtpk(a[0], a[1]), cvtpk(a[2], a[3]), cvtpk(b[0], b[1]), cvtpk(b[2], b[3])};
;                     else if (col < DIN) { f32x4* p = (f32x4*)(ZRp + row * ZR + (col - ZC)); p[0] = a; p[1] = b; } } }
.LBB0_273:
	s_or_saveexec_b64 s[0:1], s[0:1]
	v_mad_i64_i32 v[116:117], s[16:17], v115, s85, 0
	v_lshl_add_u64 v[116:117], s[14:15], 0, v[116:117]
	s_xor_b64 exec, exec, s[0:1]
	s_cbranch_execz .LBB0_275
	v_cvt_pk_bf16_f32 v108, v108, v109
	v_cvt_pk_bf16_f32 v109, v110, v111
	v_cvt_pk_bf16_f32 v110, v104, v105
	v_cvt_pk_bf16_f32 v111, v106, v107
	v_lshl_add_u64 v[104:105], v[140:141], 1, v[116:117]
	global_store_dwordx4 v[104:105], v[108:111], off sc1

; __device__ __forceinline__ unsigned cvtpk(float lo, float hi) { f32x2_t v = {lo, hi}; bf16x2_t b = __builtin_convertvector(v, bf16x2_t); return __builtin_bit_cast(unsigned, b); }
;     __device__ __forceinline__ void operator()(const Acc& acc, const Unit& u, int wr, int wc, int fr, int fq) const {
;     ...
;                 for (int bj = 0; bj < 2; ++bj) { const int col = col0 + bj * HALF; const f32x4 a = acc[ai][bj][m][0] * rs, b = acc[ai][bj][m][1] * rs;
;                     if (col < ZC) *(u32x4*)(ZCp + row * ZC + col) = (u32x4){cvtpk(a[0], a[1]), cvtpk(a[2], a[3]), cvtpk(b[0], b[1]), cvtpk(b[2], b[3])};
;                     else if (col < DIN) { f32x4* p = (f32x4*)(ZRp + row * ZR + (col - ZC)); p[0] = a; p[1] = b; } } }
.LBB0_279:
	s_andn2_saveexec_b64 s[0:1], s[0:1]
	s_cbranch_execz .LBB0_281
	v_cvt_pk_bf16_f32 v100, v100, v101
	v_cvt_pk_bf16_f32 v101, v102, v103
	v_cvt_pk_bf16_f32 v102, v96, v97
	v_cvt_pk_bf16_f32 v103, v98, v99
	v_lshl_add_u64 v[96:97], v[140:141], 1, v[116:117]
	global_store_dwordx4 v[96:97], v[100:103], off offset:256 sc1

; __device__ __forceinline__ unsigned cvtpk(float lo, float hi) { f32x2_t v = {lo, hi}; bf16x2_t b = __builtin_convertvector(v, bf16x2_t); return __builtin_bit_cast(unsigned, b); }
;     __device__ __forceinline__ void operator()(const Acc& acc, const Unit& u, int wr, int wc, int fr, int fq) const {
;     ...
;                 for (int bj = 0; bj < 2; ++bj) { const int col = col0 + bj * HALF; const f32x4 a = acc[ai][bj][m][0] * rs, b = acc[ai][bj][m][1] * rs;
;                     if (col < ZC) *(u32x4*)(ZCp + row * ZC + col) = (u32x4){cvtpk(a[0], a[1]), cvtpk(a[2], a[3]), cvtpk(b[0], b[1]), cvtpk(b[2], b[3])};
;                     else if (col < DIN) { f32x4* p = (f32x4*)(ZRp + row * ZR + (col - ZC)); p[0] = a; p[1] = b; } } }
.LBB0_284:
	s_or_saveexec_b64 s[0:1], s[0:1]
	v_mad_i64_i32 v[100:101], s[16:17], v99, s85, 0
	v_lshl_add_u64 v[100:101], s[14:15], 0, v[100:101]
	s_xor_b64 exec, exec, s[0:1]
	s_cbranch_execz .LBB0_286
	v_cvt_pk_bf16_f32 v92, v92, v93
	v_cvt_pk_bf16_f32 v93, v94, v95
	v_cvt_pk_bf16_f32 v94, v88, v89
	v_cvt_pk_bf16_f32 v95, v90, v91
	v_lshl_add_u64 v[88:89], v[140:141], 1, v[100:101]
	global_store_dwordx4 v[88:89], v[92:95], off sc1

; __device__ __forceinline__ unsigned cvtpk(float lo, float hi) { f32x2_t v = {lo, hi}; bf16x2_t b = __builtin_convertvector(v, bf16x2_t); return __builtin_bit_cast(unsigned, b); }
;     __device__ __forceinline__ void operator()(const Acc& acc, const Unit& u, int wr, int wc, int fr, int fq) const {
;     ...
;                 for (int bj = 0; bj < 2; ++bj) { const int col = col0 + bj * HALF; const f32x4 a = acc[ai][bj][m][0] * rs, b = acc[ai][bj][m][1] * rs;
;                     if (col < ZC) *(u32x4*)(ZCp + row * ZC + col) = (u32x4){cvtpk(a[0], a[1]), cvtpk(a[2], a[3]), cvtpk(b[0], b[1]), cvtpk(b[2], b[3])};
;                     else if (col < DIN) { f32x4* p = (f32x4*)(ZRp + row * ZR + (col - ZC)); p[0] = a; p[1] = b; } } }
.LBB0_290:
	s_andn2_saveexec_b64 s[0:1], s[0:1]
	s_cbranch_execz .LBB0_292
	v_cvt_pk_bf16_f32 v84, v84, v85
	v_cvt_pk_bf16_f32 v85, v86, v87
	v_cvt_pk_bf16_f32 v86, v80, v81
	v_cvt_pk_bf16_f32 v87, v82, v83
	v_lshl_add_u64 v[80:81], v[140:141], 1, v[100:101]
	global_store_dwordx4 v[80:81], v[84:87], off offset:256 sc1

; __device__ __forceinline__ unsigned cvtpk(float lo, float hi) { f32x2_t v = {lo, hi}; bf16x2_t b = __builtin_convertvector(v, bf16x2_t); return __builtin_bit_cast(unsigned, b); }
;     __device__ __forceinline__ void operator()(const Acc& acc, const Unit& u, int wr, int wc, int fr, int fq) const {
;     ...
;                 for (int bj = 0; bj < 2; ++bj) { const int col = col0 + bj * HALF; const f32x4 a = acc[ai][bj][m][0] * rs, b = acc[ai][bj][m][1] * rs;
;                     if (col < ZC) *(u32x4*)(ZCp + row * ZC + col) = (u32x4){cvtpk(a[0], a[1]), cvtpk(a[2], a[3]), cvtpk(b[0], b[1]), cvtpk(b[2], b[3])};
;                     else if (col < DIN) { f32x4* p = (f32x4*)(ZRp + row * ZR + (col - ZC)); p[0] = a; p[1] = b; } } }
.LBB0_295:
	s_or_saveexec_b64 s[0:1], s[0:1]
	v_mad_i64_i32 v[84:85], s[16:17], v83, s85, 0
	v_lshl_add_u64 v[84:85], s[14:15], 0, v[84:85]
	s_xor_b64 exec, exec, s[0:1]
	s_cbranch_execz .LBB0_297
	v_cvt_pk_bf16_f32 v76, v76, v77
	v_cvt_pk_bf16_f32 v77, v78, v79
	v_cvt_pk_bf16_f32 v78, v72, v73
	v_cvt_pk_bf16_f32 v79, v74, v75
	v_lshl_add_u64 v[72:73], v[140:141], 1, v[84:85]
	global_store_dwordx4 v[72:73], v[76:79], off sc1

; __device__ __forceinline__ unsigned cvtpk(float lo, float hi) { f32x2_t v = {lo, hi}; bf16x2_t b = __builtin_convertvector(v, bf16x2_t); return __builtin_bit_cast(unsigned, b); }
;     __device__ __forceinline__ void operator()(const Acc& acc, const Unit& u, int wr, int wc, int fr, int fq) const {
;     ...
;                 for (int bj = 0; bj < 2; ++bj) { const int col = col0 + bj * HALF; const f32x4 a = acc[ai][bj][m][0] * rs, b = acc[ai][bj][m][1] * rs;
;                     if (col < ZC) *(u32x4*)(ZCp + row * ZC + col) = (u32x4){cvtpk(a[0], a[1]), cvtpk(a[2], a[3]), cvtpk(b[0], b[1]), cvtpk(b[2], b[3])};
;                     else if (col < DIN) { f32x4* p = (f32x4*)(ZRp + row * ZR + (col - ZC)); p[0] = a; p[1] = b; } } }
.LBB0_301:
	s_andn2_saveexec_b64 s[0:1], s[0:1]
	s_cbranch_execz .LBB0_303
	v_cvt_pk_bf16_f32 v68, v68, v69
	v_cvt_pk_bf16_f32 v69, v70, v71
	v_cvt_pk_bf16_f32 v70, v64, v65
	v_cvt_pk_bf16_f32 v71, v66, v67
	v_lshl_add_u64 v[64:65], v[140:141], 1, v[84:85]
	global_store_dwordx4 v[64:65], v[68:71], off offset:256 sc1

; __device__ __forceinline__ unsigned cvtpk(float lo, float hi) { f32x2_t v = {lo, hi}; bf16x2_t b = __builtin_convertvector(v, bf16x2_t); return __builtin_bit_cast(unsigned, b); }
;     __device__ __forceinline__ void operator()(const Acc& acc, const Unit& u, int wr, int wc, int fr, int fq) const {
;     ...
;                 for (int bj = 0; bj < 2; ++bj) { const int col = col0 + bj * HALF; const f32x4 a = acc[ai][bj][m][0] * rs, b = acc[ai][bj][m][1] * rs;
;                     if (col < ZC) *(u32x4*)(ZCp + row * ZC + col) = (u32x4){cvtpk(a[0], a[1]), cvtpk(a[2], a[3]), cvtpk(b[0], b[1]), cvtpk(b[2], b[3])};
;                     else if (col < DIN) { f32x4* p = (f32x4*)(ZRp + row * ZR + (col - ZC)); p[0] = a; p[1] = b; } } }
.LBB0_306:
	s_or_saveexec_b64 s[0:1], s[0:1]
	v_mad_i64_i32 v[68:69], s[16:17], v67, s85, 0
	v_lshl_add_u64 v[68:69], s[14:15], 0, v[68:69]
	s_xor_b64 exec, exec, s[0:1]
	s_cbranch_execz .LBB0_308
	v_cvt_pk_bf16_f32 v60, v60, v61
	v_cvt_pk_bf16_f32 v61, v62, v63
	v_cvt_pk_bf16_f32 v62, v56, v57
	v_cvt_pk_bf16_f32 v63, v58, v59
	v_lshl_add_u64 v[56:57], v[140:141], 1, v[68:69]
	global_store_dwordx4 v[56:57], v[60:63], off sc1

; __device__ __forceinline__ unsigned cvtpk(float lo, float hi) { f32x2_t v = {lo, hi}; bf16x2_t b = __builtin_convertvector(v, bf16x2_t); return __builtin_bit_cast(unsigned, b); }
;     __device__ __forceinline__ void operator()(const Acc& acc, const Unit& u, int wr, int wc, int fr, int fq) const {
;     ...
;                 for (int bj = 0; bj < 2; ++bj) { const int col = col0 + bj * HALF; const f32x4 a = acc[ai][bj][m][0] * rs, b = acc[ai][bj][m][1] * rs;
;                     if (col < ZC) *(u32x4*)(ZCp + row * ZC + col) = (u32x4){cvtpk(a[0], a[1]), cvtpk(a[2], a[3]), cvtpk(b[0], b[1]), cvtpk(b[2], b[3])};
;                     else if (col < DIN) { f32x4* p = (f32x4*)(ZRp + row * ZR + (col - ZC)); p[0] = a; p[1] = b; } } }
.LBB0_312:
	s_andn2_saveexec_b64 s[0:1], s[0:1]
	s_cbranch_execz .LBB0_314
	v_cvt_pk_bf16_f32 v52, v52, v53
	v_cvt_pk_bf16_f32 v53, v54, v55
	v_cvt_pk_bf16_f32 v54, v48, v49
	v_cvt_pk_bf16_f32 v55, v50, v51
	v_lshl_add_u64 v[48:49], v[140:141], 1, v[68:69]
	global_store_dwordx4 v[48:49], v[52:55], off offset:256 sc1

; __device__ __forceinline__ unsigned cvtpk(float lo, float hi) { f32x2_t v = {lo, hi}; bf16x2_t b = __builtin_convertvector(v, bf16x2_t); return __builtin_bit_cast(unsigned, b); }
;     __device__ __forceinline__ void operator()(const Acc& acc, const Unit& u, int wr, int wc, int fr, int fq) const {
;     ...
;                 for (int bj = 0; bj < 2; ++bj) { const int col = col0 + bj * HALF; const f32x4 a = acc[ai][bj][m][0] * rs, b = acc[ai][bj][m][1] * rs;
;                     if (col < ZC) *(u32x4*)(ZCp + row * ZC + col) = (u32x4){cvtpk(a[0], a[1]), cvtpk(a[2], a[3]), cvtpk(b[0], b[1]), cvtpk(b[2], b[3])};
;                     else if (col < DIN) { f32x4* p = (f32x4*)(ZRp + row * ZR + (col - ZC)); p[0] = a; p[1] = b; } } }
.LBB0_317:
	s_or_saveexec_b64 s[0:1], s[0:1]
	v_mad_i64_i32 v[52:53], s[16:17], v51, s85, 0
	v_lshl_add_u64 v[52:53], s[14:15], 0, v[52:53]
	s_xor_b64 exec, exec, s[0:1]
	s_cbranch_execz .LBB0_319
	v_cvt_pk_bf16_f32 v44, v44, v45
	v_cvt_pk_bf16_f32 v45, v46, v47
	v_cvt_pk_bf16_f32 v46, v40, v41
	v_cvt_pk_bf16_f32 v47, v42, v43
	v_lshl_add_u64 v[40:41], v[140:141], 1, v[52:53]
	global_store_dwordx4 v[40:41], v[44:47], off sc1

; __device__ __forceinline__ unsigned cvtpk(float lo, float hi) { f32x2_t v = {lo, hi}; bf16x2_t b = __builtin_convertvector(v, bf16x2_t); return __builtin_bit_cast(unsigned, b); }
;     __device__ __forceinline__ void operator()(const Acc& acc, const Unit& u, int wr, int wc, int fr, int fq) const {
;     ...
;                 for (int bj = 0; bj < 2; ++bj) { const int col = col0 + bj * HALF; const f32x4 a = acc[ai][bj][m][0] * rs, b = acc[ai][bj][m][1] * rs;
;                     if (col < ZC) *(u32x4*)(ZCp + row * ZC + col) = (u32x4){cvtpk(a[0], a[1]), cvtpk(a[2], a[3]), cvtpk(b[0], b[1]), cvtpk(b[2], b[3])};
;                     else if (col < DIN) { f32x4* p = (f32x4*)(ZRp + row * ZR + (col - ZC)); p[0] = a; p[1] = b; } } }
.LBB0_323:
	s_andn2_saveexec_b64 s[0:1], s[0:1]
	s_cbranch_execz .LBB0_325
	v_cvt_pk_bf16_f32 v36, v36, v37
	v_cvt_pk_bf16_f32 v37, v38, v39
	v_cvt_pk_bf16_f32 v38, v32, v33
	v_cvt_pk_bf16_f32 v39, v34, v35
	v_lshl_add_u64 v[32:33], v[140:141], 1, v[52:53]
	global_store_dwordx4 v[32:33], v[36:39], off offset:256 sc1

; __device__ __forceinline__ unsigned cvtpk(float lo, float hi) { f32x2_t v = {lo, hi}; bf16x2_t b = __builtin_convertvector(v, bf16x2_t); return __builtin_bit_cast(unsigned, b); }
;     __device__ __forceinline__ void operator()(const Acc& acc, const Unit& u, int wr, int wc, int fr, int fq) const {
;     ...
;                 for (int bj = 0; bj < 2; ++bj) { const int col = col0 + bj * HALF; const f32x4 a = acc[ai][bj][m][0] * rs, b = acc[ai][bj][m][1] * rs;
;                     if (col < ZC) *(u32x4*)(ZCp + row * ZC + col) = (u32x4){cvtpk(a[0], a[1]), cvtpk(a[2], a[3]), cvtpk(b[0], b[1]), cvtpk(b[2], b[3])};
;                     else if (col < DIN) { f32x4* p = (f32x4*)(ZRp + row * ZR + (col - ZC)); p[0] = a; p[1] = b; } } }
.LBB0_328:
	s_or_saveexec_b64 s[0:1], s[0:1]
	v_mad_i64_i32 v[36:37], s[16:17], v35, s85, 0
	v_lshl_add_u64 v[36:37], s[14:15], 0, v[36:37]
	s_xor_b64 exec, exec, s[0:1]
	s_cbranch_execz .LBB0_330
	v_cvt_pk_bf16_f32 v28, v28, v29
	v_cvt_pk_bf16_f32 v29, v30, v31
	v_cvt_pk_bf16_f32 v30, v24, v25
	v_cvt_pk_bf16_f32 v31, v26, v27
	v_lshl_add_u64 v[24:25], v[140:141], 1, v[36:37]
	global_store_dwordx4 v[24:25], v[28:31], off sc1

; __device__ __forceinline__ unsigned cvtpk(float lo, float hi) { f32x2_t v = {lo, hi}; bf16x2_t b = __builtin_convertvector(v, bf16x2_t); return __builtin_bit_cast(unsigned, b); }
;     __device__ __forceinline__ void operator()(const Acc& acc, const Unit& u, int wr, int wc, int fr, int fq) const {
;     ...
;                 for (int bj = 0; bj < 2; ++bj) { const int col = col0 + bj * HALF; const f32x4 a = acc[ai][bj][m][0] * rs, b = acc[ai][bj][m][1] * rs;
;                     if (col < ZC) *(u32x4*)(ZCp + row * ZC + col) = (u32x4){cvtpk(a[0], a[1]), cvtpk(a[2], a[3]), cvtpk(b[0], b[1]), cvtpk(b[2], b[3])};
;                     else if (col < DIN) { f32x4* p = (f32x4*)(ZRp + row * ZR + (col - ZC)); p[0] = a; p[1] = b; } } }
.LBB0_334:
	s_andn2_saveexec_b64 s[0:1], s[0:1]
	s_cbranch_execz .LBB0_336
	v_cvt_pk_bf16_f32 v20, v20, v21
	v_cvt_pk_bf16_f32 v21, v22, v23
	v_cvt_pk_bf16_f32 v22, v16, v17
	v_cvt_pk_bf16_f32 v23, v18, v19
	v_lshl_add_u64 v[16:17], v[140:141], 1, v[36:37]
	global_store_dwordx4 v[16:17], v[20:23], off offset:256 sc1

; __device__ __forceinline__ unsigned cvtpk(float lo, float hi) { f32x2_t v = {lo, hi}; bf16x2_t b = __builtin_convertvector(v, bf16x2_t); return __builtin_bit_cast(unsigned, b); }
;     __device__ __forceinline__ void operator()(const Acc& acc, const Unit& u, int wr, int wc, int fr, int fq) const {
;     ...
;                 for (int bj = 0; bj < 2; ++bj) { const int col = col0 + bj * HALF; const f32x4 a = acc[ai][bj][m][0] * rs, b = acc[ai][bj][m][1] * rs;
;                     if (col < ZC) *(u32x4*)(ZCp + row * ZC + col) = (u32x4){cvtpk(a[0], a[1]), cvtpk(a[2], a[3]), cvtpk(b[0], b[1]), cvtpk(b[2], b[3])};
;                     else if (col < DIN) { f32x4* p = (f32x4*)(ZRp + row * ZR + (col - ZC)); p[0] = a; p[1] = b; } } }
.LBB0_339:
	s_or_saveexec_b64 s[0:1], s[0:1]
	v_mad_i64_i32 v[20:21], s[16:17], v19, s85, 0
	v_lshl_add_u64 v[20:21], s[14:15], 0, v[20:21]
	s_xor_b64 exec, exec, s[0:1]
	s_cbranch_execz .LBB0_341
	v_cvt_pk_bf16_f32 v12, v12, v13
	v_cvt_pk_bf16_f32 v13, v14, v15
	v_cvt_pk_bf16_f32 v14, v8, v9
	v_cvt_pk_bf16_f32 v15, v10, v11
	v_lshl_add_u64 v[8:9], v[140:141], 1, v[20:21]
	global_store_dwordx4 v[8:9], v[12:15], off sc1

; __device__ __forceinline__ unsigned cvtpk(float lo, float hi) { f32x2_t v = {lo, hi}; bf16x2_t b = __builtin_convertvector(v, bf16x2_t); return __builtin_bit_cast(unsigned, b); }
;     __device__ __forceinline__ void operator()(const Acc& acc, const Unit& u, int wr, int wc, int fr, int fq) const {
;     ...
;                 for (int bj = 0; bj < 2; ++bj) { const int col = col0 + bj * HALF; const f32x4 a = acc[ai][bj][m][0] * rs, b = acc[ai][bj][m][1] * rs;
;                     if (col < ZC) *(u32x4*)(ZCp + row * ZC + col) = (u32x4){cvtpk(a[0], a[1]), cvtpk(a[2], a[3]), cvtpk(b[0], b[1]), cvtpk(b[2], b[3])};
;                     else if (col < DIN) { f32x4* p = (f32x4*)(ZRp + row * ZR + (col - ZC)); p[0] = a; p[1] = b; } } }
.LBB0_347:
	v_cvt_pk_bf16_f32 v4, v4, v5
	v_cvt_pk_bf16_f32 v5, v6, v7
	v_cvt_pk_bf16_f32 v6, v0, v1
	v_cvt_pk_bf16_f32 v7, v2, v3
	v_lshl_add_u64 v[0:1], v[140:141], 1, v[20:21]
	global_store_dwordx4 v[0:1], v[4:7], off offset:256 sc1
	s_or_b64 exec, exec, s[0:1]
	s_andn2_b64 vcc, exec, s[42:43]
	s_mov_b64 s[0:1], -1
	s_cbranch_vccnz .LBB0_252

; __device__ __forceinline__ unsigned cvtpk(float lo, float hi) { f32x2_t v = {lo, hi}; bf16x2_t b = __builtin_convertvector(v, bf16x2_t); return __builtin_bit_cast(unsigned, b); }
;     __device__ __forceinline__ void operator()(const Acc& acc, const Unit& u, int wr, int wc, int fr, int fq) const {
;     ...
;             for (int m = 0; m < 4; ++m) { bf16_t* rp = C + (size_t)(row0 + ai * HALF + m * 16) * ldc + col0;
; #pragma unroll
;                 for (int bj = 0; bj < 2; ++bj) { const f32x4 a = acc[ai][bj][m][0], b = acc[ai][bj][m][1];
;                     *(u32x4*)(rp + bj * HALF) = (u32x4){cvtpk(a[0], a[1]), cvtpk(a[2], a[3]), cvtpk(b[0], b[1]), cvtpk(b[2], b[3])}; } }
.LBB0_777:
	v_lshl_add_u32 v148, s54, 8, v138
	v_lshl_or_b32 v142, s57, 8, v140
	v_ashrrev_i32_e32 v143, 31, v142
	v_mov_b64_e32 v[144:145], s[2:3]
	v_cvt_pk_bf16_f32 v68, v68, v69
	v_cvt_pk_bf16_f32 v69, v70, v71
	v_cvt_pk_bf16_f32 v70, v64, v65
	v_add_u32_e32 v64, 0x80, v148
	v_mad_i64_i32 v[146:147], s[16:17], v148, s86, v[144:145]
	v_lshlrev_b64 v[142:143], 1, v[142:143]
	v_cvt_pk_bf16_f32 v108, v108, v109
	v_cvt_pk_bf16_f32 v109, v110, v111
	v_cvt_pk_bf16_f32 v110, v104, v105
	v_or_b32_e32 v104, 16, v148
	v_mad_i64_i32 v[64:65], s[16:17], v64, s86, v[144:145]
	v_cvt_pk_bf16_f32 v44, v44, v45
	v_cvt_pk_bf16_f32 v45, v46, v47
	v_cvt_pk_bf16_f32 v46, v40, v41
	v_add_u32_e32 v40, 0x90, v148
	v_lshl_add_u64 v[146:147], v[146:147], 0, v[142:143]
	v_cvt_pk_bf16_f32 v111, v106, v107
	v_mad_i64_i32 v[104:105], s[16:17], v104, s86, v[144:145]
	v_cvt_pk_bf16_f32 v92, v92, v93
	v_cvt_pk_bf16_f32 v93, v94, v95
	v_cvt_pk_bf16_f32 v94, v88, v89
	v_or_b32_e32 v88, 32, v148
	v_lshl_add_u64 v[64:65], v[64:65], 0, v[142:143]
	v_cvt_pk_bf16_f32 v47, v42, v43
	v_mad_i64_i32 v[40:41], s[16:17], v40, s86, v[144:145]
	v_cvt_pk_bf16_f32 v28, v28, v29
	v_cvt_pk_bf16_f32 v29, v30, v31
	v_cvt_pk_bf16_f32 v30, v24, v25
	v_add_u32_e32 v24, 0xa0, v148
	global_store_dwordx4 v[146:147], v[108:111], off offset:256 sc1
	v_cvt_pk_bf16_f32 v95, v90, v91
	v_mad_i64_i32 v[88:89], s[16:17], v88, s86, v[144:145]
	v_lshl_add_u64 v[108:109], v[104:105], 0, v[142:143]
	v_cvt_pk_bf16_f32 v76, v76, v77
	v_cvt_pk_bf16_f32 v77, v78, v79
	v_cvt_pk_bf16_f32 v78, v72, v73
	v_or_b32_e32 v72, 48, v148
	global_store_dwordx4 v[64:65], v[44:47], off offset:256 sc1
	v_cvt_pk_bf16_f32 v31, v26, v27
	v_mad_i64_i32 v[24:25], s[16:17], v24, s86, v[144:145]
	v_lshl_add_u64 v[44:45], v[40:41], 0, v[142:143]
	v_cvt_pk_bf16_f32 v12, v12, v13
	v_cvt_pk_bf16_f32 v13, v14, v15
	v_cvt_pk_bf16_f32 v14, v8, v9
	v_add_u32_e32 v8, 0xb0, v148
	global_store_dwordx4 v[108:109], v[92:95], off offset:256 sc1
	v_cvt_pk_bf16_f32 v79, v74, v75
	v_mad_i64_i32 v[72:73], s[16:17], v72, s86, v[144:145]
	v_lshl_add_u64 v[92:93], v[88:89], 0, v[142:143]
	global_store_dwordx4 v[44:45], v[28:31], off offset:256 sc1
	v_cvt_pk_bf16_f32 v15, v10, v11
	v_mad_i64_i32 v[8:9], s[16:17], v8, s86, v[144:145]
	v_lshl_add_u64 v[28:29], v[24:25], 0, v[142:143]
	v_cvt_pk_bf16_f32 v124, v124, v125
	v_cvt_pk_bf16_f32 v125, v126, v127
	v_cvt_pk_bf16_f32 v126, v120, v121
	v_cvt_pk_bf16_f32 v127, v122, v123
	v_cvt_pk_bf16_f32 v104, v116, v117
	v_cvt_pk_bf16_f32 v105, v118, v119
	v_cvt_pk_bf16_f32 v106, v112, v113
	v_cvt_pk_bf16_f32 v107, v114, v115
	v_cvt_pk_bf16_f32 v88, v100, v101
	v_cvt_pk_bf16_f32 v89, v102, v103
	v_cvt_pk_bf16_f32 v90, v96, v97
	v_cvt_pk_bf16_f32 v91, v98, v99
	global_store_dwordx4 v[92:93], v[76:79], off offset:256 sc1
	v_cvt_pk_bf16_f32 v74, v80, v81
	v_cvt_pk_bf16_f32 v75, v82, v83
	v_lshl_add_u64 v[76:77], v[72:73], 0, v[142:143]
	v_cvt_pk_bf16_f32 v72, v84, v85
	v_cvt_pk_bf16_f32 v73, v86, v87
	v_cvt_pk_bf16_f32 v71, v66, v67
	v_cvt_pk_bf16_f32 v60, v60, v61
	v_cvt_pk_bf16_f32 v61, v62, v63
	v_cvt_pk_bf16_f32 v62, v56, v57
	v_cvt_pk_bf16_f32 v63, v58, v59
	v_cvt_pk_bf16_f32 v40, v52, v53
	v_cvt_pk_bf16_f32 v41, v54, v55
	v_cvt_pk_bf16_f32 v42, v48, v49
	v_cvt_pk_bf16_f32 v43, v50, v51
	v_cvt_pk_bf16_f32 v24, v36, v37
	v_cvt_pk_bf16_f32 v25, v38, v39
	v_cvt_pk_bf16_f32 v26, v32, v33
	v_cvt_pk_bf16_f32 v27, v34, v35
	global_store_dwordx4 v[28:29], v[12:15], off offset:256 sc1
	v_cvt_pk_bf16_f32 v10, v16, v17
	v_cvt_pk_bf16_f32 v11, v18, v19
	v_lshl_add_u64 v[12:13], v[8:9], 0, v[142:143]
	v_cvt_pk_bf16_f32 v8, v20, v21
	v_cvt_pk_bf16_f32 v9, v22, v23
	v_cvt_pk_bf16_f32 v4, v4, v5
	v_cvt_pk_bf16_f32 v5, v6, v7
	v_cvt_pk_bf16_f32 v6, v0, v1
	v_cvt_pk_bf16_f32 v7, v2, v3
	s_and_b64 vcc, exec, s[42:43]
	s_mov_b64 s[16:17], -1
	global_store_dwordx4 v[146:147], v[124:127], off sc1
	global_store_dwordx4 v[108:109], v[104:107], off sc1
	global_store_dwordx4 v[92:93], v[88:91], off sc1
	global_store_dwordx4 v[76:77], v[72:75], off sc1
	global_store_dwordx4 v[76:77], v[68:71], off offset:256 sc1
	global_store_dwordx4 v[64:65], v[60:63], off sc1
	global_store_dwordx4 v[44:45], v[40:43], off sc1
	global_store_dwordx4 v[28:29], v[24:27], off sc1
	global_store_dwordx4 v[12:13], v[8:11], off sc1
	global_store_dwordx4 v[12:13], v[4:7], off offset:256 sc1
	s_cbranch_vccnz .LBB0_766
	s_andn2_b64 vcc, exec, s[0:1]
	s_cbranch_vccnz .LBB0_765
	s_barrier
	s_branch .LBB0_765

; __device__ __forceinline__ unsigned cvtpk(float lo, float hi) { f32x2_t v = {lo, hi}; bf16x2_t b = __builtin_convertvector(v, bf16x2_t); return __builtin_bit_cast(unsigned, b); }
;     __device__ __forceinline__ void operator()(const Acc& acc, const Unit& u, int wr, int wc, int fr, int fq) const {
;     ...
;             for (int m = 0; m < 4; ++m) { bf16_t* rp = C + (size_t)(row0 + ai * HALF + m * 16) * ldc + col0;
; #pragma unroll
;                 for (int bj = 0; bj < 2; ++bj) { const f32x4 a = acc[ai][bj][m][0], b = acc[ai][bj][m][1];
;                     *(u32x4*)(rp + bj * HALF) = (u32x4){cvtpk(a[0], a[1]), cvtpk(a[2], a[3]), cvtpk(b[0], b[1]), cvtpk(b[2], b[3])}; } }
.LBB0_803:
	v_lshl_add_u32 v138, s66, 8, v134
	v_lshl_or_b32 v140, s67, 8, v136
	v_ashrrev_i32_e32 v139, 31, v138
	v_ashrrev_i32_e32 v141, 31, v140
	v_lshlrev_b64 v[142:143], 11, v[138:139]
	v_lshl_add_u64 v[142:143], s[2:3], 0, v[142:143]
	v_lshlrev_b64 v[140:141], 1, v[140:141]
	v_lshl_add_u64 v[142:143], v[142:143], 0, v[140:141]
	s_mov_b64 s[16:17], 0x40000
	v_cvt_pk_bf16_f32 v68, v68, v69
	v_cvt_pk_bf16_f32 v69, v70, v71
	v_cvt_pk_bf16_f32 v70, v64, v65
	v_lshl_add_u64 v[64:65], v[142:143], 0, s[16:17]
	v_cvt_pk_bf16_f32 v60, v60, v61
	v_cvt_pk_bf16_f32 v61, v62, v63
	v_cvt_pk_bf16_f32 v62, v56, v57
	v_add_co_u32_e32 v56, vcc, s92, v142
	v_cvt_pk_bf16_f32 v44, v44, v45
	v_cvt_pk_bf16_f32 v45, v46, v47
	v_cvt_pk_bf16_f32 v46, v40, v41
	v_cvt_pk_bf16_f32 v47, v42, v43
	s_mov_b64 s[16:17], 0x48000
	v_addc_co_u32_e32 v57, vcc, 0, v143, vcc
	global_store_dwordx4 v[64:65], v[44:47], off offset:256 sc1
	v_cvt_pk_bf16_f32 v108, v108, v109
	v_cvt_pk_bf16_f32 v109, v110, v111
	v_lshl_add_u64 v[44:45], v[142:143], 0, s[16:17]
	s_mov_b32 s16, 0x48000
	v_cvt_pk_bf16_f32 v110, v104, v105
	v_or_b32_e32 v104, 16, v138
	v_add_co_u32_e32 v46, vcc, s16, v142
	v_cvt_pk_bf16_f32 v28, v28, v29
	v_cvt_pk_bf16_f32 v29, v30, v31
	v_cvt_pk_bf16_f32 v30, v24, v25
	v_cvt_pk_bf16_f32 v31, v26, v27
	s_mov_b64 s[16:17], 0x50000
	v_ashrrev_i32_e32 v105, 31, v104
	v_cvt_pk_bf16_f32 v92, v92, v93
	v_cvt_pk_bf16_f32 v93, v94, v95
	v_cvt_pk_bf16_f32 v94, v88, v89
	v_or_b32_e32 v88, 32, v138
	v_addc_co_u32_e32 v47, vcc, 0, v143, vcc
	global_store_dwordx4 v[44:45], v[28:31], off offset:256 sc1
	v_lshlrev_b64 v[104:105], 11, v[104:105]
	v_ashrrev_i32_e32 v89, 31, v88
	v_lshl_add_u64 v[28:29], v[142:143], 0, s[16:17]
	s_mov_b32 s16, 0x50000
	v_cvt_pk_bf16_f32 v76, v76, v77
	v_cvt_pk_bf16_f32 v77, v78, v79
	v_cvt_pk_bf16_f32 v78, v72, v73
	v_or_b32_e32 v72, 48, v138
	v_add_co_u32_e32 v30, vcc, s16, v142
	v_cvt_pk_bf16_f32 v12, v12, v13
	v_cvt_pk_bf16_f32 v13, v14, v15
	v_cvt_pk_bf16_f32 v14, v8, v9
	v_cvt_pk_bf16_f32 v15, v10, v11
	s_mov_b64 s[16:17], 0x58000
	v_cvt_pk_bf16_f32 v111, v106, v107
	v_lshl_add_u64 v[104:105], s[2:3], 0, v[104:105]
	v_lshlrev_b64 v[88:89], 11, v[88:89]
	v_ashrrev_i32_e32 v73, 31, v72
	v_addc_co_u32_e32 v31, vcc, 0, v143, vcc
	global_store_dwordx4 v[28:29], v[12:15], off offset:256 sc1
	global_store_dwordx4 v[142:143], v[108:111], off offset:256 sc1
	v_cvt_pk_bf16_f32 v95, v90, v91
	v_lshl_add_u64 v[12:13], v[142:143], 0, s[16:17]
	s_mov_b32 s16, 0x58000
	v_lshl_add_u64 v[108:109], v[104:105], 0, v[140:141]
	v_lshl_add_u64 v[88:89], s[2:3], 0, v[88:89]
	v_lshlrev_b64 v[72:73], 11, v[72:73]
	v_add_co_u32_e32 v14, vcc, s16, v142
	global_store_dwordx4 v[108:109], v[92:95], off offset:256 sc1
	v_cvt_pk_bf16_f32 v79, v74, v75
	v_lshl_add_u64 v[72:73], s[2:3], 0, v[72:73]
	v_lshl_add_u64 v[92:93], v[88:89], 0, v[140:141]
	v_addc_co_u32_e32 v15, vcc, 0, v143, vcc
	v_readlane_b32 s76, v254, 58
	v_readlane_b32 s78, v254, 60
	v_readlane_b32 s80, v254, 62
	v_cvt_pk_bf16_f32 v124, v124, v125
	v_cvt_pk_bf16_f32 v125, v126, v127
	v_cvt_pk_bf16_f32 v126, v120, v121
	v_cvt_pk_bf16_f32 v127, v122, v123
	v_cvt_pk_bf16_f32 v104, v116, v117
	v_cvt_pk_bf16_f32 v105, v118, v119
	v_cvt_pk_bf16_f32 v106, v112, v113
	v_cvt_pk_bf16_f32 v107, v114, v115
	v_cvt_pk_bf16_f32 v88, v100, v101
	v_cvt_pk_bf16_f32 v89, v102, v103
	v_cvt_pk_bf16_f32 v90, v96, v97
	v_cvt_pk_bf16_f32 v91, v98, v99
	global_store_dwordx4 v[92:93], v[76:79], off offset:256 sc1
	v_cvt_pk_bf16_f32 v74, v80, v81
	v_cvt_pk_bf16_f32 v75, v82, v83
	v_lshl_add_u64 v[76:77], v[72:73], 0, v[140:141]
	v_cvt_pk_bf16_f32 v72, v84, v85
	v_cvt_pk_bf16_f32 v73, v86, v87
	v_cvt_pk_bf16_f32 v71, v66, v67
	v_cvt_pk_bf16_f32 v63, v58, v59
	v_cvt_pk_bf16_f32 v40, v52, v53
	v_cvt_pk_bf16_f32 v41, v54, v55
	v_cvt_pk_bf16_f32 v42, v48, v49
	v_cvt_pk_bf16_f32 v43, v50, v51
	v_cvt_pk_bf16_f32 v24, v36, v37
	v_cvt_pk_bf16_f32 v25, v38, v39
	v_cvt_pk_bf16_f32 v26, v32, v33
	v_cvt_pk_bf16_f32 v27, v34, v35
	v_cvt_pk_bf16_f32 v8, v20, v21
	v_cvt_pk_bf16_f32 v9, v22, v23
	v_cvt_pk_bf16_f32 v10, v16, v17
	v_cvt_pk_bf16_f32 v11, v18, v19
	v_cvt_pk_bf16_f32 v4, v4, v5
	v_cvt_pk_bf16_f32 v5, v6, v7
	v_cvt_pk_bf16_f32 v6, v0, v1
	v_cvt_pk_bf16_f32 v7, v2, v3
	s_and_b64 vcc, exec, s[42:43]
	s_mov_b64 s[16:17], -1
	v_readlane_b32 s77, v254, 59
	v_readlane_b32 s79, v254, 61
	v_readlane_b32 s81, v254, 63
	global_store_dwordx4 v[142:143], v[124:127], off sc1
	global_store_dwordx4 v[108:109], v[104:107], off sc1
	global_store_dwordx4 v[92:93], v[88:91], off sc1
	global_store_dwordx4 v[76:77], v[72:75], off sc1
	global_store_dwordx4 v[76:77], v[68:71], off offset:256 sc1
	global_store_dwordx4 v[56:57], v[60:63], off sc1
	global_store_dwordx4 v[46:47], v[40:43], off sc1
	global_store_dwordx4 v[30:31], v[24:27], off sc1
	global_store_dwordx4 v[14:15], v[8:11], off sc1
	global_store_dwordx4 v[12:13], v[4:7], off offset:256 sc1
	s_cbranch_vccnz .LBB0_790
	s_andn2_b64 vcc, exec, s[0:1]
	s_cbranch_vccnz .LBB0_789
	s_barrier
	s_branch .LBB0_789

; __device__ __forceinline__ void finalize_qkv(const bf16_t* QP, const bf16_t* KVP, const float* ZRp, const float* RQ, const float* RKV, const float* ROPE,
;                                              const float* qn, const float* kn, bf16_t* Qb, bf16_t* Kimg, bf16_t* Vimg, int gw, int NGW, int lane) {
;     ...
;     for (int it = gw; it < (SEQ / 16) * 2; it += NGW) {
;         const int g = it >> 1, hh = it & 1; const int tok0 = g * 16; const float rl = RKV[tok0 + (lane & 15)];
; #pragma unroll
;         for (int h4 = 0; h4 < 4; ++h4) { const int hd = hh * 4 + h4;
; #pragma unroll
;             for (int hi = 0; hi < 2; ++hi) { float e[8];
; #pragma unroll
;                 for (int j = 0; j < 8; ++j) { const int t = 8 * (j >> 2) + 4 * hi + (j & 3); e[j] = bf2f(KVP[(size_t)(tok0 + t) * 1024 + 512 + hd * 64 + lane]) * __shfl(rl, t); }
.LBB0_868:
	s_waitcnt vmcnt(0)
	s_lshr_b32 s0, s89, 1
	s_and_b32 s1, s89, 1
	s_lshl_b32 s2, s0, 4
	v_or_b32_e32 v2, s2, v36
	v_mov_b32_e32 v3, 0
	v_lshl_add_u64 v[2:3], v[2:3], 2, s[14:15]
	global_load_dword v35, v[2:3], off
	s_lshl_b32 s3, s2, 11
	s_lshl_b32 s16, s1, 9
	s_add_u32 s3, s3, s16
	s_add_u32 s20, s18, s3
	s_addc_u32 s21, s19, 0
	global_load_ushort v64, v160, s[20:21] offset:1024
	global_load_ushort v80, v160, s[20:21] offset:1152
	global_load_ushort v96, v160, s[20:21] offset:1280
	global_load_ushort v112, v160, s[20:21] offset:1408
	s_add_u32 s20, s20, 0x800
	s_addc_u32 s21, s21, 0
	global_load_ushort v65, v160, s[20:21] offset:1024
	global_load_ushort v81, v160, s[20:21] offset:1152
	global_load_ushort v97, v160, s[20:21] offset:1280
	global_load_ushort v113, v160, s[20:21] offset:1408
	s_add_u32 s20, s20, 0x800
	s_addc_u32 s21, s21, 0
	global_load_ushort v66, v160, s[20:21] offset:1024
	global_load_ushort v82, v160, s[20:21] offset:1152
	global_load_ushort v98, v160, s[20:21] offset:1280
	global_load_ushort v114, v160, s[20:21] offset:1408
	s_add_u32 s20, s20, 0x800
	s_addc_u32 s21, s21, 0
	global_load_ushort v67, v160, s[20:21] offset:1024
	global_load_ushort v83, v160, s[20:21] offset:1152
	global_load_ushort v99, v160, s[20:21] offset:1280
	global_load_ushort v115, v160, s[20:21] offset:1408
	s_add_u32 s20, s20, 0x800
	s_addc_u32 s21, s21, 0
	global_load_ushort v68, v160, s[20:21] offset:1024
	global_load_ushort v84, v160, s[20:21] offset:1152
	global_load_ushort v100, v160, s[20:21] offset:1280
	global_load_ushort v116, v160, s[20:21] offset:1408
	s_add_u32 s20, s20, 0x800
	s_addc_u32 s21, s21, 0
	global_load_ushort v69, v160, s[20:21] offset:1024
	global_load_ushort v85, v160, s[20:21] offset:1152
	global_load_ushort v101, v160, s[20:21] offset:1280
	global_load_ushort v117, v160, s[20:21] offset:1408
	s_add_u32 s20, s20, 0x800
	s_addc_u32 s21, s21, 0
	global_load_ushort v70, v160, s[20:21] offset:1024
	global_load_ushort v86, v160, s[20:21] offset:1152
	global_load_ushort v102, v160, s[20:21] offset:1280
	global_load_ushort v118, v160, s[20:21] offset:1408
	s_add_u32 s20, s20, 0x800
	s_addc_u32 s21, s21, 0
	global_load_ushort v71, v160, s[20:21] offset:1024
	global_load_ushort v87, v160, s[20:21] offset:1152
	global_load_ushort v103, v160, s[20:21] offset:1280
	global_load_ushort v119, v160, s[20:21] offset:1408
	s_add_u32 s20, s20, 0x800
	s_addc_u32 s21, s21, 0
	global_load_ushort v72, v160, s[20:21] offset:1024
	global_load_ushort v88, v160, s[20:21] offset:1152
	global_load_ushort v104, v160, s[20:21] offset:1280
	global_load_ushort v120, v160, s[20:21] offset:1408
	s_add_u32 s20, s20, 0x800
	s_addc_u32 s21, s21, 0
	global_load_ushort v73, v160, s[20:21] offset:1024
	global_load_ushort v89, v160, s[20:21] offset:1152
	global_load_ushort v105, v160, s[20:21] offset:1280
	global_load_ushort v121, v160, s[20:21] offset:1408
	s_add_u32 s20, s20, 0x800
	s_addc_u32 s21, s21, 0
	global_load_ushort v74, v160, s[20:21] offset:1024
	global_load_ushort v90, v160, s[20:21] offset:1152
	global_load_ushort v106, v160, s[20:21] offset:1280
	global_load_ushort v122, v160, s[20:21] offset:1408
	s_add_u32 s20, s20, 0x800
	s_addc_u32 s21, s21, 0
	global_load_ushort v75, v160, s[20:21] offset:1024
	global_load_ushort v91, v160, s[20:21] offset:1152
	global_load_ushort v107, v160, s[20:21] offset:1280
	global_load_ushort v123, v160, s[20:21] offset:1408
	s_add_u32 s20, s20, 0x800
	s_addc_u32 s21, s21, 0
	global_load_ushort v76, v160, s[20:21] offset:1024
	global_load_ushort v92, v160, s[20:21] offset:1152
	global_load_ushort v108, v160, s[20:21] offset:1280
	global_load_ushort v124, v160, s[20:21] offset:1408
	s_add_u32 s20, s20, 0x800
	s_addc_u32 s21, s21, 0
	global_load_ushort v77, v160, s[20:21] offset:1024
	global_load_ushort v93, v160, s[20:21] offset:1152
	global_load_ushort v109, v160, s[20:21] offset:1280
	global_load_ushort v125, v160, s[20:21] offset:1408
	s_add_u32 s20, s20, 0x800
	s_addc_u32 s21, s21, 0
	global_load_ushort v78, v160, s[20:21] offset:1024
	global_load_ushort v94, v160, s[20:21] offset:1152
	global_load_ushort v110, v160, s[20:21] offset:1280
	global_load_ushort v126, v160, s[20:21] offset:1408
	s_add_u32 s20, s20, 0x800
	s_addc_u32 s21, s21, 0
	global_load_ushort v79, v160, s[20:21] offset:1024
	global_load_ushort v95, v160, s[20:21] offset:1152
	global_load_ushort v111, v160, s[20:21] offset:1280
	global_load_ushort v127, v160, s[20:21] offset:1408
	s_lshl_b32 s16, s1, 23
	s_lshr_b32 s17, s0, 2
	s_lshl_b32 s17, s17, 13
	s_add_u32 s16, s16, s17
	s_and_b32 s17, s0, 3
	s_lshl_b32 s17, s17, 11
	s_add_u32 s16, s16, s17
	s_add_u32 s24, s28, s16
	s_addc_u32 s25, s29, 0
	v_lshlrev_b32_e32 v14, 1, v37
	s_waitcnt vmcnt(0)
; __device__ __forceinline__ unsigned cvtpk(float lo, float hi) { f32x2_t v = {lo, hi}; bf16x2_t b = __builtin_convertvector(v, bf16x2_t); return __builtin_bit_cast(unsigned, b); }
; __device__ __forceinline__ void finalize_qkv(const bf16_t* QP, const bf16_t* KVP, const float* ZRp, const float* RQ, const float* RKV, const float* ROPE,
;                                              const float* qn, const float* kn, bf16_t* Qb, bf16_t* Kimg, bf16_t* Vimg, int gw, int NGW, int lane) {
;     ...
;         const int g = it >> 1, hh = it & 1; const int tok0 = g * 16; const float rl = RKV[tok0 + (lane & 15)];
; #pragma unroll
;         for (int h4 = 0; h4 < 4; ++h4) { const int hd = hh * 4 + h4;
; #pragma unroll
;             for (int hi = 0; hi < 2; ++hi) { float e[8];
; #pragma unroll
;                 for (int j = 0; j < 8; ++j) { const int t = 8 * (j >> 2) + 4 * hi + (j & 3); e[j] = bf2f(KVP[(size_t)(tok0 + t) * 1024 + 512 + hd * 64 + lane]) * __shfl(rl, t); }
;                 *(u32x4*)(Vimg + ((size_t)hd * 256 + (g >> 2)) * 4096 + ((size_t)((g & 3) * 2 + hi) * 64 + lane) * 8) = (u32x4){cvtpk(e[0], e[1]), cvtpk(e[2], e[3]), cvtpk(e[4], e[5]), cvtpk(e[6], e[7])}; } }
;     }
	v_readlane_b32 s40, v35, 0
	v_readlane_b32 s41, v35, 1
	v_readlane_b32 s42, v35, 2
	v_readlane_b32 s43, v35, 3
	v_readlane_b32 s44, v35, 4
	v_readlane_b32 s45, v35, 5
	v_readlane_b32 s46, v35, 6
	v_readlane_b32 s47, v35, 7
	v_readlane_b32 s48, v35, 8
	v_readlane_b32 s49, v35, 9
	v_readlane_b32 s50, v35, 10
	v_readlane_b32 s51, v35, 11
	v_readlane_b32 s52, v35, 12
	v_readlane_b32 s53, v35, 13
	v_readlane_b32 s54, v35, 14
	v_readlane_b32 s55, v35, 15
	s_nop 1
	v_lshlrev_b32_e32 v2, 16, v64
	v_lshlrev_b32_e32 v3, 16, v65
	v_lshlrev_b32_e32 v4, 16, v66
	v_lshlrev_b32_e32 v5, 16, v67
	v_lshlrev_b32_e32 v6, 16, v72
	v_lshlrev_b32_e32 v7, 16, v73
	v_lshlrev_b32_e32 v8, 16, v74
	v_lshlrev_b32_e32 v9, 16, v75
	v_mul_f32_e32 v2, s40, v2
	v_mul_f32_e32 v3, s41, v3
	v_mul_f32_e32 v4, s42, v4
	v_mul_f32_e32 v5, s43, v5
	v_mul_f32_e32 v6, s48, v6
	v_mul_f32_e32 v7, s49, v7
	v_mul_f32_e32 v8, s50, v8
	v_mul_f32_e32 v9, s51, v9
	v_cvt_pk_bf16_f32 v10, v2, v3
	v_cvt_pk_bf16_f32 v11, v4, v5
	v_cvt_pk_bf16_f32 v12, v6, v7
	v_cvt_pk_bf16_f32 v13, v8, v9
	global_store_dwordx4 v14, v[10:13], s[24:25] sc1
	v_lshlrev_b32_e32 v2, 16, v68
	v_lshlrev_b32_e32 v3, 16, v69
	v_lshlrev_b32_e32 v4, 16, v70
	v_lshlrev_b32_e32 v5, 16, v71
	v_lshlrev_b32_e32 v6, 16, v76
	v_lshlrev_b32_e32 v7, 16, v77
	v_lshlrev_b32_e32 v8, 16, v78
	v_lshlrev_b32_e32 v9, 16, v79
	v_mul_f32_e32 v2, s44, v2
	v_mul_f32_e32 v3, s45, v3
	v_mul_f32_e32 v4, s46, v4
	v_mul_f32_e32 v5, s47, v5
	v_mul_f32_e32 v6, s52, v6
	v_mul_f32_e32 v7, s53, v7
	v_mul_f32_e32 v8, s54, v8
	v_mul_f32_e32 v9, s55, v9
	v_cvt_pk_bf16_f32 v10, v2, v3
	v_cvt_pk_bf16_f32 v11, v4, v5
	v_cvt_pk_bf16_f32 v12, v6, v7
	v_cvt_pk_bf16_f32 v13, v8, v9
	global_store_dwordx4 v14, v[10:13], s[24:25] offset:1024 sc1
	s_add_u32 s24, s24, 0x200000
	s_addc_u32 s25, s25, 0
	v_lshlrev_b32_e32 v2, 16, v80
	v_lshlrev_b32_e32 v3, 16, v81
	v_lshlrev_b32_e32 v4, 16, v82
	v_lshlrev_b32_e32 v5, 16, v83
	v_lshlrev_b32_e32 v6, 16, v88
	v_lshlrev_b32_e32 v7, 16, v89
	v_lshlrev_b32_e32 v8, 16, v90
	v_lshlrev_b32_e32 v9, 16, v91
	v_mul_f32_e32 v2, s40, v2
	v_mul_f32_e32 v3, s41, v3
	v_mul_f32_e32 v4, s42, v4
	v_mul_f32_e32 v5, s43, v5
	v_mul_f32_e32 v6, s48, v6
	v_mul_f32_e32 v7, s49, v7
	v_mul_f32_e32 v8, s50, v8
	v_mul_f32_e32 v9, s51, v9
	v_cvt_pk_bf16_f32 v10, v2, v3
	v_cvt_pk_bf16_f32 v11, v4, v5
	v_cvt_pk_bf16_f32 v12, v6, v7
	v_cvt_pk_bf16_f32 v13, v8, v9
	global_store_dwordx4 v14, v[10:13], s[24:25] sc1
	v_lshlrev_b32_e32 v2, 16, v84
	v_lshlrev_b32_e32 v3, 16, v85
	v_lshlrev_b32_e32 v4, 16, v86
	v_lshlrev_b32_e32 v5, 16, v87
	v_lshlrev_b32_e32 v6, 16, v92
	v_lshlrev_b32_e32 v7, 16, v93
	v_lshlrev_b32_e32 v8, 16, v94
	v_lshlrev_b32_e32 v9, 16, v95
	v_mul_f32_e32 v2, s44, v2
	v_mul_f32_e32 v3, s45, v3
	v_mul_f32_e32 v4, s46, v4
	v_mul_f32_e32 v5, s47, v5
	v_mul_f32_e32 v6, s52, v6
	v_mul_f32_e32 v7, s53, v7
	v_mul_f32_e32 v8, s54, v8
	v_mul_f32_e32 v9, s55, v9
	v_cvt_pk_bf16_f32 v10, v2, v3
	v_cvt_pk_bf16_f32 v11, v4, v5
	v_cvt_pk_bf16_f32 v12, v6, v7
	v_cvt_pk_bf16_f32 v13, v8, v9
	global_store_dwordx4 v14, v[10:13], s[24:25] offset:1024 sc1
	s_add_u32 s24, s24, 0x200000
	s_addc_u32 s25, s25, 0
	v_lshlrev_b32_e32 v2, 16, v96
	v_lshlrev_b32_e32 v3, 16, v97
	v_lshlrev_b32_e32 v4, 16, v98
	v_lshlrev_b32_e32 v5, 16, v99
	v_lshlrev_b32_e32 v6, 16, v104
	v_lshlrev_b32_e32 v7, 16, v105
	v_lshlrev_b32_e32 v8, 16, v106
	v_lshlrev_b32_e32 v9, 16, v107
	v_mul_f32_e32 v2, s40, v2
	v_mul_f32_e32 v3, s41, v3
	v_mul_f32_e32 v4, s42, v4
	v_mul_f32_e32 v5, s43, v5
	v_mul_f32_e32 v6, s48, v6
	v_mul_f32_e32 v7, s49, v7
	v_mul_f32_e32 v8, s50, v8
	v_mul_f32_e32 v9, s51, v9
	v_cvt_pk_bf16_f32 v10, v2, v3
	v_cvt_pk_bf16_f32 v11, v4, v5
	v_cvt_pk_bf16_f32 v12, v6, v7
	v_cvt_pk_bf16_f32 v13, v8, v9
	global_store_dwordx4 v14, v[10:13], s[24:25] sc1
	v_lshlrev_b32_e32 v2, 16, v100
	v_lshlrev_b32_e32 v3, 16, v101
	v_lshlrev_b32_e32 v4, 16, v102
	v_lshlrev_b32_e32 v5, 16, v103
	v_lshlrev_b32_e32 v6, 16, v108
	v_lshlrev_b32_e32 v7, 16, v109
	v_lshlrev_b32_e32 v8, 16, v110
	v_lshlrev_b32_e32 v9, 16, v111
	v_mul_f32_e32 v2, s44, v2
	v_mul_f32_e32 v3, s45, v3
	v_mul_f32_e32 v4, s46, v4
	v_mul_f32_e32 v5, s47, v5
	v_mul_f32_e32 v6, s52, v6
	v_mul_f32_e32 v7, s53, v7
	v_mul_f32_e32 v8, s54, v8
	v_mul_f32_e32 v9, s55, v9
	v_cvt_pk_bf16_f32 v10, v2, v3
	v_cvt_pk_bf16_f32 v11, v4, v5
	v_cvt_pk_bf16_f32 v12, v6, v7
	v_cvt_pk_bf16_f32 v13, v8, v9
	global_store_dwordx4 v14, v[10:13], s[24:25] offset:1024 sc1
	s_add_u32 s24, s24, 0x200000
	s_addc_u32 s25, s25, 0
	v_lshlrev_b32_e32 v2, 16, v112
	v_lshlrev_b32_e32 v3, 16, v113
	v_lshlrev_b32_e32 v4, 16, v114
	v_lshlrev_b32_e32 v5, 16, v115
	v_lshlrev_b32_e32 v6, 16, v120
	v_lshlrev_b32_e32 v7, 16, v121
	v_lshlrev_b32_e32 v8, 16, v122
	v_lshlrev_b32_e32 v9, 16, v123
	v_mul_f32_e32 v2, s40, v2
	v_mul_f32_e32 v3, s41, v3
	v_mul_f32_e32 v4, s42, v4
	v_mul_f32_e32 v5, s43, v5
	v_mul_f32_e32 v6, s48, v6
	v_mul_f32_e32 v7, s49, v7
	v_mul_f32_e32 v8, s50, v8
	v_mul_f32_e32 v9, s51, v9
	v_cvt_pk_bf16_f32 v10, v2, v3
	v_cvt_pk_bf16_f32 v11, v4, v5
	v_cvt_pk_bf16_f32 v12, v6, v7
	v_cvt_pk_bf16_f32 v13, v8, v9
	global_store_dwordx4 v14, v[10:13], s[24:25] sc1
	v_lshlrev_b32_e32 v2, 16, v116
	v_lshlrev_b32_e32 v3, 16, v117
	v_lshlrev_b32_e32 v4, 16, v118
	v_lshlrev_b32_e32 v5, 16, v119
	v_lshlrev_b32_e32 v6, 16, v124
	v_lshlrev_b32_e32 v7, 16, v125
	v_lshlrev_b32_e32 v8, 16, v126
	v_lshlrev_b32_e32 v9, 16, v127
	v_mul_f32_e32 v2, s44, v2
	v_mul_f32_e32 v3, s45, v3
	v_mul_f32_e32 v4, s46, v4
	v_mul_f32_e32 v5, s47, v5
	v_mul_f32_e32 v6, s52, v6
	v_mul_f32_e32 v7, s53, v7
	v_mul_f32_e32 v8, s54, v8
	v_mul_f32_e32 v9, s55, v9
	v_cvt_pk_bf16_f32 v10, v2, v3
	v_cvt_pk_bf16_f32 v11, v4, v5
	v_cvt_pk_bf16_f32 v12, v6, v7
	v_cvt_pk_bf16_f32 v13, v8, v9
	global_store_dwordx4 v14, v[10:13], s[24:25] offset:1024 sc1
	s_add_i32 s89, s89, s88
	s_cmpk_lt_i32 s89, 0x800
	s_cbranch_scc1 .LBB0_868

; __device__ __forceinline__ unsigned cvtpk(float lo, float hi) { f32x2_t v = {lo, hi}; bf16x2_t b = __builtin_convertvector(v, bf16x2_t); return __builtin_bit_cast(unsigned, b); }
;     __device__ __forceinline__ void operator()(const Acc& acc, const Unit& u, int wr, int wc, int fr, int fq) const {
;     ...
;             for (int m = 0; m < 4; ++m) { const size_t row = (size_t)(row0 + ai * HALF + m * 16);
; #pragma unroll
;                 for (int bj = 0; bj < 2; ++bj) { const int col = col0 + bj * HALF; const f32x4 s0 = *(const f32x4*)(scale + col), s1 = *(const f32x4*)(scale + col + 4);
;                     const f32x4 a = acc[ai][bj][m][0] * s0, b = acc[ai][bj][m][1] * s1;
;                     *(u32x4*)(AB + row * DM + PW + col) = (u32x4){cvtpk(a[0], a[1]), cvtpk(a[2], a[3]), cvtpk(b[0], b[1]), cvtpk(b[2], b[3])}; } }
.LBB0_889:
	v_lshl_or_b32 v140, s61, 8, v144
	v_ashrrev_i32_e32 v141, 31, v140
	v_lshl_add_u64 v[138:139], v[140:141], 2, s[14:15]
	v_mov_b64_e32 v[218:219], v[138:139]
	global_load_dwordx4 v[166:169], v[218:219], off
	global_load_dwordx4 v[170:173], v[218:219], off offset:16
	global_load_dwordx4 v[174:177], v[218:219], off offset:512
	global_load_dwordx4 v[178:181], v[218:219], off offset:528
	v_lshl_add_u32 v154, s44, 8, v142
	v_ashrrev_i32_e32 v155, 31, v154
	v_lshlrev_b64 v[156:157], 11, v[154:155]
	v_lshlrev_b64 v[158:159], 1, v[140:141]
	v_lshl_add_u64 v[140:141], s[2:3], 0, v[156:157]
	v_lshl_add_u64 v[140:141], v[140:141], 0, v[158:159]
	s_mov_b64 s[16:17], 0x40000
	s_andn2_b64 vcc, exec, s[42:43]
	s_waitcnt vmcnt(0)
	v_pk_mul_f32 v[126:127], v[126:127], v[168:169]
	v_pk_mul_f32 v[124:125], v[124:125], v[166:167]
	v_pk_mul_f32 v[146:147], v[122:123], v[172:173]
	v_pk_mul_f32 v[122:123], v[120:121], v[170:171]
	v_cvt_pk_bf16_f32 v120, v124, v125
	v_cvt_pk_bf16_f32 v121, v126, v127
	v_cvt_pk_bf16_f32 v122, v122, v123
	v_cvt_pk_bf16_f32 v123, v146, v147
	global_store_dwordx4 v[140:141], v[120:123], off offset:1024 sc1
	s_nop 1
	v_pk_mul_f32 v[118:119], v[118:119], v[176:177]
	v_pk_mul_f32 v[116:117], v[116:117], v[174:175]
	v_pk_mul_f32 v[120:121], v[114:115], v[180:181]
	v_pk_mul_f32 v[114:115], v[112:113], v[178:179]
	v_cvt_pk_bf16_f32 v112, v116, v117
	v_cvt_pk_bf16_f32 v113, v118, v119
	v_cvt_pk_bf16_f32 v114, v114, v115
	v_cvt_pk_bf16_f32 v115, v120, v121
	global_store_dwordx4 v[140:141], v[112:115], off offset:1280 sc1
	v_or_b32_e32 v120, 16, v154
	v_ashrrev_i32_e32 v121, 31, v120
	v_lshlrev_b64 v[120:121], 11, v[120:121]
	v_lshl_add_u64 v[120:121], s[2:3], 0, v[120:121]
	v_lshl_add_u64 v[120:121], v[120:121], 0, v[158:159]
	v_pk_mul_f32 v[110:111], v[110:111], v[168:169]
	v_pk_mul_f32 v[108:109], v[108:109], v[166:167]
	v_pk_mul_f32 v[112:113], v[106:107], v[172:173]
	v_pk_mul_f32 v[106:107], v[104:105], v[170:171]
	v_cvt_pk_bf16_f32 v104, v108, v109
	v_cvt_pk_bf16_f32 v105, v110, v111
	v_cvt_pk_bf16_f32 v106, v106, v107
	v_cvt_pk_bf16_f32 v107, v112, v113
	global_store_dwordx4 v[120:121], v[104:107], off offset:1024 sc1
	s_nop 1
	v_pk_mul_f32 v[102:103], v[102:103], v[176:177]
	v_pk_mul_f32 v[100:101], v[100:101], v[174:175]
	v_pk_mul_f32 v[104:105], v[98:99], v[180:181]
	v_pk_mul_f32 v[98:99], v[96:97], v[178:179]
	v_cvt_pk_bf16_f32 v96, v100, v101
	v_cvt_pk_bf16_f32 v97, v102, v103
	v_cvt_pk_bf16_f32 v98, v98, v99
	v_cvt_pk_bf16_f32 v99, v104, v105
	global_store_dwordx4 v[120:121], v[96:99], off offset:1280 sc1
	v_or_b32_e32 v104, 32, v154
	v_ashrrev_i32_e32 v105, 31, v104
	v_lshlrev_b64 v[104:105], 11, v[104:105]
	v_lshl_add_u64 v[104:105], s[2:3], 0, v[104:105]
	v_lshl_add_u64 v[104:105], v[104:105], 0, v[158:159]
	v_pk_mul_f32 v[94:95], v[94:95], v[168:169]
	v_pk_mul_f32 v[92:93], v[92:93], v[166:167]
	v_pk_mul_f32 v[96:97], v[90:91], v[172:173]
	v_pk_mul_f32 v[90:91], v[88:89], v[170:171]
	v_cvt_pk_bf16_f32 v88, v92, v93
	v_cvt_pk_bf16_f32 v89, v94, v95
	v_cvt_pk_bf16_f32 v90, v90, v91
	v_cvt_pk_bf16_f32 v91, v96, v97
	global_store_dwordx4 v[104:105], v[88:91], off offset:1024 sc1
	s_nop 1
	v_pk_mul_f32 v[86:87], v[86:87], v[176:177]
	v_pk_mul_f32 v[84:85], v[84:85], v[174:175]
	v_pk_mul_f32 v[88:89], v[82:83], v[180:181]
	v_pk_mul_f32 v[82:83], v[80:81], v[178:179]
	v_cvt_pk_bf16_f32 v80, v84, v85
	v_cvt_pk_bf16_f32 v81, v86, v87
	v_cvt_pk_bf16_f32 v82, v82, v83
	v_cvt_pk_bf16_f32 v83, v88, v89
	global_store_dwordx4 v[104:105], v[80:83], off offset:1280 sc1
	v_or_b32_e32 v88, 48, v154
	v_ashrrev_i32_e32 v89, 31, v88
	v_lshlrev_b64 v[88:89], 11, v[88:89]
	v_lshl_add_u64 v[88:89], s[2:3], 0, v[88:89]
	v_lshl_add_u64 v[88:89], v[88:89], 0, v[158:159]
	v_pk_mul_f32 v[78:79], v[78:79], v[168:169]
	v_pk_mul_f32 v[76:77], v[76:77], v[166:167]
	v_pk_mul_f32 v[80:81], v[74:75], v[172:173]
	v_pk_mul_f32 v[74:75], v[72:73], v[170:171]
	v_cvt_pk_bf16_f32 v72, v76, v77
; __device__ __forceinline__ unsigned cvtpk(float lo, float hi) { f32x2_t v = {lo, hi}; bf16x2_t b = __builtin_convertvector(v, bf16x2_t); return __builtin_bit_cast(unsigned, b); }
;     __device__ __forceinline__ void operator()(const Acc& acc, const Unit& u, int wr, int wc, int fr, int fq) const {
;     ...
;             for (int m = 0; m < 4; ++m) { const size_t row = (size_t)(row0 + ai * HALF + m * 16);
; #pragma unroll
;                 for (int bj = 0; bj < 2; ++bj) { const int col = col0 + bj * HALF; const f32x4 s0 = *(const f32x4*)(scale + col), s1 = *(const f32x4*)(scale + col + 4);
;                     const f32x4 a = acc[ai][bj][m][0] * s0, b = acc[ai][bj][m][1] * s1;
;                     *(u32x4*)(AB + row * DM + PW + col) = (u32x4){cvtpk(a[0], a[1]), cvtpk(a[2], a[3]), cvtpk(b[0], b[1]), cvtpk(b[2], b[3])}; } }
	v_cvt_pk_bf16_f32 v73, v78, v79
	v_cvt_pk_bf16_f32 v74, v74, v75
	v_cvt_pk_bf16_f32 v75, v80, v81
	global_store_dwordx4 v[88:89], v[72:75], off offset:1024 sc1
	s_nop 1
	v_pk_mul_f32 v[70:71], v[70:71], v[176:177]
	v_pk_mul_f32 v[68:69], v[68:69], v[174:175]
	v_pk_mul_f32 v[72:73], v[66:67], v[180:181]
	v_pk_mul_f32 v[66:67], v[64:65], v[178:179]
	v_cvt_pk_bf16_f32 v64, v68, v69
	v_cvt_pk_bf16_f32 v65, v70, v71
	v_cvt_pk_bf16_f32 v66, v66, v67
	v_cvt_pk_bf16_f32 v67, v72, v73
	global_store_dwordx4 v[88:89], v[64:67], off offset:1280 sc1
	v_lshl_add_u64 v[72:73], v[140:141], 0, s[16:17]
	s_mov_b64 s[16:17], 0x48000
	v_pk_mul_f32 v[62:63], v[62:63], v[168:169]
	v_pk_mul_f32 v[60:61], v[60:61], v[166:167]
	v_pk_mul_f32 v[64:65], v[58:59], v[172:173]
	v_pk_mul_f32 v[58:59], v[56:57], v[170:171]
	v_cvt_pk_bf16_f32 v56, v60, v61
	v_cvt_pk_bf16_f32 v57, v62, v63
	v_cvt_pk_bf16_f32 v58, v58, v59
	v_cvt_pk_bf16_f32 v59, v64, v65
	global_store_dwordx4 v[72:73], v[56:59], off offset:1024 sc1
	s_nop 1
	v_pk_mul_f32 v[54:55], v[54:55], v[176:177]
	v_pk_mul_f32 v[52:53], v[52:53], v[174:175]
	v_pk_mul_f32 v[56:57], v[50:51], v[180:181]
	v_pk_mul_f32 v[50:51], v[48:49], v[178:179]
	v_cvt_pk_bf16_f32 v48, v52, v53
	v_cvt_pk_bf16_f32 v49, v54, v55
	v_cvt_pk_bf16_f32 v50, v50, v51
	v_cvt_pk_bf16_f32 v51, v56, v57
	global_store_dwordx4 v[72:73], v[48:51], off offset:1280 sc1
	v_lshl_add_u64 v[56:57], v[140:141], 0, s[16:17]
	s_mov_b64 s[16:17], 0x50000
	v_pk_mul_f32 v[46:47], v[46:47], v[168:169]
	v_pk_mul_f32 v[44:45], v[44:45], v[166:167]
	v_pk_mul_f32 v[48:49], v[42:43], v[172:173]
	v_pk_mul_f32 v[42:43], v[40:41], v[170:171]
	v_cvt_pk_bf16_f32 v40, v44, v45
	v_cvt_pk_bf16_f32 v41, v46, v47
	v_cvt_pk_bf16_f32 v42, v42, v43
	v_cvt_pk_bf16_f32 v43, v48, v49
	global_store_dwordx4 v[56:57], v[40:43], off offset:1024 sc1
	s_nop 1
	v_pk_mul_f32 v[38:39], v[38:39], v[176:177]
	v_pk_mul_f32 v[36:37], v[36:37], v[174:175]
	v_pk_mul_f32 v[40:41], v[34:35], v[180:181]
	v_pk_mul_f32 v[34:35], v[32:33], v[178:179]
	v_cvt_pk_bf16_f32 v32, v36, v37
	v_cvt_pk_bf16_f32 v33, v38, v39
	v_cvt_pk_bf16_f32 v34, v34, v35
	v_cvt_pk_bf16_f32 v35, v40, v41
	global_store_dwordx4 v[56:57], v[32:35], off offset:1280 sc1
	v_lshl_add_u64 v[40:41], v[140:141], 0, s[16:17]
	s_mov_b64 s[16:17], 0x58000
	v_pk_mul_f32 v[30:31], v[30:31], v[168:169]
	v_pk_mul_f32 v[28:29], v[28:29], v[166:167]
	v_pk_mul_f32 v[32:33], v[26:27], v[172:173]
	v_pk_mul_f32 v[26:27], v[24:25], v[170:171]
	v_cvt_pk_bf16_f32 v24, v28, v29
	v_cvt_pk_bf16_f32 v25, v30, v31
	v_cvt_pk_bf16_f32 v26, v26, v27
	v_cvt_pk_bf16_f32 v27, v32, v33
	global_store_dwordx4 v[40:41], v[24:27], off offset:1024 sc1
	s_nop 1
	v_pk_mul_f32 v[22:23], v[22:23], v[176:177]
	v_pk_mul_f32 v[20:21], v[20:21], v[174:175]
	v_pk_mul_f32 v[24:25], v[18:19], v[180:181]
	v_pk_mul_f32 v[18:19], v[16:17], v[178:179]
	v_cvt_pk_bf16_f32 v16, v20, v21
	v_cvt_pk_bf16_f32 v17, v22, v23
	v_cvt_pk_bf16_f32 v18, v18, v19
	v_cvt_pk_bf16_f32 v19, v24, v25
	global_store_dwordx4 v[40:41], v[16:19], off offset:1280 sc1
	v_lshl_add_u64 v[24:25], v[140:141], 0, s[16:17]
	s_mov_b64 s[16:17], -1
	v_pk_mul_f32 v[14:15], v[14:15], v[168:169]
	v_pk_mul_f32 v[12:13], v[12:13], v[166:167]
	v_pk_mul_f32 v[16:17], v[10:11], v[172:173]
	v_pk_mul_f32 v[10:11], v[8:9], v[170:171]
	v_cvt_pk_bf16_f32 v8, v12, v13
	v_cvt_pk_bf16_f32 v9, v14, v15
	v_cvt_pk_bf16_f32 v10, v10, v11
	v_cvt_pk_bf16_f32 v11, v16, v17
	global_store_dwordx4 v[24:25], v[8:11], off offset:1024 sc1
	s_nop 1
	v_pk_mul_f32 v[6:7], v[6:7], v[176:177]
	v_pk_mul_f32 v[4:5], v[4:5], v[174:175]
	v_pk_mul_f32 v[8:9], v[2:3], v[180:181]
	v_pk_mul_f32 v[2:3], v[0:1], v[178:179]
	v_cvt_pk_bf16_f32 v0, v4, v5
	v_cvt_pk_bf16_f32 v1, v6, v7
	v_cvt_pk_bf16_f32 v2, v2, v3
	v_cvt_pk_bf16_f32 v3, v8, v9
	global_store_dwordx4 v[24:25], v[0:3], off offset:1280 sc1
	s_cbranch_vccnz .LBB0_878
	s_andn2_b64 vcc, exec, s[0:1]
	s_cbranch_vccnz .LBB0_877
	s_barrier
	s_branch .LBB0_877

; __device__ __forceinline__ unsigned cvtpk(float lo, float hi) { f32x2_t v = {lo, hi}; bf16x2_t b = __builtin_convertvector(v, bf16x2_t); return __builtin_bit_cast(unsigned, b); }
;     __device__ __forceinline__ void operator()(const Acc& acc, const Unit& u, int wr, int wc, int fr, int fq) const {
;         const int row0 = u.pm * BM + wr * 64 + fr, col0 = u.pn * BM + wc * 32 + 8 * fq;
; #pragma unroll
;         for (int ai = 0; ai < 2; ++ai)
; #pragma unroll
;             for (int m = 0; m < 4; ++m) { const int row = row0 + ai * HALF + m * 16; float* rp = X + (size_t)row * DM + col0; const float* ip = Xin + (size_t)row * DM + col0; bf16_t* bp = XB + (size_t)row * DM + col0; float part = 0.f;
; #pragma unroll
;                 for (int bj = 0; bj < 2; ++bj) { f32x4* p = (f32x4*)(rp + bj * HALF); const f32x4* q = (const f32x4*)(ip + bj * HALF); f32x4 a = q[0], b = q[1]; a += acc[ai][bj][m][0] * scale; b += acc[ai][bj][m][1] * scale; p[0] = a; p[1] = b;
;                     *(u32x4*)(bp + bj * HALF) = (u32x4){cvtpk(a[0], a[1]), cvtpk(a[2], a[3]), cvtpk(b[0], b[1]), cvtpk(b[2], b[3])};
;                     part += (a[0] * a[0] + a[1] * a[1]) + (a[2] * a[2] + a[3] * a[3]) + (b[0] * b[0] + b[1] * b[1]) + (b[2] * b[2] + b[3] * b[3]); }
;                 part += __shfl_xor(part, 16); part += __shfl_xor(part, 32);
;                 if (fq == 0) __hip_atomic_fetch_add(SS + row, (u64)(part * SSF), __ATOMIC_RELAXED, __HIP_MEMORY_SCOPE_AGENT); }
.LBB0_1060:
	v_lshl_add_u32 v140, s46, 8, v142
	v_ashrrev_i32_e32 v141, 31, v140
	v_lshl_or_b32 v138, s52, 8, v144
	v_lshlrev_b64 v[146:147], 12, v[140:141]
	v_ashrrev_i32_e32 v139, 31, v138
	v_lshl_add_u64 v[146:147], s[48:49], 0, v[146:147]
	v_lshl_add_u64 v[158:159], v[138:139], 2, v[146:147]
	global_load_dwordx4 v[146:149], v[158:159], off
	global_load_dwordx4 v[150:153], v[158:159], off offset:16
	v_lshlrev_b64 v[154:155], 11, v[140:141]
	v_lshl_add_u64 v[154:155], s[14:15], 0, v[154:155]
	v_lshl_add_u64 v[162:163], v[138:139], 1, v[154:155]
	s_waitcnt vmcnt(0)
	v_pk_add_f32 v[126:127], v[126:127], v[148:149]
	v_pk_add_f32 v[124:125], v[124:125], v[146:147]
	v_pk_add_f32 v[148:149], v[122:123], v[152:153]
	v_pk_add_f32 v[146:147], v[120:121], v[150:151]
	v_cvt_pk_bf16_f32 v120, v124, v125
	v_cvt_pk_bf16_f32 v121, v126, v127
	v_cvt_pk_bf16_f32 v122, v146, v147
	v_cvt_pk_bf16_f32 v123, v148, v149
	global_store_dwordx4 v[158:159], v[124:127], off
	global_store_dwordx4 v[158:159], v[146:149], off offset:16
	global_store_dwordx4 v[162:163], v[120:123], off sc1
	global_load_dwordx4 v[150:153], v[158:159], off offset:512
	global_load_dwordx4 v[154:157], v[158:159], off offset:528
	v_and_b32_e32 v121, 64, v229
	v_xor_b32_e32 v120, 16, v229
	v_add_u32_e32 v121, 64, v121
	v_xor_b32_e32 v122, 32, v229
	v_cmp_lt_i32_e32 vcc, v120, v121
	v_mul_f32_e32 v123, v127, v127
	v_fmac_f32_e32 v123, v126, v126
	v_cndmask_b32_e32 v120, v229, v120, vcc
	v_cmp_lt_i32_e32 vcc, v122, v121
	v_lshlrev_b32_e32 v121, 2, v120
	v_mul_f32_e32 v127, v149, v149
	v_cndmask_b32_e32 v122, v229, v122, vcc
	v_lshlrev_b32_e32 v120, 2, v122
	v_mul_f32_e32 v122, v125, v125
	v_mul_f32_e32 v125, v147, v147
	v_fmac_f32_e32 v122, v124, v124
	v_fmac_f32_e32 v125, v146, v146
	v_add_f32_e32 v122, v122, v123
	v_fmac_f32_e32 v127, v148, v148
	v_add_f32_e32 v122, v125, v122
	v_add_f32_e32 v126, v127, v122
	s_waitcnt vmcnt(1)
	v_pk_add_f32 v[118:119], v[118:119], v[152:153]
	v_pk_add_f32 v[116:117], v[116:117], v[150:151]
	s_waitcnt vmcnt(0)
	v_pk_add_f32 v[122:123], v[112:113], v[154:155]
	v_mul_f32_e32 v112, v117, v117
	v_mul_f32_e32 v113, v119, v119
	v_pk_add_f32 v[124:125], v[114:115], v[156:157]
	v_mul_f32_e32 v114, v123, v123
	v_fmac_f32_e32 v112, v116, v116
	v_fmac_f32_e32 v113, v118, v118
	v_mul_f32_e32 v115, v125, v125
	v_fmac_f32_e32 v114, v122, v122
	v_add_f32_e32 v112, v112, v113
	v_add_f32_e32 v112, v114, v112
	v_fmac_f32_e32 v115, v124, v124
	v_add_f32_e32 v112, v115, v112
	v_add_f32_e32 v112, v126, v112
	ds_bpermute_b32 v113, v121, v112
	global_store_dwordx4 v[158:159], v[116:119], off offset:512
	global_store_dwordx4 v[158:159], v[122:125], off offset:528
	s_waitcnt lgkmcnt(0)
	v_add_f32_e32 v114, v112, v113
	ds_bpermute_b32 v115, v120, v114
	v_cvt_pk_bf16_f32 v116, v116, v117
	v_cvt_pk_bf16_f32 v117, v118, v119
	v_cvt_pk_bf16_f32 v118, v122, v123
	v_cvt_pk_bf16_f32 v119, v124, v125
	v_lshl_add_u64 v[112:113], v[140:141], 3, s[18:19]
	global_store_dwordx4 v[162:163], v[116:119], off offset:256 sc1
	s_and_saveexec_b64 s[16:17], s[42:43]
	s_cbranch_execz .LBB0_1062
	s_waitcnt lgkmcnt(0)
	v_add_f32_e32 v114, v114, v115
	v_mul_f32_e32 v114, 0x4b800000, v114
	v_trunc_f32_e32 v114, v114
	v_mul_f32_e32 v115, 0x2f800000, v114
	v_floor_f32_e32 v115, v115
	v_fmac_f32_e32 v114, 0xcf800000, v115
	v_cvt_u32_f32_e32 v114, v114
	v_cvt_u32_f32_e32 v115, v115
	global_atomic_add_x2 v[112:113], v[114:115], off
.LBB0_1062:
	s_or_b64 exec, exec, s[16:17]
	v_or_b32_e32 v118, 16, v140
	v_ashrrev_i32_e32 v119, 31, v118
	s_waitcnt lgkmcnt(0)
	v_lshlrev_b64 v[114:115], 12, v[118:119]
	v_lshl_add_u64 v[114:115], s[48:49], 0, v[114:115]
	v_lshl_add_u64 v[126:127], v[138:139], 2, v[114:115]
	global_load_dwordx4 v[114:117], v[126:127], off
	global_load_dwordx4 v[122:125], v[126:127], off offset:16
	v_lshlrev_b64 v[118:119], 11, v[118:119]
	v_lshl_add_u64 v[118:119], s[14:15], 0, v[118:119]
	v_lshl_add_u64 v[118:119], v[138:139], 1, v[118:119]
	s_waitcnt vmcnt(1)
	v_pk_add_f32 v[110:111], v[110:111], v[116:117]
	v_pk_add_f32 v[108:109], v[108:109], v[114:115]
	s_waitcnt vmcnt(0)
	v_pk_add_f32 v[106:107], v[106:107], v[124:125]
	v_pk_add_f32 v[104:105], v[104:105], v[122:123]
	v_cvt_pk_bf16_f32 v114, v108, v109
	v_cvt_pk_bf16_f32 v115, v110, v111
	v_cvt_pk_bf16_f32 v116, v104, v105
	v_cvt_pk_bf16_f32 v117, v106, v107
	global_store_dwordx4 v[126:127], v[108:111], off
	global_store_dwordx4 v[126:127], v[104:107], off offset:16
	global_store_dwordx4 v[118:119], v[114:117], off sc1
	global_load_dwordx4 v[114:117], v[126:127], off offset:512
	s_nop 0
	global_load_dwordx4 v[122:125], v[126:127], off offset:528
	v_mul_f32_e32 v109, v109, v109
	v_mul_f32_e32 v111, v111, v111
	v_mul_f32_e32 v105, v105, v105
	v_fmac_f32_e32 v109, v108, v108
	v_fmac_f32_e32 v111, v110, v110
	v_mul_f32_e32 v107, v107, v107
	v_fmac_f32_e32 v105, v104, v104
	v_add_f32_e32 v104, v109, v111
	v_fmac_f32_e32 v107, v106, v106
	v_add_f32_e32 v104, v105, v104
	v_add_f32_e32 v108, v107, v104
	s_waitcnt vmcnt(1)
	v_pk_add_f32 v[102:103], v[102:103], v[116:117]
	v_pk_add_f32 v[100:101], v[100:101], v[114:115]
	s_waitcnt vmcnt(0)
	v_pk_add_f32 v[104:105], v[96:97], v[122:123]
	v_mul_f32_e32 v96, v101, v101
	v_mul_f32_e32 v97, v103, v103
	v_pk_add_f32 v[106:107], v[98:99], v[124:125]
	v_mul_f32_e32 v98, v105, v105
	v_fmac_f32_e32 v96, v100, v100
	v_fmac_f32_e32 v97, v102, v102
	v_mul_f32_e32 v99, v107, v107
	v_fmac_f32_e32 v98, v104, v104
	v_add_f32_e32 v96, v96, v97
	v_add_f32_e32 v96, v98, v96
	v_fmac_f32_e32 v99, v106, v106
	v_add_f32_e32 v96, v99, v96
	v_add_f32_e32 v96, v108, v96
	ds_bpermute_b32 v97, v121, v96
	global_store_dwordx4 v[126:127], v[100:103], off offset:512
	global_store_dwordx4 v[126:127], v[104:107], off offset:528
	v_cvt_pk_bf16_f32 v98, v100, v101
	v_cvt_pk_bf16_f32 v99, v102, v103
	v_cvt_pk_bf16_f32 v100, v104, v105
	s_waitcnt lgkmcnt(0)
	v_add_f32_e32 v96, v96, v97
	ds_bpermute_b32 v97, v120, v96
	v_cvt_pk_bf16_f32 v101, v106, v107
	global_store_dwordx4 v[118:119], v[98:101], off offset:256 sc1
	s_and_saveexec_b64 s[16:17], s[42:43]
	s_cbranch_execz .LBB0_1064
	s_waitcnt lgkmcnt(0)
	v_add_f32_e32 v96, v96, v97
	v_mul_f32_e32 v96, 0x4b800000, v96
	v_trunc_f32_e32 v96, v96
	v_mul_f32_e32 v97, 0x2f800000, v96
	v_floor_f32_e32 v97, v97
	v_fmac_f32_e32 v96, 0xcf800000, v97
	v_cvt_u32_f32_e32 v96, v96
	v_cvt_u32_f32_e32 v97, v97
	global_atomic_add_x2 v[112:113], v[96:97], off offset:128
; __device__ __forceinline__ unsigned cvtpk(float lo, float hi) { f32x2_t v = {lo, hi}; bf16x2_t b = __builtin_convertvector(v, bf16x2_t); return __builtin_bit_cast(unsigned, b); }
;     __device__ __forceinline__ void operator()(const Acc& acc, const Unit& u, int wr, int wc, int fr, int fq) const {
;         const int row0 = u.pm * BM + wr * 64 + fr, col0 = u.pn * BM + wc * 32 + 8 * fq;
; #pragma unroll
;         for (int ai = 0; ai < 2; ++ai)
; #pragma unroll
;             for (int m = 0; m < 4; ++m) { const int row = row0 + ai * HALF + m * 16; float* rp = X + (size_t)row * DM + col0; const float* ip = Xin + (size_t)row * DM + col0; bf16_t* bp = XB + (size_t)row * DM + col0; float part = 0.f;
; #pragma unroll
;                 for (int bj = 0; bj < 2; ++bj) { f32x4* p = (f32x4*)(rp + bj * HALF); const f32x4* q = (const f32x4*)(ip + bj * HALF); f32x4 a = q[0], b = q[1]; a += acc[ai][bj][m][0] * scale; b += acc[ai][bj][m][1] * scale; p[0] = a; p[1] = b;
;                     *(u32x4*)(bp + bj * HALF) = (u32x4){cvtpk(a[0], a[1]), cvtpk(a[2], a[3]), cvtpk(b[0], b[1]), cvtpk(b[2], b[3])};
;                     part += (a[0] * a[0] + a[1] * a[1]) + (a[2] * a[2] + a[3] * a[3]) + (b[0] * b[0] + b[1] * b[1]) + (b[2] * b[2] + b[3] * b[3]); }
;                 part += __shfl_xor(part, 16); part += __shfl_xor(part, 32);
;                 if (fq == 0) __hip_atomic_fetch_add(SS + row, (u64)(part * SSF), __ATOMIC_RELAXED, __HIP_MEMORY_SCOPE_AGENT); }
.LBB0_1064:
	s_or_b64 exec, exec, s[16:17]
	v_or_b32_e32 v104, 32, v140
	v_ashrrev_i32_e32 v105, 31, v104
	s_waitcnt lgkmcnt(0)
	v_lshlrev_b64 v[96:97], 12, v[104:105]
	v_lshl_add_u64 v[96:97], s[48:49], 0, v[96:97]
	v_lshl_add_u64 v[106:107], v[138:139], 2, v[96:97]
	global_load_dwordx4 v[96:99], v[106:107], off
	global_load_dwordx4 v[100:103], v[106:107], off offset:16
	v_lshlrev_b64 v[104:105], 11, v[104:105]
	v_lshl_add_u64 v[104:105], s[14:15], 0, v[104:105]
	v_lshl_add_u64 v[104:105], v[138:139], 1, v[104:105]
	s_waitcnt vmcnt(1)
	v_pk_add_f32 v[94:95], v[94:95], v[98:99]
	v_pk_add_f32 v[92:93], v[92:93], v[96:97]
	s_waitcnt vmcnt(0)
	v_pk_add_f32 v[90:91], v[90:91], v[102:103]
	v_pk_add_f32 v[88:89], v[88:89], v[100:101]
	v_cvt_pk_bf16_f32 v96, v92, v93
	v_cvt_pk_bf16_f32 v97, v94, v95
	v_cvt_pk_bf16_f32 v98, v88, v89
	v_cvt_pk_bf16_f32 v99, v90, v91
	global_store_dwordx4 v[106:107], v[92:95], off
	global_store_dwordx4 v[106:107], v[88:91], off offset:16
	global_store_dwordx4 v[104:105], v[96:99], off sc1
	global_load_dwordx4 v[96:99], v[106:107], off offset:512
	s_nop 0
	global_load_dwordx4 v[100:103], v[106:107], off offset:528
	v_mul_f32_e32 v93, v93, v93
	v_mul_f32_e32 v95, v95, v95
	v_mul_f32_e32 v89, v89, v89
	v_fmac_f32_e32 v93, v92, v92
	v_fmac_f32_e32 v95, v94, v94
	v_mul_f32_e32 v91, v91, v91
	v_fmac_f32_e32 v89, v88, v88
	v_add_f32_e32 v88, v93, v95
	v_fmac_f32_e32 v91, v90, v90
	v_add_f32_e32 v88, v89, v88
	v_add_f32_e32 v92, v91, v88
	s_waitcnt vmcnt(1)
	v_pk_add_f32 v[86:87], v[86:87], v[98:99]
	v_pk_add_f32 v[84:85], v[84:85], v[96:97]
	s_waitcnt vmcnt(0)
	v_pk_add_f32 v[88:89], v[80:81], v[100:101]
	v_mul_f32_e32 v80, v85, v85
	v_mul_f32_e32 v81, v87, v87
	v_pk_add_f32 v[90:91], v[82:83], v[102:103]
	v_mul_f32_e32 v82, v89, v89
	v_fmac_f32_e32 v80, v84, v84
	v_fmac_f32_e32 v81, v86, v86
	v_mul_f32_e32 v83, v91, v91
	v_fmac_f32_e32 v82, v88, v88
	v_add_f32_e32 v80, v80, v81
	v_add_f32_e32 v80, v82, v80
	v_fmac_f32_e32 v83, v90, v90
	v_add_f32_e32 v80, v83, v80
	v_add_f32_e32 v80, v92, v80
	ds_bpermute_b32 v81, v121, v80
	global_store_dwordx4 v[106:107], v[84:87], off offset:512
	global_store_dwordx4 v[106:107], v[88:91], off offset:528
	v_cvt_pk_bf16_f32 v82, v84, v85
	v_cvt_pk_bf16_f32 v83, v86, v87
	v_cvt_pk_bf16_f32 v84, v88, v89
	s_waitcnt lgkmcnt(0)
	v_add_f32_e32 v80, v80, v81
	ds_bpermute_b32 v81, v120, v80
	v_cvt_pk_bf16_f32 v85, v90, v91
	global_store_dwordx4 v[104:105], v[82:85], off offset:256 sc1
	s_and_saveexec_b64 s[16:17], s[42:43]
	s_cbranch_execz .LBB0_1066
	s_waitcnt lgkmcnt(0)
	v_add_f32_e32 v80, v80, v81
	v_mul_f32_e32 v80, 0x4b800000, v80
	v_trunc_f32_e32 v80, v80
	v_mul_f32_e32 v81, 0x2f800000, v80
	v_floor_f32_e32 v81, v81
	v_fmac_f32_e32 v80, 0xcf800000, v81
	v_cvt_u32_f32_e32 v80, v80
	v_cvt_u32_f32_e32 v81, v81
	global_atomic_add_x2 v[112:113], v[80:81], off offset:256
.LBB0_1066:
	s_or_b64 exec, exec, s[16:17]
	v_or_b32_e32 v88, 48, v140
	v_ashrrev_i32_e32 v89, 31, v88
	s_waitcnt lgkmcnt(0)
	v_lshlrev_b64 v[80:81], 12, v[88:89]
	v_lshl_add_u64 v[80:81], s[48:49], 0, v[80:81]
	v_lshl_add_u64 v[90:91], v[138:139], 2, v[80:81]
	global_load_dwordx4 v[80:83], v[90:91], off
	global_load_dwordx4 v[84:87], v[90:91], off offset:16
	v_lshlrev_b64 v[88:89], 11, v[88:89]
	v_lshl_add_u64 v[88:89], s[14:15], 0, v[88:89]
	v_lshl_add_u64 v[88:89], v[138:139], 1, v[88:89]
	s_waitcnt vmcnt(1)
	v_pk_add_f32 v[78:79], v[78:79], v[82:83]
	v_pk_add_f32 v[76:77], v[76:77], v[80:81]
	s_waitcnt vmcnt(0)
	v_pk_add_f32 v[74:75], v[74:75], v[86:87]
	v_pk_add_f32 v[72:73], v[72:73], v[84:85]
	v_cvt_pk_bf16_f32 v80, v76, v77
	v_cvt_pk_bf16_f32 v81, v78, v79
	v_cvt_pk_bf16_f32 v82, v72, v73
	v_cvt_pk_bf16_f32 v83, v74, v75
	global_store_dwordx4 v[90:91], v[76:79], off
	global_store_dwordx4 v[90:91], v[72:75], off offset:16
	global_store_dwordx4 v[88:89], v[80:83], off sc1
	global_load_dwordx4 v[80:83], v[90:91], off offset:512
	s_nop 0
	global_load_dwordx4 v[84:87], v[90:91], off offset:528
	v_mul_f32_e32 v77, v77, v77
	v_mul_f32_e32 v79, v79, v79
	v_mul_f32_e32 v73, v73, v73
	v_fmac_f32_e32 v77, v76, v76
	v_fmac_f32_e32 v79, v78, v78
	v_mul_f32_e32 v75, v75, v75
	v_fmac_f32_e32 v73, v72, v72
	v_add_f32_e32 v72, v77, v79
	v_fmac_f32_e32 v75, v74, v74
	v_add_f32_e32 v72, v73, v72
	v_add_f32_e32 v76, v75, v72
	s_waitcnt vmcnt(1)
	v_pk_add_f32 v[70:71], v[70:71], v[82:83]
	v_pk_add_f32 v[68:69], v[68:69], v[80:81]
	s_waitcnt vmcnt(0)
	v_pk_add_f32 v[72:73], v[64:65], v[84:85]
	v_mul_f32_e32 v64, v69, v69
	v_mul_f32_e32 v65, v71, v71
	v_pk_add_f32 v[74:75], v[66:67], v[86:87]
	v_mul_f32_e32 v66, v73, v73
	v_fmac_f32_e32 v64, v68, v68
	v_fmac_f32_e32 v65, v70, v70
	v_mul_f32_e32 v67, v75, v75
	v_fmac_f32_e32 v66, v72, v72
	v_add_f32_e32 v64, v64, v65
	v_add_f32_e32 v64, v66, v64
	v_fmac_f32_e32 v67, v74, v74
	v_add_f32_e32 v64, v67, v64
	v_add_f32_e32 v64, v76, v64
	ds_bpermute_b32 v65, v121, v64
	global_store_dwordx4 v[90:91], v[68:71], off offset:512
	global_store_dwordx4 v[90:91], v[72:75], off offset:528
	v_cvt_pk_bf16_f32 v66, v68, v69
	v_cvt_pk_bf16_f32 v67, v70, v71
	v_cvt_pk_bf16_f32 v68, v72, v73
	s_waitcnt lgkmcnt(0)
	v_add_f32_e32 v64, v64, v65
	ds_bpermute_b32 v65, v120, v64
	v_cvt_pk_bf16_f32 v69, v74, v75
	global_store_dwordx4 v[88:89], v[66:69], off offset:256 sc1
	s_and_saveexec_b64 s[16:17], s[42:43]
	s_cbranch_execz .LBB0_1068
	s_waitcnt lgkmcnt(0)
	v_add_f32_e32 v64, v64, v65
	v_mul_f32_e32 v64, 0x4b800000, v64
	v_trunc_f32_e32 v64, v64
	v_mul_f32_e32 v65, 0x2f800000, v64
	v_floor_f32_e32 v65, v65
	v_fmac_f32_e32 v64, 0xcf800000, v65
	v_cvt_u32_f32_e32 v64, v64
	v_cvt_u32_f32_e32 v65, v65
	global_atomic_add_x2 v[112:113], v[64:65], off offset:384
; __device__ __forceinline__ unsigned cvtpk(float lo, float hi) { f32x2_t v = {lo, hi}; bf16x2_t b = __builtin_convertvector(v, bf16x2_t); return __builtin_bit_cast(unsigned, b); }
;     __device__ __forceinline__ void operator()(const Acc& acc, const Unit& u, int wr, int wc, int fr, int fq) const {
;     ...
;             for (int m = 0; m < 4; ++m) { const int row = row0 + ai * HALF + m * 16; float* rp = X + (size_t)row * DM + col0; const float* ip = Xin + (size_t)row * DM + col0; bf16_t* bp = XB + (size_t)row * DM + col0; float part = 0.f;
; #pragma unroll
;                 for (int bj = 0; bj < 2; ++bj) { f32x4* p = (f32x4*)(rp + bj * HALF); const f32x4* q = (const f32x4*)(ip + bj * HALF); f32x4 a = q[0], b = q[1]; a += acc[ai][bj][m][0] * scale; b += acc[ai][bj][m][1] * scale; p[0] = a; p[1] = b;
;                     *(u32x4*)(bp + bj * HALF) = (u32x4){cvtpk(a[0], a[1]), cvtpk(a[2], a[3]), cvtpk(b[0], b[1]), cvtpk(b[2], b[3])};
;                     part += (a[0] * a[0] + a[1] * a[1]) + (a[2] * a[2] + a[3] * a[3]) + (b[0] * b[0] + b[1] * b[1]) + (b[2] * b[2] + b[3] * b[3]); }
;                 part += __shfl_xor(part, 16); part += __shfl_xor(part, 32);
;                 if (fq == 0) __hip_atomic_fetch_add(SS + row, (u64)(part * SSF), __ATOMIC_RELAXED, __HIP_MEMORY_SCOPE_AGENT); }
.LBB0_1068:
	s_or_b64 exec, exec, s[16:17]
	v_add_u32_e32 v72, 0x80, v140
	v_ashrrev_i32_e32 v73, 31, v72
	s_waitcnt lgkmcnt(0)
	v_lshlrev_b64 v[64:65], 12, v[72:73]
	v_lshl_add_u64 v[64:65], s[48:49], 0, v[64:65]
	v_lshl_add_u64 v[74:75], v[138:139], 2, v[64:65]
	global_load_dwordx4 v[64:67], v[74:75], off
	global_load_dwordx4 v[68:71], v[74:75], off offset:16
	v_lshlrev_b64 v[72:73], 11, v[72:73]
	v_lshl_add_u64 v[72:73], s[14:15], 0, v[72:73]
	v_lshl_add_u64 v[72:73], v[138:139], 1, v[72:73]
	s_waitcnt vmcnt(1)
	v_pk_add_f32 v[62:63], v[62:63], v[66:67]
	v_pk_add_f32 v[60:61], v[60:61], v[64:65]
	s_waitcnt vmcnt(0)
	v_pk_add_f32 v[58:59], v[58:59], v[70:71]
	v_pk_add_f32 v[56:57], v[56:57], v[68:69]
	v_cvt_pk_bf16_f32 v64, v60, v61
	v_cvt_pk_bf16_f32 v65, v62, v63
	v_cvt_pk_bf16_f32 v66, v56, v57
	v_cvt_pk_bf16_f32 v67, v58, v59
	global_store_dwordx4 v[74:75], v[60:63], off
	global_store_dwordx4 v[74:75], v[56:59], off offset:16
	global_store_dwordx4 v[72:73], v[64:67], off sc1
	global_load_dwordx4 v[64:67], v[74:75], off offset:512
	s_nop 0
	global_load_dwordx4 v[68:71], v[74:75], off offset:528
	v_mul_f32_e32 v61, v61, v61
	v_mul_f32_e32 v63, v63, v63
	v_mul_f32_e32 v57, v57, v57
	v_fmac_f32_e32 v61, v60, v60
	v_fmac_f32_e32 v63, v62, v62
	v_mul_f32_e32 v59, v59, v59
	v_fmac_f32_e32 v57, v56, v56
	v_add_f32_e32 v56, v61, v63
	v_fmac_f32_e32 v59, v58, v58
	v_add_f32_e32 v56, v57, v56
	v_add_f32_e32 v60, v59, v56
	s_waitcnt vmcnt(1)
	v_pk_add_f32 v[54:55], v[54:55], v[66:67]
	v_pk_add_f32 v[52:53], v[52:53], v[64:65]
	s_waitcnt vmcnt(0)
	v_pk_add_f32 v[56:57], v[48:49], v[68:69]
	v_mul_f32_e32 v48, v53, v53
	v_mul_f32_e32 v49, v55, v55
	v_pk_add_f32 v[58:59], v[50:51], v[70:71]
	v_mul_f32_e32 v50, v57, v57
	v_fmac_f32_e32 v48, v52, v52
	v_fmac_f32_e32 v49, v54, v54
	v_mul_f32_e32 v51, v59, v59
	v_fmac_f32_e32 v50, v56, v56
	v_add_f32_e32 v48, v48, v49
	v_add_f32_e32 v48, v50, v48
	v_fmac_f32_e32 v51, v58, v58
	v_add_f32_e32 v48, v51, v48
	v_add_f32_e32 v48, v60, v48
	ds_bpermute_b32 v49, v121, v48
	global_store_dwordx4 v[74:75], v[52:55], off offset:512
	global_store_dwordx4 v[74:75], v[56:59], off offset:528
	v_cvt_pk_bf16_f32 v50, v52, v53
	v_cvt_pk_bf16_f32 v51, v54, v55
	v_cvt_pk_bf16_f32 v52, v56, v57
	s_waitcnt lgkmcnt(0)
	v_add_f32_e32 v48, v48, v49
	ds_bpermute_b32 v49, v120, v48
	v_cvt_pk_bf16_f32 v53, v58, v59
	global_store_dwordx4 v[72:73], v[50:53], off offset:256 sc1
	s_and_saveexec_b64 s[16:17], s[42:43]
	s_cbranch_execz .LBB0_1070
	s_waitcnt lgkmcnt(0)
	v_add_f32_e32 v48, v48, v49
	v_mul_f32_e32 v48, 0x4b800000, v48
	v_trunc_f32_e32 v48, v48
	v_mul_f32_e32 v49, 0x2f800000, v48
	v_floor_f32_e32 v49, v49
	v_fmac_f32_e32 v48, 0xcf800000, v49
	v_cvt_u32_f32_e32 v48, v48
	v_cvt_u32_f32_e32 v49, v49
	global_atomic_add_x2 v[112:113], v[48:49], off offset:1024
.LBB0_1070:
	s_or_b64 exec, exec, s[16:17]
	v_add_u32_e32 v56, 0x90, v140
	v_ashrrev_i32_e32 v57, 31, v56
	s_waitcnt lgkmcnt(0)
	v_lshlrev_b64 v[48:49], 12, v[56:57]
	v_lshl_add_u64 v[48:49], s[48:49], 0, v[48:49]
	v_lshl_add_u64 v[58:59], v[138:139], 2, v[48:49]
	global_load_dwordx4 v[48:51], v[58:59], off
	global_load_dwordx4 v[52:55], v[58:59], off offset:16
	v_lshlrev_b64 v[56:57], 11, v[56:57]
	v_lshl_add_u64 v[56:57], s[14:15], 0, v[56:57]
	v_lshl_add_u64 v[56:57], v[138:139], 1, v[56:57]
	s_waitcnt vmcnt(1)
	v_pk_add_f32 v[46:47], v[46:47], v[50:51]
	v_pk_add_f32 v[44:45], v[44:45], v[48:49]
	s_waitcnt vmcnt(0)
	v_pk_add_f32 v[42:43], v[42:43], v[54:55]
	v_pk_add_f32 v[40:41], v[40:41], v[52:53]
	v_cvt_pk_bf16_f32 v48, v44, v45
	v_cvt_pk_bf16_f32 v49, v46, v47
	v_cvt_pk_bf16_f32 v50, v40, v41
	v_cvt_pk_bf16_f32 v51, v42, v43
	global_store_dwordx4 v[58:59], v[44:47], off
	global_store_dwordx4 v[58:59], v[40:43], off offset:16
	global_store_dwordx4 v[56:57], v[48:51], off sc1
	global_load_dwordx4 v[48:51], v[58:59], off offset:512
	s_nop 0
	global_load_dwordx4 v[52:55], v[58:59], off offset:528
	v_mul_f32_e32 v45, v45, v45
	v_mul_f32_e32 v47, v47, v47
	v_mul_f32_e32 v41, v41, v41
	v_fmac_f32_e32 v45, v44, v44
	v_fmac_f32_e32 v47, v46, v46
	v_mul_f32_e32 v43, v43, v43
	v_fmac_f32_e32 v41, v40, v40
	v_add_f32_e32 v40, v45, v47
	v_fmac_f32_e32 v43, v42, v42
	v_add_f32_e32 v40, v41, v40
	v_add_f32_e32 v44, v43, v40
	s_waitcnt vmcnt(1)
	v_pk_add_f32 v[38:39], v[38:39], v[50:51]
	v_pk_add_f32 v[36:37], v[36:37], v[48:49]
	s_waitcnt vmcnt(0)
	v_pk_add_f32 v[40:41], v[32:33], v[52:53]
	v_mul_f32_e32 v32, v37, v37
	v_mul_f32_e32 v33, v39, v39
	v_pk_add_f32 v[42:43], v[34:35], v[54:55]
	v_mul_f32_e32 v34, v41, v41
	v_fmac_f32_e32 v32, v36, v36
	v_fmac_f32_e32 v33, v38, v38
	v_mul_f32_e32 v35, v43, v43
	v_fmac_f32_e32 v34, v40, v40
	v_add_f32_e32 v32, v32, v33
	v_add_f32_e32 v32, v34, v32
	v_fmac_f32_e32 v35, v42, v42
	v_add_f32_e32 v32, v35, v32
	v_add_f32_e32 v32, v44, v32
	ds_bpermute_b32 v33, v121, v32
	global_store_dwordx4 v[58:59], v[36:39], off offset:512
	global_store_dwordx4 v[58:59], v[40:43], off offset:528
	v_cvt_pk_bf16_f32 v34, v36, v37
	v_cvt_pk_bf16_f32 v35, v38, v39
	v_cvt_pk_bf16_f32 v36, v40, v41
	s_waitcnt lgkmcnt(0)
	v_add_f32_e32 v32, v32, v33
	ds_bpermute_b32 v33, v120, v32
	v_cvt_pk_bf16_f32 v37, v42, v43
	global_store_dwordx4 v[56:57], v[34:37], off offset:256 sc1
	s_and_saveexec_b64 s[16:17], s[42:43]
	s_cbranch_execz .LBB0_1072
	s_waitcnt lgkmcnt(0)
	v_add_f32_e32 v32, v32, v33
	v_mul_f32_e32 v32, 0x4b800000, v32
	v_trunc_f32_e32 v32, v32
	v_mul_f32_e32 v33, 0x2f800000, v32
	v_floor_f32_e32 v33, v33
	v_fmac_f32_e32 v32, 0xcf800000, v33
	v_cvt_u32_f32_e32 v32, v32
	v_cvt_u32_f32_e32 v33, v33
	global_atomic_add_x2 v[112:113], v[32:33], off offset:1152
; __device__ __forceinline__ unsigned cvtpk(float lo, float hi) { f32x2_t v = {lo, hi}; bf16x2_t b = __builtin_convertvector(v, bf16x2_t); return __builtin_bit_cast(unsigned, b); }
;     __device__ __forceinline__ void operator()(const Acc& acc, const Unit& u, int wr, int wc, int fr, int fq) const {
;     ...
;             for (int m = 0; m < 4; ++m) { const int row = row0 + ai * HALF + m * 16; float* rp = X + (size_t)row * DM + col0; const float* ip = Xin + (size_t)row * DM + col0; bf16_t* bp = XB + (size_t)row * DM + col0; float part = 0.f;
; #pragma unroll
;                 for (int bj = 0; bj < 2; ++bj) { f32x4* p = (f32x4*)(rp + bj * HALF); const f32x4* q = (const f32x4*)(ip + bj * HALF); f32x4 a = q[0], b = q[1]; a += acc[ai][bj][m][0] * scale; b += acc[ai][bj][m][1] * scale; p[0] = a; p[1] = b;
;                     *(u32x4*)(bp + bj * HALF) = (u32x4){cvtpk(a[0], a[1]), cvtpk(a[2], a[3]), cvtpk(b[0], b[1]), cvtpk(b[2], b[3])};
;                     part += (a[0] * a[0] + a[1] * a[1]) + (a[2] * a[2] + a[3] * a[3]) + (b[0] * b[0] + b[1] * b[1]) + (b[2] * b[2] + b[3] * b[3]); }
;                 part += __shfl_xor(part, 16); part += __shfl_xor(part, 32);
;                 if (fq == 0) __hip_atomic_fetch_add(SS + row, (u64)(part * SSF), __ATOMIC_RELAXED, __HIP_MEMORY_SCOPE_AGENT); }
.LBB0_1072:
	s_or_b64 exec, exec, s[16:17]
	v_add_u32_e32 v40, 0xa0, v140
	v_ashrrev_i32_e32 v41, 31, v40
	s_waitcnt lgkmcnt(0)
	v_lshlrev_b64 v[32:33], 12, v[40:41]
	v_lshl_add_u64 v[32:33], s[48:49], 0, v[32:33]
	v_lshl_add_u64 v[42:43], v[138:139], 2, v[32:33]
	global_load_dwordx4 v[32:35], v[42:43], off
	global_load_dwordx4 v[36:39], v[42:43], off offset:16
	v_lshlrev_b64 v[40:41], 11, v[40:41]
	v_lshl_add_u64 v[40:41], s[14:15], 0, v[40:41]
	v_lshl_add_u64 v[40:41], v[138:139], 1, v[40:41]
	s_waitcnt vmcnt(1)
	v_pk_add_f32 v[30:31], v[30:31], v[34:35]
	v_pk_add_f32 v[28:29], v[28:29], v[32:33]
	s_waitcnt vmcnt(0)
	v_pk_add_f32 v[26:27], v[26:27], v[38:39]
	v_pk_add_f32 v[24:25], v[24:25], v[36:37]
	v_cvt_pk_bf16_f32 v32, v28, v29
	v_cvt_pk_bf16_f32 v33, v30, v31
	v_cvt_pk_bf16_f32 v34, v24, v25
	v_cvt_pk_bf16_f32 v35, v26, v27
	global_store_dwordx4 v[42:43], v[28:31], off
	global_store_dwordx4 v[42:43], v[24:27], off offset:16
	global_store_dwordx4 v[40:41], v[32:35], off sc1
	global_load_dwordx4 v[32:35], v[42:43], off offset:512
	s_nop 0
	global_load_dwordx4 v[36:39], v[42:43], off offset:528
	v_mul_f32_e32 v29, v29, v29
	v_mul_f32_e32 v31, v31, v31
	v_mul_f32_e32 v25, v25, v25
	v_fmac_f32_e32 v29, v28, v28
	v_fmac_f32_e32 v31, v30, v30
	v_mul_f32_e32 v27, v27, v27
	v_fmac_f32_e32 v25, v24, v24
	v_add_f32_e32 v24, v29, v31
	v_fmac_f32_e32 v27, v26, v26
	v_add_f32_e32 v24, v25, v24
	v_add_f32_e32 v28, v27, v24
	s_waitcnt vmcnt(1)
	v_pk_add_f32 v[22:23], v[22:23], v[34:35]
	v_pk_add_f32 v[20:21], v[20:21], v[32:33]
	s_waitcnt vmcnt(0)
	v_pk_add_f32 v[24:25], v[16:17], v[36:37]
	v_mul_f32_e32 v16, v21, v21
	v_mul_f32_e32 v17, v23, v23
	v_pk_add_f32 v[26:27], v[18:19], v[38:39]
	v_mul_f32_e32 v18, v25, v25
	v_fmac_f32_e32 v16, v20, v20
	v_fmac_f32_e32 v17, v22, v22
	v_mul_f32_e32 v19, v27, v27
	v_fmac_f32_e32 v18, v24, v24
	v_add_f32_e32 v16, v16, v17
	v_add_f32_e32 v16, v18, v16
	v_fmac_f32_e32 v19, v26, v26
	v_add_f32_e32 v16, v19, v16
	v_add_f32_e32 v16, v28, v16
	ds_bpermute_b32 v17, v121, v16
	global_store_dwordx4 v[42:43], v[20:23], off offset:512
	global_store_dwordx4 v[42:43], v[24:27], off offset:528
	v_cvt_pk_bf16_f32 v18, v20, v21
	v_cvt_pk_bf16_f32 v19, v22, v23
	v_cvt_pk_bf16_f32 v20, v24, v25
	s_waitcnt lgkmcnt(0)
	v_add_f32_e32 v16, v16, v17
	ds_bpermute_b32 v17, v120, v16
	v_cvt_pk_bf16_f32 v21, v26, v27
	global_store_dwordx4 v[40:41], v[18:21], off offset:256 sc1
	s_and_saveexec_b64 s[16:17], s[42:43]
	s_cbranch_execz .LBB0_1074
	s_waitcnt lgkmcnt(0)
	v_add_f32_e32 v16, v16, v17
	v_mul_f32_e32 v16, 0x4b800000, v16
	v_trunc_f32_e32 v16, v16
	v_mul_f32_e32 v17, 0x2f800000, v16
	v_floor_f32_e32 v17, v17
	v_fmac_f32_e32 v16, 0xcf800000, v17
	v_cvt_u32_f32_e32 v16, v16
	v_cvt_u32_f32_e32 v17, v17
	global_atomic_add_x2 v[112:113], v[16:17], off offset:1280
.LBB0_1074:
	s_or_b64 exec, exec, s[16:17]
	v_add_u32_e32 v16, 0xb0, v140
	s_waitcnt lgkmcnt(0)
	v_ashrrev_i32_e32 v17, 31, v16
	v_lshlrev_b64 v[18:19], 12, v[16:17]
	v_lshl_add_u64 v[18:19], s[48:49], 0, v[18:19]
	v_lshlrev_b64 v[16:17], 11, v[16:17]
	v_lshl_add_u64 v[24:25], v[138:139], 2, v[18:19]
	v_lshl_add_u64 v[16:17], s[14:15], 0, v[16:17]
	v_lshl_add_u64 v[26:27], v[138:139], 1, v[16:17]
	global_load_dwordx4 v[16:19], v[24:25], off offset:16
	global_load_dwordx4 v[20:23], v[24:25], off
	s_waitcnt vmcnt(1)
	v_pk_add_f32 v[10:11], v[10:11], v[18:19]
	s_waitcnt vmcnt(0)
	v_pk_add_f32 v[14:15], v[14:15], v[22:23]
	v_pk_add_f32 v[12:13], v[12:13], v[20:21]
	v_pk_add_f32 v[8:9], v[8:9], v[16:17]
	global_store_dwordx4 v[24:25], v[12:15], off
	global_store_dwordx4 v[24:25], v[8:11], off offset:16
	v_cvt_pk_bf16_f32 v16, v12, v13
	v_mul_f32_e32 v13, v13, v13
	v_fmac_f32_e32 v13, v12, v12
	v_mul_f32_e32 v12, v15, v15
	v_cvt_pk_bf16_f32 v18, v8, v9
	v_fmac_f32_e32 v12, v14, v14
	v_mul_f32_e32 v9, v9, v9
	v_add_f32_e32 v12, v13, v12
	v_fmac_f32_e32 v9, v8, v8
	v_cvt_pk_bf16_f32 v17, v14, v15
	v_cvt_pk_bf16_f32 v19, v10, v11
	v_add_f32_e32 v8, v9, v12
	v_mul_f32_e32 v9, v11, v11
	global_store_dwordx4 v[26:27], v[16:19], off sc1
	v_fmac_f32_e32 v9, v10, v10
	s_nop 0
	v_add_f32_e32 v16, v9, v8
	global_load_dwordx4 v[8:11], v[24:25], off offset:528
	global_load_dwordx4 v[12:15], v[24:25], off offset:512
	s_waitcnt vmcnt(1)
	v_pk_add_f32 v[2:3], v[2:3], v[10:11]
	s_waitcnt vmcnt(0)
	v_pk_add_f32 v[6:7], v[6:7], v[14:15]
	v_pk_add_f32 v[4:5], v[4:5], v[12:13]
	v_pk_add_f32 v[0:1], v[0:1], v[8:9]
	global_store_dwordx4 v[24:25], v[4:7], off offset:512
	global_store_dwordx4 v[24:25], v[0:3], off offset:528
	v_cvt_pk_bf16_f32 v8, v4, v5
	v_mul_f32_e32 v5, v5, v5
	v_fmac_f32_e32 v5, v4, v4
	v_mul_f32_e32 v4, v7, v7
	v_cvt_pk_bf16_f32 v10, v0, v1
	v_fmac_f32_e32 v4, v6, v6
	v_mul_f32_e32 v1, v1, v1
	v_add_f32_e32 v4, v5, v4
	v_fmac_f32_e32 v1, v0, v0
	v_add_f32_e32 v0, v1, v4
	v_mul_f32_e32 v1, v3, v3
	v_fmac_f32_e32 v1, v2, v2
	v_add_f32_e32 v0, v1, v0
	v_add_f32_e32 v0, v16, v0
	ds_bpermute_b32 v1, v121, v0
	v_cvt_pk_bf16_f32 v9, v6, v7
	v_cvt_pk_bf16_f32 v11, v2, v3
	global_store_dwordx4 v[26:27], v[8:11], off offset:256 sc1
	s_waitcnt lgkmcnt(0)
	v_add_f32_e32 v0, v0, v1
	ds_bpermute_b32 v1, v120, v0
	s_and_saveexec_b64 s[16:17], s[42:43]
	s_cbranch_execz .LBB0_1076
	s_waitcnt lgkmcnt(0)
	v_add_f32_e32 v0, v0, v1
	v_mul_f32_e32 v0, 0x4b800000, v0
	v_trunc_f32_e32 v0, v0
	v_mul_f32_e32 v1, 0x2f800000, v0
	v_floor_f32_e32 v1, v1
	v_fmac_f32_e32 v0, 0xcf800000, v1
	v_cvt_u32_f32_e32 v0, v0
	v_cvt_u32_f32_e32 v1, v1
	global_atomic_add_x2 v[112:113], v[0:1], off offset:1408

; __device__ __forceinline__ unsigned cvtpk(float lo, float hi) { f32x2_t v = {lo, hi}; bf16x2_t b = __builtin_convertvector(v, bf16x2_t); return __builtin_bit_cast(unsigned, b); }
;     __device__ __forceinline__ void operator()(const Acc& acc, const Unit& u, int wr, int wc, int fr, int fq) const {
;     ...
;             for (int m = 0; m < 4; ++m) { const int row = row0 + ai * HALF + m * 16; float* rp = X + (size_t)row * DM + col0; const float* ip = Xin + (size_t)row * DM + col0; bf16_t* bp = XB + (size_t)row * DM + col0; float part = 0.f;
; #pragma unroll
;                 for (int bj = 0; bj < 2; ++bj) { f32x4* p = (f32x4*)(rp + bj * HALF); const f32x4* q = (const f32x4*)(ip + bj * HALF); f32x4 a = q[0], b = q[1]; a += acc[ai][bj][m][0] * scale; b += acc[ai][bj][m][1] * scale; p[0] = a; p[1] = b;
;                     *(u32x4*)(bp + bj * HALF) = (u32x4){cvtpk(a[0], a[1]), cvtpk(a[2], a[3]), cvtpk(b[0], b[1]), cvtpk(b[2], b[3])};
;                     part += (a[0] * a[0] + a[1] * a[1]) + (a[2] * a[2] + a[3] * a[3]) + (b[0] * b[0] + b[1] * b[1]) + (b[2] * b[2] + b[3] * b[3]); }
;                 part += __shfl_xor(part, 16); part += __shfl_xor(part, 32);
;                 if (fq == 0) __hip_atomic_fetch_add(SS + row, (u64)(part * SSF), __ATOMIC_RELAXED, __HIP_MEMORY_SCOPE_AGENT); }
.LBB0_1260:
	v_lshl_add_u32 v140, s64, 8, v142
	v_ashrrev_i32_e32 v141, 31, v140
	v_lshl_or_b32 v138, s65, 8, v144
	v_lshlrev_b64 v[146:147], 12, v[140:141]
	v_ashrrev_i32_e32 v139, 31, v138
	v_lshl_add_u64 v[146:147], s[48:49], 0, v[146:147]
	v_lshl_add_u64 v[158:159], v[138:139], 2, v[146:147]
	global_load_dwordx4 v[146:149], v[158:159], off
	global_load_dwordx4 v[150:153], v[158:159], off offset:16
	v_lshlrev_b64 v[154:155], 11, v[140:141]
	v_lshl_add_u64 v[154:155], s[14:15], 0, v[154:155]
	v_lshl_add_u64 v[162:163], v[138:139], 1, v[154:155]
	s_waitcnt vmcnt(0)
	v_pk_fma_f32 v[126:127], v[126:127], 0.5, v[148:149] op_sel_hi:[1,0,1]
	v_pk_fma_f32 v[124:125], v[124:125], 0.5, v[146:147] op_sel_hi:[1,0,1]
	v_pk_fma_f32 v[148:149], v[122:123], 0.5, v[152:153] op_sel_hi:[1,0,1]
	v_pk_fma_f32 v[146:147], v[120:121], 0.5, v[150:151] op_sel_hi:[1,0,1]
	v_cvt_pk_bf16_f32 v120, v124, v125
	v_cvt_pk_bf16_f32 v121, v126, v127
	v_cvt_pk_bf16_f32 v122, v146, v147
	v_cvt_pk_bf16_f32 v123, v148, v149
	global_store_dwordx4 v[158:159], v[124:127], off
	global_store_dwordx4 v[158:159], v[146:149], off offset:16
	global_store_dwordx4 v[162:163], v[120:123], off sc1
	global_load_dwordx4 v[150:153], v[158:159], off offset:512
	global_load_dwordx4 v[154:157], v[158:159], off offset:528
	v_and_b32_e32 v121, 64, v229
	v_xor_b32_e32 v120, 16, v229
	v_add_u32_e32 v121, 64, v121
	v_xor_b32_e32 v122, 32, v229
	v_cmp_lt_i32_e32 vcc, v120, v121
	v_mul_f32_e32 v123, v127, v127
	v_fmac_f32_e32 v123, v126, v126
	v_cndmask_b32_e32 v120, v229, v120, vcc
	v_cmp_lt_i32_e32 vcc, v122, v121
	v_mul_f32_e32 v127, v149, v149
	v_fmac_f32_e32 v127, v148, v148
	v_cndmask_b32_e32 v121, v229, v122, vcc
	v_mul_f32_e32 v122, v125, v125
	v_mul_f32_e32 v125, v147, v147
	v_fmac_f32_e32 v122, v124, v124
	v_fmac_f32_e32 v125, v146, v146
	v_add_f32_e32 v122, v122, v123
	v_add_f32_e32 v122, v125, v122
	v_add_f32_e32 v126, v127, v122
	v_lshlrev_b32_e32 v120, 2, v120
	s_waitcnt vmcnt(1)
	v_pk_fma_f32 v[118:119], v[118:119], 0.5, v[152:153] op_sel_hi:[1,0,1]
	v_pk_fma_f32 v[116:117], v[116:117], 0.5, v[150:151] op_sel_hi:[1,0,1]
	s_waitcnt vmcnt(0)
	v_pk_fma_f32 v[122:123], v[112:113], 0.5, v[154:155] op_sel_hi:[1,0,1]
	v_mul_f32_e32 v112, v117, v117
	v_mul_f32_e32 v113, v119, v119
	v_pk_fma_f32 v[124:125], v[114:115], 0.5, v[156:157] op_sel_hi:[1,0,1]
	v_mul_f32_e32 v114, v123, v123
	v_fmac_f32_e32 v112, v116, v116
	v_fmac_f32_e32 v113, v118, v118
	v_mul_f32_e32 v115, v125, v125
	v_fmac_f32_e32 v114, v122, v122
	v_add_f32_e32 v112, v112, v113
	v_add_f32_e32 v112, v114, v112
	v_fmac_f32_e32 v115, v124, v124
	v_add_f32_e32 v112, v115, v112
	v_add_f32_e32 v112, v126, v112
	ds_bpermute_b32 v113, v120, v112
	v_lshlrev_b32_e32 v114, 2, v121
	global_store_dwordx4 v[158:159], v[116:119], off offset:512
	global_store_dwordx4 v[158:159], v[122:125], off offset:528
	s_waitcnt lgkmcnt(0)
	v_add_f32_e32 v112, v112, v113
	ds_bpermute_b32 v113, v114, v112
	v_cvt_pk_bf16_f32 v116, v116, v117
	v_cvt_pk_bf16_f32 v117, v118, v119
	v_cvt_pk_bf16_f32 v118, v122, v123
	v_cvt_pk_bf16_f32 v119, v124, v125
	global_store_dwordx4 v[162:163], v[116:119], off offset:256 sc1
	s_and_saveexec_b64 s[16:17], s[40:41]
	s_cbranch_execz .LBB0_1262
	s_waitcnt lgkmcnt(0)
	v_add_f32_e32 v112, v112, v113
	v_mul_f32_e32 v112, 0x4b800000, v112
	v_trunc_f32_e32 v112, v112
	v_mul_f32_e32 v113, 0x2f800000, v112
	v_floor_f32_e32 v113, v113
	v_fmac_f32_e32 v112, 0xcf800000, v113
	v_cvt_u32_f32_e32 v112, v112
	v_cvt_u32_f32_e32 v113, v113
	v_lshl_add_u64 v[116:117], v[140:141], 3, s[18:19]
	global_atomic_add_x2 v[116:117], v[112:113], off
.LBB0_1262:
	s_or_b64 exec, exec, s[16:17]
	v_or_b32_e32 v112, 16, v140
	s_waitcnt lgkmcnt(0)
	v_ashrrev_i32_e32 v113, 31, v112
	v_lshlrev_b64 v[116:117], 12, v[112:113]
	v_lshl_add_u64 v[116:117], s[48:49], 0, v[116:117]
	v_lshl_add_u64 v[126:127], v[138:139], 2, v[116:117]
	global_load_dwordx4 v[116:119], v[126:127], off
	global_load_dwordx4 v[122:125], v[126:127], off offset:16
	v_lshlrev_b64 v[146:147], 11, v[112:113]
	v_lshl_add_u64 v[146:147], s[14:15], 0, v[146:147]
	v_lshl_add_u64 v[146:147], v[138:139], 1, v[146:147]
	s_waitcnt vmcnt(1)
	v_pk_fma_f32 v[110:111], v[110:111], 0.5, v[118:119] op_sel_hi:[1,0,1]
	v_pk_fma_f32 v[108:109], v[108:109], 0.5, v[116:117] op_sel_hi:[1,0,1]
	s_waitcnt vmcnt(0)
	v_pk_fma_f32 v[106:107], v[106:107], 0.5, v[124:125] op_sel_hi:[1,0,1]
	v_pk_fma_f32 v[104:105], v[104:105], 0.5, v[122:123] op_sel_hi:[1,0,1]
	v_cvt_pk_bf16_f32 v116, v108, v109
	v_cvt_pk_bf16_f32 v117, v110, v111
	v_cvt_pk_bf16_f32 v118, v104, v105
	v_cvt_pk_bf16_f32 v119, v106, v107
	global_store_dwordx4 v[126:127], v[108:111], off
	global_store_dwordx4 v[126:127], v[104:107], off offset:16
	global_store_dwordx4 v[146:147], v[116:119], off sc1
	global_load_dwordx4 v[116:119], v[126:127], off offset:512
	s_nop 0
	global_load_dwordx4 v[122:125], v[126:127], off offset:528
	v_mul_f32_e32 v109, v109, v109
	v_mul_f32_e32 v111, v111, v111
	v_mul_f32_e32 v105, v105, v105
	v_fmac_f32_e32 v109, v108, v108
	v_fmac_f32_e32 v111, v110, v110
	v_mul_f32_e32 v107, v107, v107
	v_fmac_f32_e32 v105, v104, v104
	v_add_f32_e32 v104, v109, v111
	v_fmac_f32_e32 v107, v106, v106
	v_add_f32_e32 v104, v105, v104
	v_add_f32_e32 v108, v107, v104
	s_waitcnt vmcnt(1)
	v_pk_fma_f32 v[102:103], v[102:103], 0.5, v[118:119] op_sel_hi:[1,0,1]
	v_pk_fma_f32 v[100:101], v[100:101], 0.5, v[116:117] op_sel_hi:[1,0,1]
	s_waitcnt vmcnt(0)
	v_pk_fma_f32 v[104:105], v[96:97], 0.5, v[122:123] op_sel_hi:[1,0,1]
	v_mul_f32_e32 v96, v101, v101
	v_mul_f32_e32 v97, v103, v103
	v_pk_fma_f32 v[106:107], v[98:99], 0.5, v[124:125] op_sel_hi:[1,0,1]
	v_mul_f32_e32 v98, v105, v105
	v_fmac_f32_e32 v96, v100, v100
	v_fmac_f32_e32 v97, v102, v102
	v_mul_f32_e32 v99, v107, v107
	v_fmac_f32_e32 v98, v104, v104
	v_add_f32_e32 v96, v96, v97
	v_add_f32_e32 v96, v98, v96
	v_fmac_f32_e32 v99, v106, v106
	v_add_f32_e32 v96, v99, v96
	v_add_f32_e32 v96, v108, v96
	ds_bpermute_b32 v97, v120, v96
	global_store_dwordx4 v[126:127], v[100:103], off offset:512
	global_store_dwordx4 v[126:127], v[104:107], off offset:528
	v_cvt_pk_bf16_f32 v98, v100, v101
	v_cvt_pk_bf16_f32 v99, v102, v103
	v_cvt_pk_bf16_f32 v100, v104, v105
	s_waitcnt lgkmcnt(0)
	v_add_f32_e32 v96, v96, v97
	ds_bpermute_b32 v97, v114, v96
	v_cvt_pk_bf16_f32 v101, v106, v107
	global_store_dwordx4 v[146:147], v[98:101], off offset:256 sc1
	s_and_saveexec_b64 s[16:17], s[40:41]
	s_cbranch_execz .LBB0_1264
	s_waitcnt lgkmcnt(0)
	v_add_f32_e32 v96, v96, v97
	v_mul_f32_e32 v96, 0x4b800000, v96
	v_trunc_f32_e32 v96, v96
	v_mul_f32_e32 v97, 0x2f800000, v96
	v_floor_f32_e32 v97, v97
	v_fmac_f32_e32 v96, 0xcf800000, v97
	v_cvt_u32_f32_e32 v96, v96
	v_cvt_u32_f32_e32 v97, v97
	v_lshl_add_u64 v[98:99], v[112:113], 3, s[18:19]
	global_atomic_add_x2 v[98:99], v[96:97], off
; __device__ __forceinline__ unsigned cvtpk(float lo, float hi) { f32x2_t v = {lo, hi}; bf16x2_t b = __builtin_convertvector(v, bf16x2_t); return __builtin_bit_cast(unsigned, b); }
;     __device__ __forceinline__ void operator()(const Acc& acc, const Unit& u, int wr, int wc, int fr, int fq) const {
;     ...
;             for (int m = 0; m < 4; ++m) { const int row = row0 + ai * HALF + m * 16; float* rp = X + (size_t)row * DM + col0; const float* ip = Xin + (size_t)row * DM + col0; bf16_t* bp = XB + (size_t)row * DM + col0; float part = 0.f;
; #pragma unroll
;                 for (int bj = 0; bj < 2; ++bj) { f32x4* p = (f32x4*)(rp + bj * HALF); const f32x4* q = (const f32x4*)(ip + bj * HALF); f32x4 a = q[0], b = q[1]; a += acc[ai][bj][m][0] * scale; b += acc[ai][bj][m][1] * scale; p[0] = a; p[1] = b;
;                     *(u32x4*)(bp + bj * HALF) = (u32x4){cvtpk(a[0], a[1]), cvtpk(a[2], a[3]), cvtpk(b[0], b[1]), cvtpk(b[2], b[3])};
;                     part += (a[0] * a[0] + a[1] * a[1]) + (a[2] * a[2] + a[3] * a[3]) + (b[0] * b[0] + b[1] * b[1]) + (b[2] * b[2] + b[3] * b[3]); }
;                 part += __shfl_xor(part, 16); part += __shfl_xor(part, 32);
;                 if (fq == 0) __hip_atomic_fetch_add(SS + row, (u64)(part * SSF), __ATOMIC_RELAXED, __HIP_MEMORY_SCOPE_AGENT); }
.LBB0_1264:
	s_or_b64 exec, exec, s[16:17]
	v_or_b32_e32 v96, 32, v140
	s_waitcnt lgkmcnt(0)
	v_ashrrev_i32_e32 v97, 31, v96
	v_lshlrev_b64 v[98:99], 12, v[96:97]
	v_lshl_add_u64 v[98:99], s[48:49], 0, v[98:99]
	v_lshl_add_u64 v[106:107], v[138:139], 2, v[98:99]
	global_load_dwordx4 v[98:101], v[106:107], off
	global_load_dwordx4 v[102:105], v[106:107], off offset:16
	v_lshlrev_b64 v[108:109], 11, v[96:97]
	v_lshl_add_u64 v[108:109], s[14:15], 0, v[108:109]
	v_lshl_add_u64 v[108:109], v[138:139], 1, v[108:109]
	s_waitcnt vmcnt(1)
	v_pk_fma_f32 v[94:95], v[94:95], 0.5, v[100:101] op_sel_hi:[1,0,1]
	v_pk_fma_f32 v[92:93], v[92:93], 0.5, v[98:99] op_sel_hi:[1,0,1]
	s_waitcnt vmcnt(0)
	v_pk_fma_f32 v[90:91], v[90:91], 0.5, v[104:105] op_sel_hi:[1,0,1]
	v_pk_fma_f32 v[88:89], v[88:89], 0.5, v[102:103] op_sel_hi:[1,0,1]
	v_cvt_pk_bf16_f32 v98, v92, v93
	v_cvt_pk_bf16_f32 v99, v94, v95
	v_cvt_pk_bf16_f32 v100, v88, v89
	v_cvt_pk_bf16_f32 v101, v90, v91
	global_store_dwordx4 v[106:107], v[92:95], off
	global_store_dwordx4 v[106:107], v[88:91], off offset:16
	global_store_dwordx4 v[108:109], v[98:101], off sc1
	global_load_dwordx4 v[98:101], v[106:107], off offset:512
	s_nop 0
	global_load_dwordx4 v[102:105], v[106:107], off offset:528
	v_mul_f32_e32 v93, v93, v93
	v_mul_f32_e32 v95, v95, v95
	v_mul_f32_e32 v89, v89, v89
	v_fmac_f32_e32 v93, v92, v92
	v_fmac_f32_e32 v95, v94, v94
	v_mul_f32_e32 v91, v91, v91
	v_fmac_f32_e32 v89, v88, v88
	v_add_f32_e32 v88, v93, v95
	v_fmac_f32_e32 v91, v90, v90
	v_add_f32_e32 v88, v89, v88
	v_add_f32_e32 v92, v91, v88
	s_waitcnt vmcnt(1)
	v_pk_fma_f32 v[86:87], v[86:87], 0.5, v[100:101] op_sel_hi:[1,0,1]
	v_pk_fma_f32 v[84:85], v[84:85], 0.5, v[98:99] op_sel_hi:[1,0,1]
	s_waitcnt vmcnt(0)
	v_pk_fma_f32 v[88:89], v[80:81], 0.5, v[102:103] op_sel_hi:[1,0,1]
	v_mul_f32_e32 v80, v85, v85
	v_mul_f32_e32 v81, v87, v87
	v_pk_fma_f32 v[90:91], v[82:83], 0.5, v[104:105] op_sel_hi:[1,0,1]
	v_mul_f32_e32 v82, v89, v89
	v_fmac_f32_e32 v80, v84, v84
	v_fmac_f32_e32 v81, v86, v86
	v_mul_f32_e32 v83, v91, v91
	v_fmac_f32_e32 v82, v88, v88
	v_add_f32_e32 v80, v80, v81
	v_add_f32_e32 v80, v82, v80
	v_fmac_f32_e32 v83, v90, v90
	v_add_f32_e32 v80, v83, v80
	v_add_f32_e32 v80, v92, v80
	ds_bpermute_b32 v81, v120, v80
	global_store_dwordx4 v[106:107], v[84:87], off offset:512
	global_store_dwordx4 v[106:107], v[88:91], off offset:528
	v_cvt_pk_bf16_f32 v82, v84, v85
	v_cvt_pk_bf16_f32 v83, v86, v87
	v_cvt_pk_bf16_f32 v84, v88, v89
	s_waitcnt lgkmcnt(0)
	v_add_f32_e32 v80, v80, v81
	ds_bpermute_b32 v81, v114, v80
	v_cvt_pk_bf16_f32 v85, v90, v91
	global_store_dwordx4 v[108:109], v[82:85], off offset:256 sc1
	s_and_saveexec_b64 s[16:17], s[40:41]
	s_cbranch_execz .LBB0_1266
	s_waitcnt lgkmcnt(0)
	v_add_f32_e32 v80, v80, v81
	v_mul_f32_e32 v80, 0x4b800000, v80
	v_trunc_f32_e32 v80, v80
	v_mul_f32_e32 v81, 0x2f800000, v80
	v_floor_f32_e32 v81, v81
	v_fmac_f32_e32 v80, 0xcf800000, v81
	v_cvt_u32_f32_e32 v80, v80
	v_cvt_u32_f32_e32 v81, v81
	v_lshl_add_u64 v[82:83], v[96:97], 3, s[18:19]
	global_atomic_add_x2 v[82:83], v[80:81], off
.LBB0_1266:
	s_or_b64 exec, exec, s[16:17]
	v_or_b32_e32 v80, 48, v140
	s_waitcnt lgkmcnt(0)
	v_ashrrev_i32_e32 v81, 31, v80
	v_lshlrev_b64 v[82:83], 12, v[80:81]
	v_lshl_add_u64 v[82:83], s[48:49], 0, v[82:83]
	v_lshl_add_u64 v[90:91], v[138:139], 2, v[82:83]
	global_load_dwordx4 v[82:85], v[90:91], off
	global_load_dwordx4 v[86:89], v[90:91], off offset:16
	v_lshlrev_b64 v[92:93], 11, v[80:81]
	v_lshl_add_u64 v[92:93], s[14:15], 0, v[92:93]
	v_lshl_add_u64 v[92:93], v[138:139], 1, v[92:93]
	s_waitcnt vmcnt(1)
	v_pk_fma_f32 v[78:79], v[78:79], 0.5, v[84:85] op_sel_hi:[1,0,1]
	v_pk_fma_f32 v[76:77], v[76:77], 0.5, v[82:83] op_sel_hi:[1,0,1]
	s_waitcnt vmcnt(0)
	v_pk_fma_f32 v[74:75], v[74:75], 0.5, v[88:89] op_sel_hi:[1,0,1]
	v_pk_fma_f32 v[72:73], v[72:73], 0.5, v[86:87] op_sel_hi:[1,0,1]
	v_cvt_pk_bf16_f32 v82, v76, v77
	v_cvt_pk_bf16_f32 v83, v78, v79
	v_cvt_pk_bf16_f32 v84, v72, v73
	v_cvt_pk_bf16_f32 v85, v74, v75
	global_store_dwordx4 v[90:91], v[76:79], off
	global_store_dwordx4 v[90:91], v[72:75], off offset:16
	global_store_dwordx4 v[92:93], v[82:85], off sc1
	global_load_dwordx4 v[82:85], v[90:91], off offset:512
	s_nop 0
	global_load_dwordx4 v[86:89], v[90:91], off offset:528
	v_mul_f32_e32 v77, v77, v77
	v_mul_f32_e32 v79, v79, v79
	v_mul_f32_e32 v73, v73, v73
	v_fmac_f32_e32 v77, v76, v76
	v_fmac_f32_e32 v79, v78, v78
	v_mul_f32_e32 v75, v75, v75
	v_fmac_f32_e32 v73, v72, v72
	v_add_f32_e32 v72, v77, v79
	v_fmac_f32_e32 v75, v74, v74
	v_add_f32_e32 v72, v73, v72
	v_add_f32_e32 v76, v75, v72
	s_waitcnt vmcnt(1)
	v_pk_fma_f32 v[70:71], v[70:71], 0.5, v[84:85] op_sel_hi:[1,0,1]
	v_pk_fma_f32 v[68:69], v[68:69], 0.5, v[82:83] op_sel_hi:[1,0,1]
	s_waitcnt vmcnt(0)
	v_pk_fma_f32 v[72:73], v[64:65], 0.5, v[86:87] op_sel_hi:[1,0,1]
	v_mul_f32_e32 v64, v69, v69
	v_mul_f32_e32 v65, v71, v71
	v_pk_fma_f32 v[74:75], v[66:67], 0.5, v[88:89] op_sel_hi:[1,0,1]
	v_mul_f32_e32 v66, v73, v73
	v_fmac_f32_e32 v64, v68, v68
	v_fmac_f32_e32 v65, v70, v70
	v_mul_f32_e32 v67, v75, v75
	v_fmac_f32_e32 v66, v72, v72
	v_add_f32_e32 v64, v64, v65
	v_add_f32_e32 v64, v66, v64
	v_fmac_f32_e32 v67, v74, v74
	v_add_f32_e32 v64, v67, v64
	v_add_f32_e32 v64, v76, v64
	ds_bpermute_b32 v65, v120, v64
	global_store_dwordx4 v[90:91], v[68:71], off offset:512
	global_store_dwordx4 v[90:91], v[72:75], off offset:528
	v_cvt_pk_bf16_f32 v66, v68, v69
	v_cvt_pk_bf16_f32 v67, v70, v71
	v_cvt_pk_bf16_f32 v68, v72, v73
	s_waitcnt lgkmcnt(0)
	v_add_f32_e32 v64, v64, v65
	ds_bpermute_b32 v65, v114, v64
	v_cvt_pk_bf16_f32 v69, v74, v75
	global_store_dwordx4 v[92:93], v[66:69], off offset:256 sc1
	s_and_saveexec_b64 s[16:17], s[40:41]
	s_cbranch_execz .LBB0_1268
	s_waitcnt lgkmcnt(0)
	v_add_f32_e32 v64, v64, v65
	v_mul_f32_e32 v64, 0x4b800000, v64
	v_trunc_f32_e32 v64, v64
	v_mul_f32_e32 v65, 0x2f800000, v64
	v_floor_f32_e32 v65, v65
	v_fmac_f32_e32 v64, 0xcf800000, v65
	v_cvt_u32_f32_e32 v64, v64
	v_cvt_u32_f32_e32 v65, v65
	v_lshl_add_u64 v[66:67], v[80:81], 3, s[18:19]
	global_atomic_add_x2 v[66:67], v[64:65], off
; __device__ __forceinline__ unsigned cvtpk(float lo, float hi) { f32x2_t v = {lo, hi}; bf16x2_t b = __builtin_convertvector(v, bf16x2_t); return __builtin_bit_cast(unsigned, b); }
;     __device__ __forceinline__ void operator()(const Acc& acc, const Unit& u, int wr, int wc, int fr, int fq) const {
;     ...
;             for (int m = 0; m < 4; ++m) { const int row = row0 + ai * HALF + m * 16; float* rp = X + (size_t)row * DM + col0; const float* ip = Xin + (size_t)row * DM + col0; bf16_t* bp = XB + (size_t)row * DM + col0; float part = 0.f;
; #pragma unroll
;                 for (int bj = 0; bj < 2; ++bj) { f32x4* p = (f32x4*)(rp + bj * HALF); const f32x4* q = (const f32x4*)(ip + bj * HALF); f32x4 a = q[0], b = q[1]; a += acc[ai][bj][m][0] * scale; b += acc[ai][bj][m][1] * scale; p[0] = a; p[1] = b;
;                     *(u32x4*)(bp + bj * HALF) = (u32x4){cvtpk(a[0], a[1]), cvtpk(a[2], a[3]), cvtpk(b[0], b[1]), cvtpk(b[2], b[3])};
;                     part += (a[0] * a[0] + a[1] * a[1]) + (a[2] * a[2] + a[3] * a[3]) + (b[0] * b[0] + b[1] * b[1]) + (b[2] * b[2] + b[3] * b[3]); }
;                 part += __shfl_xor(part, 16); part += __shfl_xor(part, 32);
;                 if (fq == 0) __hip_atomic_fetch_add(SS + row, (u64)(part * SSF), __ATOMIC_RELAXED, __HIP_MEMORY_SCOPE_AGENT); }
.LBB0_1268:
	s_or_b64 exec, exec, s[16:17]
	v_add_u32_e32 v64, 0x80, v140
	s_waitcnt lgkmcnt(0)
	v_ashrrev_i32_e32 v65, 31, v64
	v_lshlrev_b64 v[66:67], 12, v[64:65]
	v_lshl_add_u64 v[66:67], s[48:49], 0, v[66:67]
	v_lshl_add_u64 v[74:75], v[138:139], 2, v[66:67]
	global_load_dwordx4 v[66:69], v[74:75], off
	global_load_dwordx4 v[70:73], v[74:75], off offset:16
	v_lshlrev_b64 v[76:77], 11, v[64:65]
	v_lshl_add_u64 v[76:77], s[14:15], 0, v[76:77]
	v_lshl_add_u64 v[76:77], v[138:139], 1, v[76:77]
	s_waitcnt vmcnt(1)
	v_pk_fma_f32 v[62:63], v[62:63], 0.5, v[68:69] op_sel_hi:[1,0,1]
	v_pk_fma_f32 v[60:61], v[60:61], 0.5, v[66:67] op_sel_hi:[1,0,1]
	s_waitcnt vmcnt(0)
	v_pk_fma_f32 v[58:59], v[58:59], 0.5, v[72:73] op_sel_hi:[1,0,1]
	v_pk_fma_f32 v[56:57], v[56:57], 0.5, v[70:71] op_sel_hi:[1,0,1]
	v_cvt_pk_bf16_f32 v66, v60, v61
	v_cvt_pk_bf16_f32 v67, v62, v63
	v_cvt_pk_bf16_f32 v68, v56, v57
	v_cvt_pk_bf16_f32 v69, v58, v59
	global_store_dwordx4 v[74:75], v[60:63], off
	global_store_dwordx4 v[74:75], v[56:59], off offset:16
	global_store_dwordx4 v[76:77], v[66:69], off sc1
	global_load_dwordx4 v[66:69], v[74:75], off offset:512
	s_nop 0
	global_load_dwordx4 v[70:73], v[74:75], off offset:528
	v_mul_f32_e32 v61, v61, v61
	v_mul_f32_e32 v63, v63, v63
	v_mul_f32_e32 v57, v57, v57
	v_fmac_f32_e32 v61, v60, v60
	v_fmac_f32_e32 v63, v62, v62
	v_mul_f32_e32 v59, v59, v59
	v_fmac_f32_e32 v57, v56, v56
	v_add_f32_e32 v56, v61, v63
	v_fmac_f32_e32 v59, v58, v58
	v_add_f32_e32 v56, v57, v56
	v_add_f32_e32 v60, v59, v56
	s_waitcnt vmcnt(1)
	v_pk_fma_f32 v[54:55], v[54:55], 0.5, v[68:69] op_sel_hi:[1,0,1]
	v_pk_fma_f32 v[52:53], v[52:53], 0.5, v[66:67] op_sel_hi:[1,0,1]
	s_waitcnt vmcnt(0)
	v_pk_fma_f32 v[56:57], v[48:49], 0.5, v[70:71] op_sel_hi:[1,0,1]
	v_mul_f32_e32 v48, v53, v53
	v_mul_f32_e32 v49, v55, v55
	v_pk_fma_f32 v[58:59], v[50:51], 0.5, v[72:73] op_sel_hi:[1,0,1]
	v_mul_f32_e32 v50, v57, v57
	v_fmac_f32_e32 v48, v52, v52
	v_fmac_f32_e32 v49, v54, v54
	v_mul_f32_e32 v51, v59, v59
	v_fmac_f32_e32 v50, v56, v56
	v_add_f32_e32 v48, v48, v49
	v_add_f32_e32 v48, v50, v48
	v_fmac_f32_e32 v51, v58, v58
	v_add_f32_e32 v48, v51, v48
	v_add_f32_e32 v48, v60, v48
	ds_bpermute_b32 v49, v120, v48
	global_store_dwordx4 v[74:75], v[52:55], off offset:512
	global_store_dwordx4 v[74:75], v[56:59], off offset:528
	v_cvt_pk_bf16_f32 v50, v52, v53
	v_cvt_pk_bf16_f32 v51, v54, v55
	v_cvt_pk_bf16_f32 v52, v56, v57
	s_waitcnt lgkmcnt(0)
	v_add_f32_e32 v48, v48, v49
	ds_bpermute_b32 v49, v114, v48
	v_cvt_pk_bf16_f32 v53, v58, v59
	global_store_dwordx4 v[76:77], v[50:53], off offset:256 sc1
	s_and_saveexec_b64 s[16:17], s[40:41]
	s_cbranch_execz .LBB0_1270
	s_waitcnt lgkmcnt(0)
	v_add_f32_e32 v48, v48, v49
	v_mul_f32_e32 v48, 0x4b800000, v48
	v_trunc_f32_e32 v48, v48
	v_mul_f32_e32 v49, 0x2f800000, v48
	v_floor_f32_e32 v49, v49
	v_fmac_f32_e32 v48, 0xcf800000, v49
	v_cvt_u32_f32_e32 v48, v48
	v_cvt_u32_f32_e32 v49, v49
	v_lshl_add_u64 v[50:51], v[64:65], 3, s[18:19]
	global_atomic_add_x2 v[50:51], v[48:49], off
.LBB0_1270:
	s_or_b64 exec, exec, s[16:17]
	v_add_u32_e32 v48, 0x90, v140
	s_waitcnt lgkmcnt(0)
	v_ashrrev_i32_e32 v49, 31, v48
	v_lshlrev_b64 v[50:51], 12, v[48:49]
	v_lshl_add_u64 v[50:51], s[48:49], 0, v[50:51]
	v_lshl_add_u64 v[58:59], v[138:139], 2, v[50:51]
	global_load_dwordx4 v[50:53], v[58:59], off
	global_load_dwordx4 v[54:57], v[58:59], off offset:16
	v_lshlrev_b64 v[60:61], 11, v[48:49]
	v_lshl_add_u64 v[60:61], s[14:15], 0, v[60:61]
	v_lshl_add_u64 v[60:61], v[138:139], 1, v[60:61]
	s_waitcnt vmcnt(1)
	v_pk_fma_f32 v[46:47], v[46:47], 0.5, v[52:53] op_sel_hi:[1,0,1]
	v_pk_fma_f32 v[44:45], v[44:45], 0.5, v[50:51] op_sel_hi:[1,0,1]
	s_waitcnt vmcnt(0)
	v_pk_fma_f32 v[42:43], v[42:43], 0.5, v[56:57] op_sel_hi:[1,0,1]
	v_pk_fma_f32 v[40:41], v[40:41], 0.5, v[54:55] op_sel_hi:[1,0,1]
	v_cvt_pk_bf16_f32 v50, v44, v45
	v_cvt_pk_bf16_f32 v51, v46, v47
	v_cvt_pk_bf16_f32 v52, v40, v41
	v_cvt_pk_bf16_f32 v53, v42, v43
	global_store_dwordx4 v[58:59], v[44:47], off
	global_store_dwordx4 v[58:59], v[40:43], off offset:16
	global_store_dwordx4 v[60:61], v[50:53], off sc1
	global_load_dwordx4 v[50:53], v[58:59], off offset:512
	s_nop 0
	global_load_dwordx4 v[54:57], v[58:59], off offset:528
	v_mul_f32_e32 v45, v45, v45
	v_mul_f32_e32 v47, v47, v47
	v_mul_f32_e32 v41, v41, v41
	v_fmac_f32_e32 v45, v44, v44
	v_fmac_f32_e32 v47, v46, v46
	v_mul_f32_e32 v43, v43, v43
	v_fmac_f32_e32 v41, v40, v40
	v_add_f32_e32 v40, v45, v47
	v_fmac_f32_e32 v43, v42, v42
	v_add_f32_e32 v40, v41, v40
	v_add_f32_e32 v44, v43, v40
	s_waitcnt vmcnt(1)
	v_pk_fma_f32 v[38:39], v[38:39], 0.5, v[52:53] op_sel_hi:[1,0,1]
	v_pk_fma_f32 v[36:37], v[36:37], 0.5, v[50:51] op_sel_hi:[1,0,1]
	s_waitcnt vmcnt(0)
	v_pk_fma_f32 v[40:41], v[32:33], 0.5, v[54:55] op_sel_hi:[1,0,1]
	v_mul_f32_e32 v32, v37, v37
	v_mul_f32_e32 v33, v39, v39
	v_pk_fma_f32 v[42:43], v[34:35], 0.5, v[56:57] op_sel_hi:[1,0,1]
	v_mul_f32_e32 v34, v41, v41
	v_fmac_f32_e32 v32, v36, v36
	v_fmac_f32_e32 v33, v38, v38
	v_mul_f32_e32 v35, v43, v43
	v_fmac_f32_e32 v34, v40, v40
	v_add_f32_e32 v32, v32, v33
	v_add_f32_e32 v32, v34, v32
	v_fmac_f32_e32 v35, v42, v42
	v_add_f32_e32 v32, v35, v32
	v_add_f32_e32 v32, v44, v32
	ds_bpermute_b32 v33, v120, v32
	global_store_dwordx4 v[58:59], v[36:39], off offset:512
	global_store_dwordx4 v[58:59], v[40:43], off offset:528
	v_cvt_pk_bf16_f32 v34, v36, v37
	v_cvt_pk_bf16_f32 v35, v38, v39
	v_cvt_pk_bf16_f32 v36, v40, v41
	s_waitcnt lgkmcnt(0)
	v_add_f32_e32 v32, v32, v33
	ds_bpermute_b32 v33, v114, v32
	v_cvt_pk_bf16_f32 v37, v42, v43
	global_store_dwordx4 v[60:61], v[34:37], off offset:256 sc1
	s_and_saveexec_b64 s[16:17], s[40:41]
	s_cbranch_execz .LBB0_1272
	s_waitcnt lgkmcnt(0)
	v_add_f32_e32 v32, v32, v33
	v_mul_f32_e32 v32, 0x4b800000, v32
	v_trunc_f32_e32 v32, v32
	v_mul_f32_e32 v33, 0x2f800000, v32
	v_floor_f32_e32 v33, v33
	v_fmac_f32_e32 v32, 0xcf800000, v33
	v_cvt_u32_f32_e32 v32, v32
	v_cvt_u32_f32_e32 v33, v33
	v_lshl_add_u64 v[34:35], v[48:49], 3, s[18:19]
	global_atomic_add_x2 v[34:35], v[32:33], off
; __device__ __forceinline__ unsigned cvtpk(float lo, float hi) { f32x2_t v = {lo, hi}; bf16x2_t b = __builtin_convertvector(v, bf16x2_t); return __builtin_bit_cast(unsigned, b); }
;     __device__ __forceinline__ void operator()(const Acc& acc, const Unit& u, int wr, int wc, int fr, int fq) const {
;     ...
;             for (int m = 0; m < 4; ++m) { const int row = row0 + ai * HALF + m * 16; float* rp = X + (size_t)row * DM + col0; const float* ip = Xin + (size_t)row * DM + col0; bf16_t* bp = XB + (size_t)row * DM + col0; float part = 0.f;
; #pragma unroll
;                 for (int bj = 0; bj < 2; ++bj) { f32x4* p = (f32x4*)(rp + bj * HALF); const f32x4* q = (const f32x4*)(ip + bj * HALF); f32x4 a = q[0], b = q[1]; a += acc[ai][bj][m][0] * scale; b += acc[ai][bj][m][1] * scale; p[0] = a; p[1] = b;
;                     *(u32x4*)(bp + bj * HALF) = (u32x4){cvtpk(a[0], a[1]), cvtpk(a[2], a[3]), cvtpk(b[0], b[1]), cvtpk(b[2], b[3])};
;                     part += (a[0] * a[0] + a[1] * a[1]) + (a[2] * a[2] + a[3] * a[3]) + (b[0] * b[0] + b[1] * b[1]) + (b[2] * b[2] + b[3] * b[3]); }
;                 part += __shfl_xor(part, 16); part += __shfl_xor(part, 32);
;                 if (fq == 0) __hip_atomic_fetch_add(SS + row, (u64)(part * SSF), __ATOMIC_RELAXED, __HIP_MEMORY_SCOPE_AGENT); }
.LBB0_1272:
	s_or_b64 exec, exec, s[16:17]
	v_add_u32_e32 v32, 0xa0, v140
	s_waitcnt lgkmcnt(0)
	v_ashrrev_i32_e32 v33, 31, v32
	v_lshlrev_b64 v[34:35], 12, v[32:33]
	v_lshl_add_u64 v[34:35], s[48:49], 0, v[34:35]
	v_lshl_add_u64 v[42:43], v[138:139], 2, v[34:35]
	global_load_dwordx4 v[34:37], v[42:43], off
	global_load_dwordx4 v[38:41], v[42:43], off offset:16
	v_lshlrev_b64 v[44:45], 11, v[32:33]
	v_lshl_add_u64 v[44:45], s[14:15], 0, v[44:45]
	v_lshl_add_u64 v[44:45], v[138:139], 1, v[44:45]
	s_waitcnt vmcnt(1)
	v_pk_fma_f32 v[30:31], v[30:31], 0.5, v[36:37] op_sel_hi:[1,0,1]
	v_pk_fma_f32 v[28:29], v[28:29], 0.5, v[34:35] op_sel_hi:[1,0,1]
	s_waitcnt vmcnt(0)
	v_pk_fma_f32 v[26:27], v[26:27], 0.5, v[40:41] op_sel_hi:[1,0,1]
	v_pk_fma_f32 v[24:25], v[24:25], 0.5, v[38:39] op_sel_hi:[1,0,1]
	v_cvt_pk_bf16_f32 v34, v28, v29
	v_cvt_pk_bf16_f32 v35, v30, v31
	v_cvt_pk_bf16_f32 v36, v24, v25
	v_cvt_pk_bf16_f32 v37, v26, v27
	global_store_dwordx4 v[42:43], v[28:31], off
	global_store_dwordx4 v[42:43], v[24:27], off offset:16
	global_store_dwordx4 v[44:45], v[34:37], off sc1
	global_load_dwordx4 v[34:37], v[42:43], off offset:512
	s_nop 0
	global_load_dwordx4 v[38:41], v[42:43], off offset:528
	v_mul_f32_e32 v29, v29, v29
	v_mul_f32_e32 v31, v31, v31
	v_mul_f32_e32 v25, v25, v25
	v_fmac_f32_e32 v29, v28, v28
	v_fmac_f32_e32 v31, v30, v30
	v_mul_f32_e32 v27, v27, v27
	v_fmac_f32_e32 v25, v24, v24
	v_add_f32_e32 v24, v29, v31
	v_fmac_f32_e32 v27, v26, v26
	v_add_f32_e32 v24, v25, v24
	v_add_f32_e32 v28, v27, v24
	s_waitcnt vmcnt(1)
	v_pk_fma_f32 v[22:23], v[22:23], 0.5, v[36:37] op_sel_hi:[1,0,1]
	v_pk_fma_f32 v[20:21], v[20:21], 0.5, v[34:35] op_sel_hi:[1,0,1]
	s_waitcnt vmcnt(0)
	v_pk_fma_f32 v[24:25], v[16:17], 0.5, v[38:39] op_sel_hi:[1,0,1]
	v_mul_f32_e32 v16, v21, v21
	v_mul_f32_e32 v17, v23, v23
	v_pk_fma_f32 v[26:27], v[18:19], 0.5, v[40:41] op_sel_hi:[1,0,1]
	v_mul_f32_e32 v18, v25, v25
	v_fmac_f32_e32 v16, v20, v20
	v_fmac_f32_e32 v17, v22, v22
	v_mul_f32_e32 v19, v27, v27
	v_fmac_f32_e32 v18, v24, v24
	v_add_f32_e32 v16, v16, v17
	v_add_f32_e32 v16, v18, v16
	v_fmac_f32_e32 v19, v26, v26
	v_add_f32_e32 v16, v19, v16
	v_add_f32_e32 v16, v28, v16
	ds_bpermute_b32 v17, v120, v16
	global_store_dwordx4 v[42:43], v[20:23], off offset:512
	global_store_dwordx4 v[42:43], v[24:27], off offset:528
	v_cvt_pk_bf16_f32 v18, v20, v21
	v_cvt_pk_bf16_f32 v19, v22, v23
	v_cvt_pk_bf16_f32 v20, v24, v25
	s_waitcnt lgkmcnt(0)
	v_add_f32_e32 v16, v16, v17
	ds_bpermute_b32 v17, v114, v16
	v_cvt_pk_bf16_f32 v21, v26, v27
	global_store_dwordx4 v[44:45], v[18:21], off offset:256 sc1
	s_and_saveexec_b64 s[16:17], s[40:41]
	s_cbranch_execz .LBB0_1274
	s_waitcnt lgkmcnt(0)
	v_add_f32_e32 v16, v16, v17
	v_mul_f32_e32 v16, 0x4b800000, v16
	v_trunc_f32_e32 v16, v16
	v_mul_f32_e32 v17, 0x2f800000, v16
	v_floor_f32_e32 v17, v17
	v_fmac_f32_e32 v16, 0xcf800000, v17
	v_cvt_u32_f32_e32 v16, v16
	v_cvt_u32_f32_e32 v17, v17
	v_lshl_add_u64 v[18:19], v[32:33], 3, s[18:19]
	global_atomic_add_x2 v[18:19], v[16:17], off
.LBB0_1274:
	s_or_b64 exec, exec, s[16:17]
	v_add_u32_e32 v16, 0xb0, v140
	s_waitcnt lgkmcnt(0)
	v_ashrrev_i32_e32 v17, 31, v16
	v_lshlrev_b64 v[18:19], 12, v[16:17]
	v_lshl_add_u64 v[18:19], s[48:49], 0, v[18:19]
	v_lshl_add_u64 v[26:27], v[138:139], 2, v[18:19]
	v_lshlrev_b64 v[18:19], 11, v[16:17]
	v_lshl_add_u64 v[18:19], s[14:15], 0, v[18:19]
	v_lshl_add_u64 v[28:29], v[138:139], 1, v[18:19]
	global_load_dwordx4 v[18:21], v[26:27], off offset:16
	global_load_dwordx4 v[22:25], v[26:27], off
	s_waitcnt vmcnt(1)
	v_pk_fma_f32 v[10:11], v[10:11], 0.5, v[20:21] op_sel_hi:[1,0,1]
	s_waitcnt vmcnt(0)
	v_pk_fma_f32 v[14:15], v[14:15], 0.5, v[24:25] op_sel_hi:[1,0,1]
	v_pk_fma_f32 v[12:13], v[12:13], 0.5, v[22:23] op_sel_hi:[1,0,1]
	v_pk_fma_f32 v[8:9], v[8:9], 0.5, v[18:19] op_sel_hi:[1,0,1]
	global_store_dwordx4 v[26:27], v[12:15], off
	global_store_dwordx4 v[26:27], v[8:11], off offset:16
	v_cvt_pk_bf16_f32 v18, v12, v13
	v_mul_f32_e32 v13, v13, v13
	v_fmac_f32_e32 v13, v12, v12
	v_mul_f32_e32 v12, v15, v15
	v_cvt_pk_bf16_f32 v20, v8, v9
	v_fmac_f32_e32 v12, v14, v14
	v_mul_f32_e32 v9, v9, v9
	v_add_f32_e32 v12, v13, v12
	v_fmac_f32_e32 v9, v8, v8
	v_cvt_pk_bf16_f32 v19, v14, v15
	v_cvt_pk_bf16_f32 v21, v10, v11
	v_add_f32_e32 v8, v9, v12
	v_mul_f32_e32 v9, v11, v11
	global_store_dwordx4 v[28:29], v[18:21], off sc1
	v_fmac_f32_e32 v9, v10, v10
	s_nop 0
	v_add_f32_e32 v18, v9, v8
	global_load_dwordx4 v[8:11], v[26:27], off offset:528
	global_load_dwordx4 v[12:15], v[26:27], off offset:512
	s_waitcnt vmcnt(1)
	v_pk_fma_f32 v[2:3], v[2:3], 0.5, v[10:11] op_sel_hi:[1,0,1]
	s_waitcnt vmcnt(0)
	v_pk_fma_f32 v[6:7], v[6:7], 0.5, v[14:15] op_sel_hi:[1,0,1]
	v_pk_fma_f32 v[4:5], v[4:5], 0.5, v[12:13] op_sel_hi:[1,0,1]
	v_pk_fma_f32 v[0:1], v[0:1], 0.5, v[8:9] op_sel_hi:[1,0,1]
	global_store_dwordx4 v[26:27], v[4:7], off offset:512
	global_store_dwordx4 v[26:27], v[0:3], off offset:528
	v_cvt_pk_bf16_f32 v8, v4, v5
	v_mul_f32_e32 v5, v5, v5
	v_fmac_f32_e32 v5, v4, v4
	v_mul_f32_e32 v4, v7, v7
	v_cvt_pk_bf16_f32 v10, v0, v1
	v_fmac_f32_e32 v4, v6, v6
	v_mul_f32_e32 v1, v1, v1
	v_add_f32_e32 v4, v5, v4
	v_fmac_f32_e32 v1, v0, v0
	v_add_f32_e32 v0, v1, v4
	v_mul_f32_e32 v1, v3, v3
	v_fmac_f32_e32 v1, v2, v2
	v_add_f32_e32 v0, v1, v0
	v_add_f32_e32 v0, v18, v0
	ds_bpermute_b32 v1, v120, v0
	v_cvt_pk_bf16_f32 v9, v6, v7
	v_cvt_pk_bf16_f32 v11, v2, v3
	global_store_dwordx4 v[28:29], v[8:11], off offset:256 sc1
	s_waitcnt lgkmcnt(0)
	v_add_f32_e32 v0, v0, v1
	ds_bpermute_b32 v1, v114, v0
	s_and_saveexec_b64 s[16:17], s[40:41]
	s_cbranch_execz .LBB0_1276
	s_waitcnt lgkmcnt(0)
	v_add_f32_e32 v0, v0, v1
	v_mul_f32_e32 v0, 0x4b800000, v0
	v_trunc_f32_e32 v0, v0
	v_mul_f32_e32 v1, 0x2f800000, v0
	v_floor_f32_e32 v1, v1
	v_fmac_f32_e32 v0, 0xcf800000, v1
	v_cvt_u32_f32_e32 v0, v0
	v_cvt_u32_f32_e32 v1, v1
	v_lshl_add_u64 v[2:3], v[16:17], 3, s[18:19]
	global_atomic_add_x2 v[2:3], v[0:1], off
